# v078 stack + xor-16 step of the converted row sums via v_permlane16_swap on a copy (no LDS round trip left in those chains)
# baseline (speedup 1.0000x reference)
.LBB0_249:
	s_min_i32 s7, s6, 0x8000
	s_ashr_i32 s7, s7, 11
	s_mul_hi_i32 s9, s7, 0x6000
	s_mulk_i32 s7, 0x6000
	s_add_u32 s7, s44, s7
	s_addc_u32 s9, s45, s9
	s_add_u32 s12, s7, 0x1000
	s_addc_u32 s13, s9, 0
	v_lshl_add_u64 v[66:67], v[116:117], 2, s[12:13]
	global_load_dwordx4 v[128:131], v[66:67], off
	s_ashr_i32 s7, s6, 31
	s_lshl_b64 s[14:15], s[6:7], 11
	v_lshl_add_u64 v[132:133], v[126:127], 0, s[14:15]
	v_lshl_add_u64 v[66:67], v[118:119], 2, s[12:13]
	s_waitcnt vmcnt(4)
	v_mul_f32_e32 v64, v17, v17
	s_waitcnt vmcnt(3)
	v_mul_f32_e32 v134, v23, v23
	s_waitcnt vmcnt(2)
	v_mul_f32_e32 v135, v25, v25
	v_mul_f32_e32 v136, v27, v27
	v_fmac_f32_e32 v64, v16, v16
	v_fmac_f32_e32 v134, v22, v22
	s_waitcnt vmcnt(1)
	v_mul_f32_e32 v137, v29, v29
	v_mul_f32_e32 v138, v31, v31
	v_fmac_f32_e32 v135, v24, v24
	v_fmac_f32_e32 v136, v26, v26
	v_fmac_f32_e32 v137, v28, v28
	v_fmac_f32_e32 v138, v30, v30
	s_waitcnt vmcnt(0)
	v_pk_add_f32 v[128:129], v[128:129], 1.0 op_sel_hi:[1,0]
	v_pk_add_f32 v[130:131], v[130:131], 1.0 op_sel_hi:[1,0]
	v_pk_mul_f32 v[128:129], v[0:1], v[128:129]
	v_pk_mul_f32 v[130:131], v[2:3], v[130:131]
	v_pk_mul_f32 v[128:129], v[16:17], v[128:129]
	v_pk_mul_f32 v[130:131], v[18:19], v[130:131]
	v_cvt_pk_bf16_f32 v128, v128, v129
	s_nop 0
	v_cvt_pk_bf16_f32 v129, v130, v131
	global_store_dwordx2 v[132:133], v[128:129], off
	global_load_dwordx4 v[128:131], v[66:67], off
	v_lshl_add_u64 v[66:67], v[120:121], 2, s[12:13]
	s_waitcnt vmcnt(0)
	v_pk_add_f32 v[128:129], v[128:129], 1.0 op_sel_hi:[1,0]
	v_pk_add_f32 v[130:131], v[130:131], 1.0 op_sel_hi:[1,0]
	v_pk_mul_f32 v[128:129], v[4:5], v[128:129]
	v_pk_mul_f32 v[130:131], v[6:7], v[130:131]
	v_pk_mul_f32 v[128:129], v[20:21], v[128:129]
	v_pk_mul_f32 v[130:131], v[22:23], v[130:131]
	v_cvt_pk_bf16_f32 v128, v128, v129
	s_nop 0
	v_cvt_pk_bf16_f32 v129, v130, v131
	global_store_dwordx2 v[132:133], v[128:129], off offset:512
	global_load_dwordx4 v[128:131], v[66:67], off
	v_lshl_add_u64 v[66:67], v[122:123], 2, s[12:13]
	s_waitcnt vmcnt(0)
	v_pk_add_f32 v[128:129], v[128:129], 1.0 op_sel_hi:[1,0]
	v_pk_add_f32 v[130:131], v[130:131], 1.0 op_sel_hi:[1,0]
	v_pk_mul_f32 v[128:129], v[8:9], v[128:129]
	v_pk_mul_f32 v[130:131], v[10:11], v[130:131]
	v_pk_mul_f32 v[128:129], v[24:25], v[128:129]
	v_pk_mul_f32 v[130:131], v[26:27], v[130:131]
	v_cvt_pk_bf16_f32 v128, v128, v129
	s_nop 0
	v_cvt_pk_bf16_f32 v129, v130, v131
	global_store_dwordx2 v[132:133], v[128:129], off offset:1024
	global_load_dwordx4 v[128:131], v[66:67], off
	v_mul_f32_e32 v66, v19, v19
	v_mul_f32_e32 v67, v21, v21
	v_fmac_f32_e32 v66, v18, v18
	v_fmac_f32_e32 v67, v20, v20
	v_add_f32_e32 v64, v64, v66
	v_add_f32_e32 v66, v67, v134
	v_add_f32_e32 v67, v135, v136
	v_add_f32_e32 v64, v64, v66
	v_add_f32_e32 v134, v137, v138
	v_add_f32_e32 v64, v64, v67
	v_add_f32_e32 v64, v64, v134
	s_nop 1
	v_add_f32_dpp v64, v64, v64 quad_perm:[1,0,3,2] row_mask:0xf bank_mask:0xf
	s_nop 1
	v_add_f32_dpp v64, v64, v64 quad_perm:[2,3,0,1] row_mask:0xf bank_mask:0xf
	s_nop 1
	v_add_f32_dpp v64, v64, v64 row_half_mirror row_mask:0xf bank_mask:0xf
	s_nop 1
	v_add_f32_dpp v64, v64, v64 row_mirror row_mask:0xf bank_mask:0xf
	v_mov_b32_e32 v66, v64
	s_nop 1
	v_permlane16_swap_b32_e32 v64, v66
	v_add_f32_e32 v64, v64, v66
	v_mov_b32_e32 v66, v64
	s_nop 1
	v_permlane32_swap_b32_e32 v64, v66
	s_waitcnt vmcnt(0)
	v_pk_add_f32 v[128:129], v[128:129], 1.0 op_sel_hi:[1,0]
	v_pk_add_f32 v[130:131], v[130:131], 1.0 op_sel_hi:[1,0]
	v_pk_mul_f32 v[128:129], v[12:13], v[128:129]
	v_pk_mul_f32 v[130:131], v[14:15], v[130:131]
	v_pk_mul_f32 v[128:129], v[28:29], v[128:129]
	v_pk_mul_f32 v[130:131], v[30:31], v[130:131]
	v_cvt_pk_bf16_f32 v128, v128, v129
	s_nop 0
	v_cvt_pk_bf16_f32 v129, v130, v131
	global_store_dwordx2 v[132:133], v[128:129], off offset:1536
	s_and_saveexec_b64 s[12:13], s[2:3]
	s_cbranch_execz .LBB0_255
	v_add_f32_e32 v64, v64, v66
	s_lshl_b64 s[14:15], s[6:7], 6
	v_cndmask_b32_e64 v64, 0, v64, s[4:5]
	v_lshl_add_u64 v[128:129], v[124:125], 0, s[14:15]
	v_mov_b32_e32 v66, v65
	v_mov_b32_e32 v67, v65
	global_store_dwordx4 v[128:129], v[64:67], off
	s_or_b64 exec, exec, s[12:13]
	s_add_i32 s12, s26, s6
	s_cmp_gt_i32 s12, 0x8fff
	s_cbranch_scc0 .LBB0_256

.LBB0_252:
	s_min_i32 s7, s12, 0x8000
	s_ashr_i32 s7, s7, 11
	s_mul_hi_i32 s9, s7, 0x6000
	s_mulk_i32 s7, 0x6000
	s_add_u32 s7, s44, s7
	s_addc_u32 s9, s45, s9
	s_add_u32 s14, s7, 0x1000
	s_addc_u32 s15, s9, 0
	v_lshl_add_u64 v[66:67], v[116:117], 2, s[14:15]
	global_load_dwordx4 v[128:131], v[66:67], off
	s_ashr_i32 s13, s12, 31
	s_lshl_b64 s[20:21], s[12:13], 11
	v_lshl_add_u64 v[132:133], v[126:127], 0, s[20:21]
	v_lshl_add_u64 v[66:67], v[118:119], 2, s[14:15]
	v_mul_f32_e32 v64, v49, v49
	v_mul_f32_e32 v134, v55, v55
	v_mul_f32_e32 v135, v57, v57
	v_mul_f32_e32 v136, v59, v59
	v_fmac_f32_e32 v64, v48, v48
	v_fmac_f32_e32 v134, v54, v54
	v_mul_f32_e32 v137, v61, v61
	v_mul_f32_e32 v138, v63, v63
	v_fmac_f32_e32 v135, v56, v56
	v_fmac_f32_e32 v136, v58, v58
	v_fmac_f32_e32 v137, v60, v60
	v_fmac_f32_e32 v138, v62, v62
	s_waitcnt vmcnt(0)
	v_pk_add_f32 v[128:129], v[128:129], 1.0 op_sel_hi:[1,0]
	v_pk_add_f32 v[130:131], v[130:131], 1.0 op_sel_hi:[1,0]
	v_pk_mul_f32 v[128:129], v[0:1], v[128:129]
	v_pk_mul_f32 v[130:131], v[2:3], v[130:131]
	v_pk_mul_f32 v[128:129], v[48:49], v[128:129]
	v_pk_mul_f32 v[130:131], v[50:51], v[130:131]
	v_cvt_pk_bf16_f32 v128, v128, v129
	s_nop 0
	v_cvt_pk_bf16_f32 v129, v130, v131
	global_store_dwordx2 v[132:133], v[128:129], off
	global_load_dwordx4 v[128:131], v[66:67], off
	v_lshl_add_u64 v[66:67], v[120:121], 2, s[14:15]
	s_waitcnt vmcnt(0)
	v_pk_add_f32 v[128:129], v[128:129], 1.0 op_sel_hi:[1,0]
	v_pk_add_f32 v[130:131], v[130:131], 1.0 op_sel_hi:[1,0]
	v_pk_mul_f32 v[128:129], v[4:5], v[128:129]
	v_pk_mul_f32 v[130:131], v[6:7], v[130:131]
	v_pk_mul_f32 v[128:129], v[52:53], v[128:129]
	v_pk_mul_f32 v[130:131], v[54:55], v[130:131]
	v_cvt_pk_bf16_f32 v128, v128, v129
	s_nop 0
	v_cvt_pk_bf16_f32 v129, v130, v131
	global_store_dwordx2 v[132:133], v[128:129], off offset:512
	global_load_dwordx4 v[128:131], v[66:67], off
	v_lshl_add_u64 v[66:67], v[122:123], 2, s[14:15]
	s_waitcnt vmcnt(0)
	v_pk_add_f32 v[128:129], v[128:129], 1.0 op_sel_hi:[1,0]
	v_pk_add_f32 v[130:131], v[130:131], 1.0 op_sel_hi:[1,0]
	v_pk_mul_f32 v[128:129], v[8:9], v[128:129]
	v_pk_mul_f32 v[130:131], v[10:11], v[130:131]
	v_pk_mul_f32 v[128:129], v[56:57], v[128:129]
	v_pk_mul_f32 v[130:131], v[58:59], v[130:131]
	v_cvt_pk_bf16_f32 v128, v128, v129
	s_nop 0
	v_cvt_pk_bf16_f32 v129, v130, v131
	global_store_dwordx2 v[132:133], v[128:129], off offset:1024
	global_load_dwordx4 v[128:131], v[66:67], off
	v_mul_f32_e32 v66, v51, v51
	v_mul_f32_e32 v67, v53, v53
	v_fmac_f32_e32 v66, v50, v50
	v_fmac_f32_e32 v67, v52, v52
	v_add_f32_e32 v64, v64, v66
	v_add_f32_e32 v66, v67, v134
	v_add_f32_e32 v67, v135, v136
	v_add_f32_e32 v64, v64, v66
	v_add_f32_e32 v134, v137, v138
	v_add_f32_e32 v64, v64, v67
	v_add_f32_e32 v64, v64, v134
	s_nop 1
	v_add_f32_dpp v64, v64, v64 quad_perm:[1,0,3,2] row_mask:0xf bank_mask:0xf
	s_nop 1
	v_add_f32_dpp v64, v64, v64 quad_perm:[2,3,0,1] row_mask:0xf bank_mask:0xf
	s_nop 1
	v_add_f32_dpp v64, v64, v64 row_half_mirror row_mask:0xf bank_mask:0xf
	s_nop 1
	v_add_f32_dpp v64, v64, v64 row_mirror row_mask:0xf bank_mask:0xf
	v_mov_b32_e32 v66, v64
	s_nop 1
	v_permlane16_swap_b32_e32 v64, v66
	v_add_f32_e32 v64, v64, v66
	v_mov_b32_e32 v66, v64
	s_nop 1
	v_permlane32_swap_b32_e32 v64, v66
	s_waitcnt vmcnt(0)
	v_pk_add_f32 v[128:129], v[128:129], 1.0 op_sel_hi:[1,0]
	v_pk_add_f32 v[130:131], v[130:131], 1.0 op_sel_hi:[1,0]
	v_pk_mul_f32 v[128:129], v[12:13], v[128:129]
	v_pk_mul_f32 v[130:131], v[14:15], v[130:131]
	v_pk_mul_f32 v[128:129], v[60:61], v[128:129]
	v_pk_mul_f32 v[130:131], v[62:63], v[130:131]
	v_cvt_pk_bf16_f32 v128, v128, v129
	s_nop 0
	v_cvt_pk_bf16_f32 v129, v130, v131
	global_store_dwordx2 v[132:133], v[128:129], off offset:1536
	s_and_saveexec_b64 s[14:15], s[2:3]
	s_cbranch_execz .LBB0_254
	v_add_f32_e32 v64, v64, v66
	s_lshl_b64 s[12:13], s[12:13], 6
	v_cndmask_b32_e64 v64, 0, v64, s[4:5]
	v_lshl_add_u64 v[128:129], v[124:125], 0, s[12:13]
	v_mov_b32_e32 v66, v65
	v_mov_b32_e32 v67, v65
	global_store_dwordx4 v[128:129], v[64:67], off

.LBB0_256:
	s_min_i32 s7, s12, 0x8000
	s_ashr_i32 s7, s7, 11
	s_mul_hi_i32 s9, s7, 0x6000
	s_mulk_i32 s7, 0x6000
	s_add_u32 s7, s44, s7
	s_addc_u32 s9, s45, s9
	s_add_u32 s14, s7, 0x1000
	s_addc_u32 s15, s9, 0
	v_lshl_add_u64 v[66:67], v[116:117], 2, s[14:15]
	global_load_dwordx4 v[128:131], v[66:67], off
	s_ashr_i32 s13, s12, 31
	s_lshl_b64 s[20:21], s[12:13], 11
	v_lshl_add_u64 v[132:133], v[126:127], 0, s[20:21]
	v_lshl_add_u64 v[66:67], v[118:119], 2, s[14:15]
	v_mul_f32_e32 v64, v33, v33
	v_mul_f32_e32 v134, v39, v39
	v_mul_f32_e32 v135, v41, v41
	v_mul_f32_e32 v136, v43, v43
	v_fmac_f32_e32 v64, v32, v32
	v_fmac_f32_e32 v134, v38, v38
	v_mul_f32_e32 v137, v45, v45
	v_mul_f32_e32 v138, v47, v47
	v_fmac_f32_e32 v135, v40, v40
	v_fmac_f32_e32 v136, v42, v42
	v_fmac_f32_e32 v137, v44, v44
	v_fmac_f32_e32 v138, v46, v46
	s_waitcnt vmcnt(0)
	v_pk_add_f32 v[128:129], v[128:129], 1.0 op_sel_hi:[1,0]
	v_pk_add_f32 v[130:131], v[130:131], 1.0 op_sel_hi:[1,0]
	v_pk_mul_f32 v[128:129], v[0:1], v[128:129]
	v_pk_mul_f32 v[130:131], v[2:3], v[130:131]
	v_pk_mul_f32 v[128:129], v[32:33], v[128:129]
	v_pk_mul_f32 v[130:131], v[34:35], v[130:131]
	v_cvt_pk_bf16_f32 v128, v128, v129
	s_nop 0
	v_cvt_pk_bf16_f32 v129, v130, v131
	global_store_dwordx2 v[132:133], v[128:129], off
	global_load_dwordx4 v[128:131], v[66:67], off
	v_lshl_add_u64 v[66:67], v[120:121], 2, s[14:15]
	s_waitcnt vmcnt(0)
	v_pk_add_f32 v[128:129], v[128:129], 1.0 op_sel_hi:[1,0]
	v_pk_add_f32 v[130:131], v[130:131], 1.0 op_sel_hi:[1,0]
	v_pk_mul_f32 v[128:129], v[4:5], v[128:129]
	v_pk_mul_f32 v[130:131], v[6:7], v[130:131]
	v_pk_mul_f32 v[128:129], v[36:37], v[128:129]
	v_pk_mul_f32 v[130:131], v[38:39], v[130:131]
	v_cvt_pk_bf16_f32 v128, v128, v129
	s_nop 0
	v_cvt_pk_bf16_f32 v129, v130, v131
	global_store_dwordx2 v[132:133], v[128:129], off offset:512
	global_load_dwordx4 v[128:131], v[66:67], off
	v_lshl_add_u64 v[66:67], v[122:123], 2, s[14:15]
	s_waitcnt vmcnt(0)
	v_pk_add_f32 v[128:129], v[128:129], 1.0 op_sel_hi:[1,0]
	v_pk_add_f32 v[130:131], v[130:131], 1.0 op_sel_hi:[1,0]
	v_pk_mul_f32 v[128:129], v[8:9], v[128:129]
	v_pk_mul_f32 v[130:131], v[10:11], v[130:131]
	v_pk_mul_f32 v[128:129], v[40:41], v[128:129]
	v_pk_mul_f32 v[130:131], v[42:43], v[130:131]
	v_cvt_pk_bf16_f32 v128, v128, v129
	s_nop 0
	v_cvt_pk_bf16_f32 v129, v130, v131
	global_store_dwordx2 v[132:133], v[128:129], off offset:1024
	global_load_dwordx4 v[128:131], v[66:67], off
	v_mul_f32_e32 v66, v35, v35
	v_mul_f32_e32 v67, v37, v37
	v_fmac_f32_e32 v66, v34, v34
	v_fmac_f32_e32 v67, v36, v36
	v_add_f32_e32 v64, v64, v66
	v_add_f32_e32 v66, v67, v134
	v_add_f32_e32 v67, v135, v136
	v_add_f32_e32 v64, v64, v66
	v_add_f32_e32 v134, v137, v138
	v_add_f32_e32 v64, v64, v67
	v_add_f32_e32 v64, v64, v134
	s_nop 1
	v_add_f32_dpp v64, v64, v64 quad_perm:[1,0,3,2] row_mask:0xf bank_mask:0xf
	s_nop 1
	v_add_f32_dpp v64, v64, v64 quad_perm:[2,3,0,1] row_mask:0xf bank_mask:0xf
	s_nop 1
	v_add_f32_dpp v64, v64, v64 row_half_mirror row_mask:0xf bank_mask:0xf
	s_nop 1
	v_add_f32_dpp v64, v64, v64 row_mirror row_mask:0xf bank_mask:0xf
	v_mov_b32_e32 v66, v64
	s_nop 1
	v_permlane16_swap_b32_e32 v64, v66
	v_add_f32_e32 v64, v64, v66
	v_mov_b32_e32 v66, v64
	s_nop 1
	v_permlane32_swap_b32_e32 v64, v66
	s_waitcnt vmcnt(0)
	v_pk_add_f32 v[128:129], v[128:129], 1.0 op_sel_hi:[1,0]
	v_pk_add_f32 v[130:131], v[130:131], 1.0 op_sel_hi:[1,0]
	v_pk_mul_f32 v[128:129], v[12:13], v[128:129]
	v_pk_mul_f32 v[130:131], v[14:15], v[130:131]
	v_pk_mul_f32 v[128:129], v[44:45], v[128:129]
	v_pk_mul_f32 v[130:131], v[46:47], v[130:131]
	v_cvt_pk_bf16_f32 v128, v128, v129
	s_nop 0
	v_cvt_pk_bf16_f32 v129, v130, v131
	global_store_dwordx2 v[132:133], v[128:129], off offset:1536
	s_and_saveexec_b64 s[14:15], s[2:3]
	s_cbranch_execz .LBB0_258
	v_add_f32_e32 v64, v64, v66
	s_lshl_b64 s[12:13], s[12:13], 6
	v_cndmask_b32_e64 v64, 0, v64, s[4:5]
	v_lshl_add_u64 v[128:129], v[124:125], 0, s[12:13]
	v_mov_b32_e32 v66, v65
	v_mov_b32_e32 v67, v65
	global_store_dwordx4 v[128:129], v[64:67], off

.LBB0_265:
	s_min_i32 s7, s8, 0x8000
	s_ashr_i32 s7, s7, 11
	s_mul_hi_i32 s9, s7, 0x6000
	s_mulk_i32 s7, 0x6000
	s_add_u32 s7, s44, s7
	s_addc_u32 s9, s45, s9
	s_add_u32 s10, s7, 0x1000
	s_addc_u32 s11, s9, 0
	v_lshl_add_u64 v[66:67], v[116:117], 2, s[10:11]
	global_load_dwordx4 v[128:131], v[66:67], off
	s_ashr_i32 s9, s8, 31
	s_lshl_b64 s[14:15], s[8:9], 11
	v_lshl_add_u64 v[132:133], v[126:127], 0, s[14:15]
	v_lshl_add_u64 v[66:67], v[118:119], 2, s[10:11]
	v_mul_f32_e32 v64, v101, v101
	v_mul_f32_e32 v134, v107, v107
	v_mul_f32_e32 v135, v109, v109
	v_mul_f32_e32 v136, v111, v111
	v_fmac_f32_e32 v64, v100, v100
	v_fmac_f32_e32 v134, v106, v106
	v_mul_f32_e32 v137, v113, v113
	v_mul_f32_e32 v138, v115, v115
	v_fmac_f32_e32 v135, v108, v108
	v_fmac_f32_e32 v136, v110, v110
	v_fmac_f32_e32 v137, v112, v112
	v_fmac_f32_e32 v138, v114, v114
	s_waitcnt vmcnt(0)
	v_pk_add_f32 v[128:129], v[128:129], 1.0 op_sel_hi:[1,0]
	v_pk_add_f32 v[130:131], v[130:131], 1.0 op_sel_hi:[1,0]
	v_pk_mul_f32 v[128:129], v[0:1], v[128:129]
	v_pk_mul_f32 v[130:131], v[2:3], v[130:131]
	v_pk_mul_f32 v[128:129], v[100:101], v[128:129]
	v_pk_mul_f32 v[130:131], v[102:103], v[130:131]
	v_cvt_pk_bf16_f32 v128, v128, v129
	s_nop 0
	v_cvt_pk_bf16_f32 v129, v130, v131
	global_store_dwordx2 v[132:133], v[128:129], off
	global_load_dwordx4 v[128:131], v[66:67], off
	v_lshl_add_u64 v[66:67], v[120:121], 2, s[10:11]
	s_waitcnt vmcnt(0)
	v_pk_add_f32 v[128:129], v[128:129], 1.0 op_sel_hi:[1,0]
	v_pk_add_f32 v[130:131], v[130:131], 1.0 op_sel_hi:[1,0]
	v_pk_mul_f32 v[128:129], v[4:5], v[128:129]
	v_pk_mul_f32 v[130:131], v[6:7], v[130:131]
	v_pk_mul_f32 v[128:129], v[104:105], v[128:129]
	v_pk_mul_f32 v[130:131], v[106:107], v[130:131]
	v_cvt_pk_bf16_f32 v128, v128, v129
	s_nop 0
	v_cvt_pk_bf16_f32 v129, v130, v131
	global_store_dwordx2 v[132:133], v[128:129], off offset:512
	global_load_dwordx4 v[128:131], v[66:67], off
	v_lshl_add_u64 v[66:67], v[122:123], 2, s[10:11]
	s_waitcnt vmcnt(0)
	v_pk_add_f32 v[128:129], v[128:129], 1.0 op_sel_hi:[1,0]
	v_pk_add_f32 v[130:131], v[130:131], 1.0 op_sel_hi:[1,0]
	v_pk_mul_f32 v[128:129], v[8:9], v[128:129]
	v_pk_mul_f32 v[130:131], v[10:11], v[130:131]
	v_pk_mul_f32 v[128:129], v[108:109], v[128:129]
	v_pk_mul_f32 v[130:131], v[110:111], v[130:131]
	v_cvt_pk_bf16_f32 v128, v128, v129
	s_nop 0
	v_cvt_pk_bf16_f32 v129, v130, v131
	global_store_dwordx2 v[132:133], v[128:129], off offset:1024
	global_load_dwordx4 v[128:131], v[66:67], off
	v_mul_f32_e32 v66, v103, v103
	v_mul_f32_e32 v67, v105, v105
	v_fmac_f32_e32 v66, v102, v102
	v_fmac_f32_e32 v67, v104, v104
	v_add_f32_e32 v64, v64, v66
	v_add_f32_e32 v66, v67, v134
	v_add_f32_e32 v67, v135, v136
	v_add_f32_e32 v64, v64, v66
	v_add_f32_e32 v134, v137, v138
	v_add_f32_e32 v64, v64, v67
	v_add_f32_e32 v64, v64, v134
	s_nop 1
	v_add_f32_dpp v64, v64, v64 quad_perm:[1,0,3,2] row_mask:0xf bank_mask:0xf
	s_nop 1
	v_add_f32_dpp v64, v64, v64 quad_perm:[2,3,0,1] row_mask:0xf bank_mask:0xf
	s_nop 1
	v_add_f32_dpp v64, v64, v64 row_half_mirror row_mask:0xf bank_mask:0xf
	s_nop 1
	v_add_f32_dpp v64, v64, v64 row_mirror row_mask:0xf bank_mask:0xf
	v_mov_b32_e32 v66, v64
	s_nop 1
	v_permlane16_swap_b32_e32 v64, v66
	v_add_f32_e32 v64, v64, v66
	v_mov_b32_e32 v66, v64
	s_nop 1
	v_permlane32_swap_b32_e32 v64, v66
	s_waitcnt vmcnt(0)
	v_pk_add_f32 v[128:129], v[128:129], 1.0 op_sel_hi:[1,0]
	v_pk_add_f32 v[130:131], v[130:131], 1.0 op_sel_hi:[1,0]
	v_pk_mul_f32 v[128:129], v[12:13], v[128:129]
	v_pk_mul_f32 v[130:131], v[14:15], v[130:131]
	v_pk_mul_f32 v[128:129], v[112:113], v[128:129]
	v_pk_mul_f32 v[130:131], v[114:115], v[130:131]
	v_cvt_pk_bf16_f32 v128, v128, v129
	s_nop 0
	v_cvt_pk_bf16_f32 v129, v130, v131
	global_store_dwordx2 v[132:133], v[128:129], off offset:1536
	s_and_saveexec_b64 s[10:11], s[2:3]
	s_cbranch_execz .LBB0_268
	v_add_f32_e32 v64, v64, v66
	s_lshl_b64 s[8:9], s[8:9], 6
	v_cndmask_b32_e64 v64, 0, v64, s[4:5]
	v_lshl_add_u64 v[128:129], v[124:125], 0, s[8:9]
	v_mov_b32_e32 v66, v65
	v_mov_b32_e32 v67, v65
	global_store_dwordx4 v[128:129], v[64:67], off
	s_or_b64 exec, exec, s[10:11]
	s_add_i32 s8, s0, s6
	s_cmp_gt_i32 s8, 0x8fff
	s_cbranch_scc0 .LBB0_269

.LBB0_269:
	s_min_i32 s7, s8, 0x8000
	s_ashr_i32 s7, s7, 11
	s_mul_hi_i32 s9, s7, 0x6000
	s_mulk_i32 s7, 0x6000
	s_add_u32 s7, s44, s7
	s_addc_u32 s9, s45, s9
	s_add_u32 s10, s7, 0x1000
	s_addc_u32 s11, s9, 0
	v_lshl_add_u64 v[66:67], v[116:117], 2, s[10:11]
	global_load_dwordx4 v[128:131], v[66:67], off
	s_ashr_i32 s9, s8, 31
	s_lshl_b64 s[14:15], s[8:9], 11
	v_lshl_add_u64 v[132:133], v[126:127], 0, s[14:15]
	v_lshl_add_u64 v[66:67], v[118:119], 2, s[10:11]
	v_mul_f32_e32 v64, v97, v97
	v_mul_f32_e32 v134, v95, v95
	v_mul_f32_e32 v135, v89, v89
	v_mul_f32_e32 v136, v91, v91
	v_fmac_f32_e32 v64, v96, v96
	v_fmac_f32_e32 v134, v94, v94
	v_mul_f32_e32 v137, v85, v85
	v_mul_f32_e32 v138, v87, v87
	v_fmac_f32_e32 v135, v88, v88
	v_fmac_f32_e32 v136, v90, v90
	v_fmac_f32_e32 v137, v84, v84
	v_fmac_f32_e32 v138, v86, v86
	s_waitcnt vmcnt(0)
	v_pk_add_f32 v[128:129], v[128:129], 1.0 op_sel_hi:[1,0]
	v_pk_add_f32 v[130:131], v[130:131], 1.0 op_sel_hi:[1,0]
	v_pk_mul_f32 v[128:129], v[0:1], v[128:129]
	v_pk_mul_f32 v[130:131], v[2:3], v[130:131]
	v_pk_mul_f32 v[128:129], v[96:97], v[128:129]
	v_pk_mul_f32 v[130:131], v[98:99], v[130:131]
	v_cvt_pk_bf16_f32 v128, v128, v129
	s_nop 0
	v_cvt_pk_bf16_f32 v129, v130, v131
	global_store_dwordx2 v[132:133], v[128:129], off
	global_load_dwordx4 v[128:131], v[66:67], off
	v_lshl_add_u64 v[66:67], v[120:121], 2, s[10:11]
	s_waitcnt vmcnt(0)
	v_pk_add_f32 v[128:129], v[128:129], 1.0 op_sel_hi:[1,0]
	v_pk_add_f32 v[130:131], v[130:131], 1.0 op_sel_hi:[1,0]
	v_pk_mul_f32 v[128:129], v[4:5], v[128:129]
	v_pk_mul_f32 v[130:131], v[6:7], v[130:131]
	v_pk_mul_f32 v[128:129], v[92:93], v[128:129]
	v_pk_mul_f32 v[130:131], v[94:95], v[130:131]
	v_cvt_pk_bf16_f32 v128, v128, v129
	s_nop 0
	v_cvt_pk_bf16_f32 v129, v130, v131
	global_store_dwordx2 v[132:133], v[128:129], off offset:512
	global_load_dwordx4 v[128:131], v[66:67], off
	v_lshl_add_u64 v[66:67], v[122:123], 2, s[10:11]
	s_waitcnt vmcnt(0)
	v_pk_add_f32 v[128:129], v[128:129], 1.0 op_sel_hi:[1,0]
	v_pk_add_f32 v[130:131], v[130:131], 1.0 op_sel_hi:[1,0]
	v_pk_mul_f32 v[128:129], v[8:9], v[128:129]
	v_pk_mul_f32 v[130:131], v[10:11], v[130:131]
	v_pk_mul_f32 v[128:129], v[88:89], v[128:129]
	v_pk_mul_f32 v[130:131], v[90:91], v[130:131]
	v_cvt_pk_bf16_f32 v128, v128, v129
	s_nop 0
	v_cvt_pk_bf16_f32 v129, v130, v131
	global_store_dwordx2 v[132:133], v[128:129], off offset:1024
	global_load_dwordx4 v[128:131], v[66:67], off
	v_mul_f32_e32 v66, v99, v99
	v_mul_f32_e32 v67, v93, v93
	v_fmac_f32_e32 v66, v98, v98
	v_fmac_f32_e32 v67, v92, v92
	v_add_f32_e32 v64, v64, v66
	v_add_f32_e32 v66, v67, v134
	v_add_f32_e32 v67, v135, v136
	v_add_f32_e32 v64, v64, v66
	v_add_f32_e32 v134, v137, v138
	v_add_f32_e32 v64, v64, v67
	v_add_f32_e32 v64, v64, v134
	s_nop 1
	v_add_f32_dpp v64, v64, v64 quad_perm:[1,0,3,2] row_mask:0xf bank_mask:0xf
	s_nop 1
	v_add_f32_dpp v64, v64, v64 quad_perm:[2,3,0,1] row_mask:0xf bank_mask:0xf
	s_nop 1
	v_add_f32_dpp v64, v64, v64 row_half_mirror row_mask:0xf bank_mask:0xf
	s_nop 1
	v_add_f32_dpp v64, v64, v64 row_mirror row_mask:0xf bank_mask:0xf
	v_mov_b32_e32 v66, v64
	s_nop 1
	v_permlane16_swap_b32_e32 v64, v66
	v_add_f32_e32 v64, v64, v66
	v_mov_b32_e32 v66, v64
	s_nop 1
	v_permlane32_swap_b32_e32 v64, v66
	s_waitcnt vmcnt(0)
	v_pk_add_f32 v[128:129], v[128:129], 1.0 op_sel_hi:[1,0]
	v_pk_add_f32 v[130:131], v[130:131], 1.0 op_sel_hi:[1,0]
	v_pk_mul_f32 v[128:129], v[12:13], v[128:129]
	v_pk_mul_f32 v[130:131], v[14:15], v[130:131]
	v_pk_mul_f32 v[128:129], v[84:85], v[128:129]
	v_pk_mul_f32 v[130:131], v[86:87], v[130:131]
	v_cvt_pk_bf16_f32 v128, v128, v129
	s_nop 0
	v_cvt_pk_bf16_f32 v129, v130, v131
	global_store_dwordx2 v[132:133], v[128:129], off offset:1536
	s_and_saveexec_b64 s[10:11], s[2:3]
	s_cbranch_execz .LBB0_271
	v_add_f32_e32 v64, v64, v66
	s_lshl_b64 s[8:9], s[8:9], 6
	v_cndmask_b32_e64 v64, 0, v64, s[4:5]
	v_lshl_add_u64 v[128:129], v[124:125], 0, s[8:9]
	v_mov_b32_e32 v66, v65
	v_mov_b32_e32 v67, v65
	global_store_dwordx4 v[128:129], v[64:67], off

.LBB0_272:
	s_min_i32 s7, s6, 0x8000
	s_ashr_i32 s7, s7, 11
	s_mul_hi_i32 s8, s7, 0x6000
	s_mulk_i32 s7, 0x6000
	s_add_u32 s7, s44, s7
	s_addc_u32 s9, s45, s8
	s_add_u32 s8, s7, 0x1000
	s_addc_u32 s9, s9, 0
	v_lshl_add_u64 v[66:67], v[116:117], 2, s[8:9]
	global_load_dwordx4 v[128:131], v[66:67], off
	s_ashr_i32 s7, s6, 31
	s_lshl_b64 s[10:11], s[6:7], 11
	v_lshl_add_u64 v[132:133], v[126:127], 0, s[10:11]
	v_lshl_add_u64 v[66:67], v[118:119], 2, s[8:9]
	v_mul_f32_e32 v64, v81, v81
	v_mul_f32_e32 v134, v79, v79
	v_mul_f32_e32 v135, v73, v73
	v_mul_f32_e32 v136, v75, v75
	v_fmac_f32_e32 v64, v80, v80
	v_fmac_f32_e32 v134, v78, v78
	v_mul_f32_e32 v137, v69, v69
	v_mul_f32_e32 v138, v71, v71
	v_fmac_f32_e32 v135, v72, v72
	v_fmac_f32_e32 v136, v74, v74
	v_fmac_f32_e32 v137, v68, v68
	v_fmac_f32_e32 v138, v70, v70
	s_waitcnt vmcnt(0)
	v_pk_add_f32 v[128:129], v[128:129], 1.0 op_sel_hi:[1,0]
	v_pk_add_f32 v[130:131], v[130:131], 1.0 op_sel_hi:[1,0]
	v_pk_mul_f32 v[128:129], v[0:1], v[128:129]
	v_pk_mul_f32 v[130:131], v[2:3], v[130:131]
	v_pk_mul_f32 v[128:129], v[80:81], v[128:129]
	v_pk_mul_f32 v[130:131], v[82:83], v[130:131]
	v_cvt_pk_bf16_f32 v128, v128, v129
	s_nop 0
	v_cvt_pk_bf16_f32 v129, v130, v131
	global_store_dwordx2 v[132:133], v[128:129], off
	global_load_dwordx4 v[128:131], v[66:67], off
	v_lshl_add_u64 v[66:67], v[120:121], 2, s[8:9]
	s_waitcnt vmcnt(0)
	v_pk_add_f32 v[128:129], v[128:129], 1.0 op_sel_hi:[1,0]
	v_pk_add_f32 v[130:131], v[130:131], 1.0 op_sel_hi:[1,0]
	v_pk_mul_f32 v[128:129], v[4:5], v[128:129]
	v_pk_mul_f32 v[130:131], v[6:7], v[130:131]
	v_pk_mul_f32 v[128:129], v[76:77], v[128:129]
	v_pk_mul_f32 v[130:131], v[78:79], v[130:131]
	v_cvt_pk_bf16_f32 v128, v128, v129
	s_nop 0
	v_cvt_pk_bf16_f32 v129, v130, v131
	global_store_dwordx2 v[132:133], v[128:129], off offset:512
	global_load_dwordx4 v[128:131], v[66:67], off
	v_lshl_add_u64 v[66:67], v[122:123], 2, s[8:9]
	s_waitcnt vmcnt(0)
	v_pk_add_f32 v[128:129], v[128:129], 1.0 op_sel_hi:[1,0]
	v_pk_add_f32 v[130:131], v[130:131], 1.0 op_sel_hi:[1,0]
	v_pk_mul_f32 v[128:129], v[8:9], v[128:129]
	v_pk_mul_f32 v[130:131], v[10:11], v[130:131]
	v_pk_mul_f32 v[128:129], v[72:73], v[128:129]
	v_pk_mul_f32 v[130:131], v[74:75], v[130:131]
	v_cvt_pk_bf16_f32 v128, v128, v129
	s_nop 0
	v_cvt_pk_bf16_f32 v129, v130, v131
	global_store_dwordx2 v[132:133], v[128:129], off offset:1024
	global_load_dwordx4 v[128:131], v[66:67], off
	v_mul_f32_e32 v66, v83, v83
	v_mul_f32_e32 v67, v77, v77
	v_fmac_f32_e32 v66, v82, v82
	v_fmac_f32_e32 v67, v76, v76
	v_add_f32_e32 v64, v64, v66
	v_add_f32_e32 v66, v67, v134
	v_add_f32_e32 v67, v135, v136
	v_add_f32_e32 v64, v64, v66
	v_add_f32_e32 v134, v137, v138
	v_add_f32_e32 v64, v64, v67
	v_add_f32_e32 v64, v64, v134
	s_nop 1
	v_add_f32_dpp v64, v64, v64 quad_perm:[1,0,3,2] row_mask:0xf bank_mask:0xf
	s_nop 1
	v_add_f32_dpp v64, v64, v64 quad_perm:[2,3,0,1] row_mask:0xf bank_mask:0xf
	s_nop 1
	v_add_f32_dpp v64, v64, v64 row_half_mirror row_mask:0xf bank_mask:0xf
	s_nop 1
	v_add_f32_dpp v64, v64, v64 row_mirror row_mask:0xf bank_mask:0xf
	v_mov_b32_e32 v66, v64
	s_nop 1
	v_permlane16_swap_b32_e32 v64, v66
	v_add_f32_e32 v64, v64, v66
	v_mov_b32_e32 v66, v64
	s_nop 1
	v_permlane32_swap_b32_e32 v64, v66
	s_waitcnt vmcnt(0)
	v_pk_add_f32 v[128:129], v[128:129], 1.0 op_sel_hi:[1,0]
	v_pk_add_f32 v[130:131], v[130:131], 1.0 op_sel_hi:[1,0]
	v_pk_mul_f32 v[128:129], v[12:13], v[128:129]
	v_pk_mul_f32 v[130:131], v[14:15], v[130:131]
	v_pk_mul_f32 v[128:129], v[68:69], v[128:129]
	v_pk_mul_f32 v[130:131], v[70:71], v[130:131]
	v_cvt_pk_bf16_f32 v128, v128, v129
	s_nop 0
	v_cvt_pk_bf16_f32 v129, v130, v131
	global_store_dwordx2 v[132:133], v[128:129], off offset:1536
	s_and_saveexec_b64 s[8:9], s[2:3]
	s_cbranch_execz .LBB0_242
	v_add_f32_e32 v64, v64, v66
	s_lshl_b64 s[6:7], s[6:7], 6
	v_cndmask_b32_e64 v64, 0, v64, s[4:5]
	v_lshl_add_u64 v[128:129], v[124:125], 0, s[6:7]
	v_mov_b32_e32 v66, v65
	v_mov_b32_e32 v67, v65
	global_store_dwordx4 v[128:129], v[64:67], off
	s_branch .LBB0_242

.LBB0_741:
	v_mbcnt_lo_u32_b32 v0, -1, 0
	v_mbcnt_hi_u32_b32 v0, -1, v0
	s_nop 0
	v_cmp_gt_u32_e32 vcc, 32, v0
	s_and_saveexec_b64 s[4:5], vcc
	v_lshl_add_u32 v130, v0, 2, s14
	ds_write2_b32 v130, v202, v203 offset0:64 offset1:96
	s_or_b64 exec, exec, s[4:5]
	v_ashrrev_i32_e32 v134, 5, v0
	s_waitcnt lgkmcnt(0)
	v_lshl_add_u32 v139, v134, 4, s14
	ds_read_b128 v[140:143], v139 offset:256
	ds_read_b128 v[130:133], v139 offset:288
	ds_read_b128 v[144:147], v139 offset:384
	v_readlane_b32 s2, v255, 35
	v_and_b32_e32 v0, 31, v0
	s_waitcnt lgkmcnt(2)
	v_rcp_f32_e32 v140, v140
	s_waitcnt lgkmcnt(0)
	v_rcp_f32_e32 v135, v144
	s_nop 0
	v_mul_f32_e32 v144, s2, v135
	v_mul_f32_e32 v2, v2, v144
	v_fma_f32 v137, v114, v140, -v2
	v_mul_f32_e32 v2, v66, v144
	v_fma_f32 v136, v98, v140, -v2
	v_mul_f32_e32 v2, v34, v144
	v_fma_f32 v135, v82, v140, -v2
	v_mul_f32_e32 v2, v18, v144
	v_rcp_f32_e32 v18, v145
	v_fma_f32 v114, v50, v140, -v2
	v_rcp_f32_e32 v2, v141
	v_mul_f32_e32 v138, v136, v136
	v_mul_f32_e32 v18, s2, v18
	v_mul_f32_e32 v3, v3, v18
	v_fma_f32 v98, v115, v2, -v3
	v_mul_f32_e32 v3, v67, v18
	v_fma_f32 v82, v99, v2, -v3
	v_mul_f32_e32 v3, v35, v18
	v_fma_f32 v67, v83, v2, -v3
	v_mul_f32_e32 v3, v19, v18
	v_fma_f32 v66, v51, v2, -v3
	v_rcp_f32_e32 v3, v146
	v_rcp_f32_e32 v2, v142
	v_fmac_f32_e32 v138, v137, v137
	v_fmac_f32_e32 v138, v135, v135
	v_mul_f32_e32 v3, s2, v3
	v_mul_f32_e32 v4, v4, v3
	v_fma_f32 v51, v116, v2, -v4
	v_mul_f32_e32 v4, v68, v3
	v_fma_f32 v50, v100, v2, -v4
	v_mul_f32_e32 v4, v36, v3
	v_mul_f32_e32 v3, v20, v3
	v_fma_f32 v35, v52, v2, -v3
	v_rcp_f32_e32 v3, v147
	v_fma_f32 v36, v84, v2, -v4
	v_rcp_f32_e32 v2, v143
	v_fmac_f32_e32 v138, v114, v114
	v_mul_f32_e32 v3, s2, v3
	v_mul_f32_e32 v4, v5, v3
	v_fma_f32 v34, v117, v2, -v4
	v_mul_f32_e32 v4, v69, v3
	v_fma_f32 v20, v101, v2, -v4
	v_mul_f32_e32 v4, v37, v3
	v_mul_f32_e32 v3, v21, v3
	v_fma_f32 v19, v85, v2, -v4
	v_fma_f32 v18, v53, v2, -v3
	ds_read_b128 v[2:5], v139 offset:416
	v_rcp_f32_e32 v21, v130
	v_mul_f32_e32 v115, v82, v82
	v_fmac_f32_e32 v115, v98, v98
	v_fmac_f32_e32 v115, v67, v67
	s_waitcnt lgkmcnt(0)
	v_rcp_f32_e32 v2, v2
	v_rcp_f32_e32 v3, v3
	v_fmac_f32_e32 v115, v66, v66
	v_mul_f32_e32 v99, v50, v50
	v_mul_f32_e32 v2, s2, v2
	v_mul_f32_e32 v6, v6, v2
	v_fma_f32 v52, v118, v21, -v6
	v_mul_f32_e32 v6, v70, v2
	v_fma_f32 v37, v102, v21, -v6
	v_mul_f32_e32 v6, v38, v2
	v_mul_f32_e32 v2, v22, v2
	v_fma_f32 v38, v86, v21, -v6
	v_fma_f32 v21, v54, v21, -v2
	v_rcp_f32_e32 v2, v131
	v_mul_f32_e32 v3, s2, v3
	v_mul_f32_e32 v6, v7, v3
	v_fmac_f32_e32 v99, v51, v51
	v_fma_f32 v54, v119, v2, -v6
	v_mul_f32_e32 v6, v71, v3
	v_fma_f32 v53, v103, v2, -v6
	v_mul_f32_e32 v6, v39, v3
	v_mul_f32_e32 v3, v23, v3
	v_fma_f32 v22, v55, v2, -v3
	v_rcp_f32_e32 v3, v4
	v_fma_f32 v39, v87, v2, -v6
	v_rcp_f32_e32 v2, v132
	v_fmac_f32_e32 v99, v36, v36
	v_mul_f32_e32 v3, s2, v3
	v_mul_f32_e32 v4, v8, v3
	v_fma_f32 v69, v120, v2, -v4
	v_mul_f32_e32 v4, v72, v3
	v_fma_f32 v55, v104, v2, -v4
	v_mul_f32_e32 v4, v40, v3
	v_mul_f32_e32 v3, v24, v3
	v_fma_f32 v40, v56, v2, -v3
	v_rcp_f32_e32 v3, v5
	v_fma_f32 v68, v88, v2, -v4
	v_rcp_f32_e32 v2, v133
	v_fmac_f32_e32 v99, v35, v35
	v_mul_f32_e32 v3, s2, v3
	v_mul_f32_e32 v4, v9, v3
	v_fma_f32 v72, v121, v2, -v4
	v_mul_f32_e32 v4, v73, v3
	v_fma_f32 v70, v105, v2, -v4
	v_mul_f32_e32 v4, v41, v3
	v_mul_f32_e32 v3, v25, v3
	v_fma_f32 v71, v89, v2, -v4
	v_fma_f32 v56, v57, v2, -v3
	ds_read_b128 v[2:5], v139 offset:320
	ds_read_b128 v[6:9], v139 offset:448
	v_mul_f32_e32 v84, v20, v20
	v_fmac_f32_e32 v84, v34, v34
	v_fmac_f32_e32 v84, v19, v19
	s_waitcnt lgkmcnt(1)
	v_rcp_f32_e32 v2, v2
	s_waitcnt lgkmcnt(0)
	v_rcp_f32_e32 v6, v6
	v_fmac_f32_e32 v84, v18, v18
	v_mul_f32_e32 v101, v37, v37
	v_fmac_f32_e32 v101, v52, v52
	v_mul_f32_e32 v6, s2, v6
	v_mul_f32_e32 v10, v10, v6
	v_fma_f32 v83, v122, v2, -v10
	v_mul_f32_e32 v10, v74, v6
	v_fma_f32 v74, v106, v2, -v10
	v_mul_f32_e32 v10, v42, v6
	v_mul_f32_e32 v6, v26, v6
	v_fma_f32 v73, v90, v2, -v10
	v_fma_f32 v58, v58, v2, -v6
	v_rcp_f32_e32 v2, v3
	v_rcp_f32_e32 v3, v7
	v_fmac_f32_e32 v101, v38, v38
	v_fmac_f32_e32 v101, v21, v21
	v_mul_f32_e32 v100, v53, v53
	v_mul_f32_e32 v3, s2, v3
	v_mul_f32_e32 v6, v11, v3
	v_fma_f32 v57, v123, v2, -v6
	v_mul_f32_e32 v6, v75, v3
	v_fma_f32 v42, v107, v2, -v6
	v_mul_f32_e32 v6, v43, v3
	v_mul_f32_e32 v3, v27, v3
	v_fma_f32 v27, v59, v2, -v3
	v_rcp_f32_e32 v3, v8
	v_fma_f32 v41, v91, v2, -v6
	v_rcp_f32_e32 v2, v4
	v_fmac_f32_e32 v100, v54, v54
	v_mul_f32_e32 v3, s2, v3
	v_mul_f32_e32 v4, v12, v3
	v_fma_f32 v26, v124, v2, -v4
	v_mul_f32_e32 v4, v76, v3
	v_fma_f32 v25, v108, v2, -v4
	v_mul_f32_e32 v4, v44, v3
	v_mul_f32_e32 v3, v28, v3
	v_fma_f32 v23, v60, v2, -v3
	v_rcp_f32_e32 v3, v9
	v_fma_f32 v24, v92, v2, -v4
	v_rcp_f32_e32 v2, v5
	ds_read_b128 v[6:9], v139 offset:480
	v_mul_f32_e32 v3, s2, v3
	v_mul_f32_e32 v4, v13, v3
	v_fma_f32 v13, v125, v2, -v4
	v_mul_f32_e32 v4, v77, v3
	v_fma_f32 v12, v109, v2, -v4
	v_mul_f32_e32 v4, v45, v3
	v_mul_f32_e32 v3, v29, v3
	v_fma_f32 v11, v93, v2, -v4
	v_fma_f32 v10, v61, v2, -v3
	ds_read_b128 v[2:5], v139 offset:352
	s_waitcnt lgkmcnt(1)
	v_rcp_f32_e32 v7, v7
	v_fmac_f32_e32 v100, v39, v39
	v_fmac_f32_e32 v100, v22, v22
	v_mul_f32_e32 v87, v55, v55
	s_waitcnt lgkmcnt(0)
	v_rcp_f32_e32 v43, v2
	v_rcp_f32_e32 v2, v6
	v_rcp_f32_e32 v3, v3
	v_mul_f32_e32 v7, s2, v7
	v_mul_f32_e32 v15, v15, v7
	v_mul_f32_e32 v6, s2, v2
	v_mul_f32_e32 v2, v14, v6
	v_fma_f32 v29, v126, v43, -v2
	v_mul_f32_e32 v2, v78, v6
	v_mul_f32_e32 v28, v46, v6
	v_mul_f32_e32 v6, v30, v6
	v_fma_f32 v14, v110, v43, -v2
	v_fma_f32 v28, v94, v43, -v28
	v_fma_f32 v6, v62, v43, -v6
	v_fma_f32 v43, v127, v3, -v15
	v_mul_f32_e32 v15, v79, v7
	v_mul_f32_e32 v30, v47, v7
	v_mul_f32_e32 v7, v31, v7
	v_fma_f32 v15, v111, v3, -v15
	v_fma_f32 v30, v95, v3, -v30
	v_fma_f32 v7, v63, v3, -v7
	v_rcp_f32_e32 v3, v4
	v_rcp_f32_e32 v4, v8
	v_fmac_f32_e32 v87, v69, v69
	v_fmac_f32_e32 v87, v68, v68
	v_fmac_f32_e32 v87, v40, v40
	v_mul_f32_e32 v4, s2, v4
	v_mul_f32_e32 v8, v16, v4
	v_fma_f32 v31, v128, v3, -v8
	v_mul_f32_e32 v8, v80, v4
	v_mul_f32_e32 v16, v48, v4
	v_mul_f32_e32 v4, v32, v4
	v_fma_f32 v8, v112, v3, -v8
	v_fma_f32 v16, v96, v3, -v16
	v_fma_f32 v4, v64, v3, -v4
	v_rcp_f32_e32 v3, v5
	v_rcp_f32_e32 v5, v9
	v_mul_f32_e32 v86, v70, v70
	v_fmac_f32_e32 v86, v72, v72
	v_fmac_f32_e32 v86, v71, v71
	v_mul_f32_e32 v5, s2, v5
	v_mul_f32_e32 v9, v17, v5
	v_fma_f32 v32, v129, v3, -v9
	v_mul_f32_e32 v9, v81, v5
	v_fma_f32 v17, v113, v3, -v9
	v_mul_f32_e32 v9, v49, v5
	v_mul_f32_e32 v5, v33, v5
	v_fma_f32 v9, v97, v3, -v9
	v_fma_f32 v5, v65, v3, -v5
	v_fmac_f32_e32 v86, v56, v56
	v_mul_f32_e32 v85, v74, v74
	v_fmac_f32_e32 v85, v83, v83
	v_fmac_f32_e32 v85, v73, v73
	s_nop 1
	v_add_f32_dpp v3, v138, v138 quad_perm:[1,0,3,2] row_mask:0xf bank_mask:0xf
	v_fmac_f32_e32 v85, v58, v58
	v_mul_f32_e32 v75, v42, v42
	v_fmac_f32_e32 v75, v57, v57
	v_fmac_f32_e32 v75, v41, v41
	s_nop 1
	v_add_f32_dpp v3, v3, v3 quad_perm:[2,3,0,1] row_mask:0xf bank_mask:0xf
	v_fmac_f32_e32 v75, v27, v27
	v_mul_f32_e32 v59, v25, v25
	v_fmac_f32_e32 v59, v26, v26
	v_fmac_f32_e32 v59, v24, v24
	s_nop 1
	v_add_f32_dpp v3, v3, v3 row_half_mirror row_mask:0xf bank_mask:0xf
	v_fmac_f32_e32 v59, v23, v23
	v_mul_f32_e32 v44, v12, v12
	v_fmac_f32_e32 v44, v13, v13
	v_fmac_f32_e32 v44, v11, v11
	s_nop 1
	v_add_f32_dpp v3, v3, v3 row_mirror row_mask:0xf bank_mask:0xf
	v_mov_b32_e32 v33, v3
	v_fmac_f32_e32 v44, v10, v10
	v_mul_f32_e32 v2, v14, v14
	v_fmac_f32_e32 v2, v29, v29
	v_fmac_f32_e32 v2, v28, v28
	s_nop 1
	v_permlane16_swap_b32_e32 v3, v33
	v_add_f32_e32 v3, v3, v33
	v_fmac_f32_e32 v2, v6, v6
	v_mul_f32_e32 v76, v15, v15
	v_fmac_f32_e32 v76, v43, v43
	v_fmac_f32_e32 v76, v30, v30
	s_nop 1
	v_add_f32_dpp v33, v115, v115 quad_perm:[1,0,3,2] row_mask:0xf bank_mask:0xf
	v_fmac_f32_e32 v76, v7, v7
	v_mul_f32_e32 v77, v8, v8
	v_fmac_f32_e32 v77, v31, v31
	v_fmac_f32_e32 v77, v16, v16
	s_nop 1
	v_add_f32_dpp v33, v33, v33 quad_perm:[2,3,0,1] row_mask:0xf bank_mask:0xf
	v_fmac_f32_e32 v77, v4, v4
	v_mul_f32_e32 v78, v17, v17
	v_fmac_f32_e32 v78, v32, v32
	v_fmac_f32_e32 v78, v9, v9
	s_nop 1
	v_add_f32_dpp v33, v33, v33 row_half_mirror row_mask:0xf bank_mask:0xf
	v_fmac_f32_e32 v78, v5, v5
	v_readlane_b32 s2, v255, 16
	v_readlane_b32 s3, v255, 17
	s_nop 1
	v_add_f32_dpp v33, v33, v33 row_mirror row_mask:0xf bank_mask:0xf
	v_mov_b32_e32 v45, v33
	s_cmp_eq_u32 s2, 0
	v_readlane_b32 s2, v255, 26
	v_lshlrev_b32_e32 v79, 2, v0
	v_readlane_b32 s3, v255, 27
	s_nop 1
	v_permlane16_swap_b32_e32 v33, v45
	v_add_f32_e32 v33, v33, v45
	v_fmamk_f32 v3, v3, 0x3c000000, v244
	s_cselect_b64 vcc, -1, 0
	s_lshl_b32 s36, s1, 1
	v_lshlrev_b32_e32 v0, 1, v0
	s_nop 1
	v_add_f32_dpp v45, v99, v99 quad_perm:[1,0,3,2] row_mask:0xf bank_mask:0xf
	s_nop 1
	v_add_f32_dpp v45, v45, v45 quad_perm:[2,3,0,1] row_mask:0xf bank_mask:0xf
	s_nop 1
	v_add_f32_dpp v45, v45, v45 row_half_mirror row_mask:0xf bank_mask:0xf
	s_nop 1
	v_add_f32_dpp v45, v45, v45 row_mirror row_mask:0xf bank_mask:0xf
	v_mov_b32_e32 v46, v45
	s_nop 1
	v_permlane16_swap_b32_e32 v45, v46
	v_add_f32_e32 v45, v45, v46
	s_nop 1
	v_add_f32_dpp v46, v84, v84 quad_perm:[1,0,3,2] row_mask:0xf bank_mask:0xf
	v_rsq_f32_e32 v84, v3
	s_nop 1
	v_add_f32_dpp v46, v46, v46 quad_perm:[2,3,0,1] row_mask:0xf bank_mask:0xf
	s_nop 1
	v_add_f32_dpp v46, v46, v46 row_half_mirror row_mask:0xf bank_mask:0xf
	s_nop 1
	v_add_f32_dpp v46, v46, v46 row_mirror row_mask:0xf bank_mask:0xf
	v_mov_b32_e32 v47, v46
	s_nop 1
	v_permlane16_swap_b32_e32 v46, v47
	v_add_f32_e32 v46, v46, v47
	s_nop 1
	v_add_f32_dpp v47, v101, v101 quad_perm:[1,0,3,2] row_mask:0xf bank_mask:0xf
	s_nop 1
	v_add_f32_dpp v47, v47, v47 quad_perm:[2,3,0,1] row_mask:0xf bank_mask:0xf
	s_nop 1
	v_add_f32_dpp v47, v47, v47 row_half_mirror row_mask:0xf bank_mask:0xf
	s_nop 1
	v_add_f32_dpp v47, v47, v47 row_mirror row_mask:0xf bank_mask:0xf
	v_mov_b32_e32 v48, v47
	s_nop 1
	v_permlane16_swap_b32_e32 v47, v48
	v_add_f32_e32 v47, v47, v48
	s_nop 1
	v_add_f32_dpp v48, v100, v100 quad_perm:[1,0,3,2] row_mask:0xf bank_mask:0xf
	s_nop 1
	v_add_f32_dpp v48, v48, v48 quad_perm:[2,3,0,1] row_mask:0xf bank_mask:0xf
	s_nop 1
	v_add_f32_dpp v48, v48, v48 row_half_mirror row_mask:0xf bank_mask:0xf
	s_nop 1
	v_add_f32_dpp v48, v48, v48 row_mirror row_mask:0xf bank_mask:0xf
	v_mov_b32_e32 v49, v48
	s_nop 1
	v_permlane16_swap_b32_e32 v48, v49
	v_add_f32_e32 v48, v48, v49
	s_nop 1
	v_add_f32_dpp v49, v87, v87 quad_perm:[1,0,3,2] row_mask:0xf bank_mask:0xf
	s_nop 1
	v_add_f32_dpp v49, v49, v49 quad_perm:[2,3,0,1] row_mask:0xf bank_mask:0xf
	s_nop 1
	v_add_f32_dpp v49, v49, v49 row_half_mirror row_mask:0xf bank_mask:0xf
	s_nop 1
	v_add_f32_dpp v49, v49, v49 row_mirror row_mask:0xf bank_mask:0xf
	ds_swizzle_b32 v60, v49 offset:swizzle(SWAP,16)
	s_waitcnt lgkmcnt(0)
	v_add_f32_e32 v60, v49, v60
	s_nop 1
	v_add_f32_dpp v49, v86, v86 quad_perm:[1,0,3,2] row_mask:0xf bank_mask:0xf
	s_nop 1
	v_add_f32_dpp v49, v49, v49 quad_perm:[2,3,0,1] row_mask:0xf bank_mask:0xf
	s_nop 1
	v_add_f32_dpp v49, v49, v49 row_half_mirror row_mask:0xf bank_mask:0xf
	s_nop 1
	v_add_f32_dpp v49, v49, v49 row_mirror row_mask:0xf bank_mask:0xf
	ds_swizzle_b32 v61, v49 offset:swizzle(SWAP,16)
	s_waitcnt lgkmcnt(0)
	v_add_f32_e32 v62, v49, v61
	s_nop 1
	v_add_f32_dpp v49, v85, v85 quad_perm:[1,0,3,2] row_mask:0xf bank_mask:0xf
	s_nop 1
	v_add_f32_dpp v49, v49, v49 quad_perm:[2,3,0,1] row_mask:0xf bank_mask:0xf
	s_nop 1
	v_add_f32_dpp v49, v49, v49 row_half_mirror row_mask:0xf bank_mask:0xf
	s_nop 1
	v_add_f32_dpp v49, v49, v49 row_mirror row_mask:0xf bank_mask:0xf
	ds_swizzle_b32 v61, v49 offset:swizzle(SWAP,16)
	s_waitcnt lgkmcnt(0)
	v_add_f32_e32 v64, v49, v61
	s_nop 1
	v_add_f32_dpp v49, v75, v75 quad_perm:[1,0,3,2] row_mask:0xf bank_mask:0xf
	s_nop 1
	v_add_f32_dpp v49, v49, v49 quad_perm:[2,3,0,1] row_mask:0xf bank_mask:0xf
	s_nop 1
	v_add_f32_dpp v49, v49, v49 row_half_mirror row_mask:0xf bank_mask:0xf
	s_nop 1
	v_add_f32_dpp v49, v49, v49 row_mirror row_mask:0xf bank_mask:0xf
	ds_swizzle_b32 v61, v49 offset:swizzle(SWAP,16)
	s_waitcnt lgkmcnt(0)
	v_add_f32_e32 v75, v49, v61
	s_nop 1
	v_add_f32_dpp v49, v59, v59 quad_perm:[1,0,3,2] row_mask:0xf bank_mask:0xf
	s_nop 1
	v_add_f32_dpp v49, v49, v49 quad_perm:[2,3,0,1] row_mask:0xf bank_mask:0xf
	s_nop 1
	v_add_f32_dpp v49, v49, v49 row_half_mirror row_mask:0xf bank_mask:0xf
	s_nop 1
	v_add_f32_dpp v49, v49, v49 row_mirror row_mask:0xf bank_mask:0xf
	ds_swizzle_b32 v59, v49 offset:swizzle(SWAP,16)
	s_waitcnt lgkmcnt(0)
	v_add_f32_e32 v65, v49, v59
	s_nop 1
	v_add_f32_dpp v44, v44, v44 quad_perm:[1,0,3,2] row_mask:0xf bank_mask:0xf
	s_nop 1
	v_add_f32_dpp v44, v44, v44 quad_perm:[2,3,0,1] row_mask:0xf bank_mask:0xf
	s_nop 1
	v_add_f32_dpp v44, v44, v44 row_half_mirror row_mask:0xf bank_mask:0xf
	s_nop 1
	v_add_f32_dpp v44, v44, v44 row_mirror row_mask:0xf bank_mask:0xf
	ds_swizzle_b32 v49, v44 offset:swizzle(SWAP,16)
	s_waitcnt lgkmcnt(0)
	v_add_f32_e32 v63, v44, v49
	s_nop 1
	v_add_f32_dpp v2, v2, v2 quad_perm:[1,0,3,2] row_mask:0xf bank_mask:0xf
	s_nop 1
	v_add_f32_dpp v2, v2, v2 quad_perm:[2,3,0,1] row_mask:0xf bank_mask:0xf
	s_nop 1
	v_add_f32_dpp v2, v2, v2 row_half_mirror row_mask:0xf bank_mask:0xf
	s_nop 1
	v_add_f32_dpp v2, v2, v2 row_mirror row_mask:0xf bank_mask:0xf
	ds_swizzle_b32 v44, v2 offset:swizzle(SWAP,16)
	s_waitcnt lgkmcnt(0)
	v_add_f32_e32 v61, v2, v44
	s_nop 1
	v_add_f32_dpp v2, v76, v76 quad_perm:[1,0,3,2] row_mask:0xf bank_mask:0xf
	global_load_dword v76, v79, s[2:3]
	s_nop 1
	v_add_f32_dpp v2, v2, v2 quad_perm:[2,3,0,1] row_mask:0xf bank_mask:0xf
	s_nop 1
	v_add_f32_dpp v2, v2, v2 row_half_mirror row_mask:0xf bank_mask:0xf
	s_nop 1
	v_add_f32_dpp v2, v2, v2 row_mirror row_mask:0xf bank_mask:0xf
	ds_swizzle_b32 v44, v2 offset:swizzle(SWAP,16)
	s_waitcnt lgkmcnt(0)
	v_add_f32_e32 v59, v2, v44
	s_nop 1
	v_add_f32_dpp v2, v77, v77 quad_perm:[1,0,3,2] row_mask:0xf bank_mask:0xf
	global_load_dword v77, v79, s[2:3] offset:128
	s_nop 1
	v_add_f32_dpp v2, v2, v2 quad_perm:[2,3,0,1] row_mask:0xf bank_mask:0xf
	s_nop 1
	v_add_f32_dpp v2, v2, v2 row_half_mirror row_mask:0xf bank_mask:0xf
	s_nop 1
	v_add_f32_dpp v2, v2, v2 row_mirror row_mask:0xf bank_mask:0xf
	ds_swizzle_b32 v44, v2 offset:swizzle(SWAP,16)
	s_waitcnt lgkmcnt(0)
	v_add_f32_e32 v49, v2, v44
	s_nop 1
	v_add_f32_dpp v2, v78, v78 quad_perm:[1,0,3,2] row_mask:0xf bank_mask:0xf
	global_load_dword v78, v79, s[2:3] offset:256
	global_load_dword v79, v79, s[2:3] offset:384
	v_readlane_b32 s2, v254, 63
	v_readlane_b32 s3, v255, 0
	s_nop 1
	v_add_f32_dpp v2, v2, v2 quad_perm:[2,3,0,1] row_mask:0xf bank_mask:0xf
	s_nop 1
	v_add_f32_dpp v2, v2, v2 row_half_mirror row_mask:0xf bank_mask:0xf
	s_nop 1
	v_add_f32_dpp v2, v2, v2 row_mirror row_mask:0xf bank_mask:0xf
	ds_swizzle_b32 v44, v2 offset:swizzle(SWAP,16)
	s_waitcnt lgkmcnt(0)
	v_add_f32_e32 v44, v2, v44
	v_cndmask_b32_e32 v2, v252, v246, vcc
	s_waitcnt vmcnt(3)
	v_mul_f32_e32 v76, v76, v2
	s_waitcnt vmcnt(2)
	v_mul_f32_e32 v77, v2, v77
	s_waitcnt vmcnt(1)
	v_mul_f32_e32 v78, v2, v78
	s_waitcnt vmcnt(0)
	v_mul_f32_e32 v79, v2, v79
	v_lshl_add_u32 v2, v134, 2, s0
	v_ashrrev_i32_e32 v3, 31, v2
	v_lshlrev_b64 v[80:81], 11, v[2:3]
	v_mul_f32_e32 v3, v137, v84
	v_lshl_add_u64 v[80:81], s[2:3], 0, v[80:81]
	v_mul_f32_e32 v3, v3, v76
	v_lshl_add_u64 v[80:81], v[80:81], 0, s[36:37]
	v_bfe_u32 v85, v3, 16, 1
	v_lshl_add_u64 v[80:81], v[80:81], 0, v[0:1]
	v_add3_u32 v3, v3, v85, s86
	global_store_short_d16_hi v[80:81], v3, off offset:1024
	v_mul_f32_e32 v3, v136, v84
	v_mul_f32_e32 v3, v3, v77
	v_bfe_u32 v85, v3, 16, 1
	v_add3_u32 v3, v3, v85, s86
	global_store_short_d16_hi v[80:81], v3, off offset:1088
	v_mul_f32_e32 v3, v135, v84
	v_mul_f32_e32 v3, v3, v78
	v_bfe_u32 v85, v3, 16, 1
	v_add3_u32 v3, v3, v85, s86
	global_store_short_d16_hi v[80:81], v3, off offset:1152
	v_mul_f32_e32 v3, v114, v84
	v_mul_f32_e32 v3, v3, v79
	v_bfe_u32 v84, v3, 16, 1
	v_add3_u32 v3, v3, v84, s86
	global_store_short_d16_hi v[80:81], v3, off offset:1216
	v_fmamk_f32 v3, v33, 0x3c000000, v244
	v_rsq_f32_e32 v3, v3
	v_or_b32_e32 v80, 1, v2
	v_ashrrev_i32_e32 v81, 31, v80
	v_lshlrev_b64 v[80:81], 11, v[80:81]
	v_mul_f32_e32 v33, v98, v3
	v_lshl_add_u64 v[80:81], s[2:3], 0, v[80:81]
	v_mul_f32_e32 v33, v33, v76
	v_lshl_add_u64 v[80:81], v[80:81], 0, s[36:37]
	v_bfe_u32 v84, v33, 16, 1
	v_lshl_add_u64 v[80:81], v[80:81], 0, v[0:1]
	v_add3_u32 v33, v33, v84, s86
	global_store_short_d16_hi v[80:81], v33, off offset:1024
	v_mul_f32_e32 v33, v82, v3
	v_mul_f32_e32 v33, v33, v77
	v_bfe_u32 v82, v33, 16, 1
	v_add3_u32 v33, v33, v82, s86
	global_store_short_d16_hi v[80:81], v33, off offset:1088
	v_mul_f32_e32 v33, v67, v3
	v_mul_f32_e32 v33, v33, v78
	v_bfe_u32 v67, v33, 16, 1
	v_mul_f32_e32 v3, v66, v3
	v_add3_u32 v33, v33, v67, s86
	v_mul_f32_e32 v3, v3, v79
	global_store_short_d16_hi v[80:81], v33, off offset:1152
	v_bfe_u32 v33, v3, 16, 1
	v_add3_u32 v3, v3, v33, s86
	global_store_short_d16_hi v[80:81], v3, off offset:1216
	v_fmamk_f32 v3, v45, 0x3c000000, v244
	v_rsq_f32_e32 v3, v3
	v_or_b32_e32 v66, 2, v2
	v_ashrrev_i32_e32 v67, 31, v66
	v_lshlrev_b64 v[66:67], 11, v[66:67]
	v_mul_f32_e32 v33, v51, v3
	v_lshl_add_u64 v[66:67], s[2:3], 0, v[66:67]
	v_mul_f32_e32 v33, v33, v76
	v_lshl_add_u64 v[66:67], v[66:67], 0, s[36:37]
	v_bfe_u32 v45, v33, 16, 1
	v_lshl_add_u64 v[66:67], v[66:67], 0, v[0:1]
	v_add3_u32 v33, v33, v45, s86
	global_store_short_d16_hi v[66:67], v33, off offset:1024
	v_mul_f32_e32 v33, v50, v3
	v_mul_f32_e32 v33, v33, v77
	v_bfe_u32 v45, v33, 16, 1
	v_add3_u32 v33, v33, v45, s86
	global_store_short_d16_hi v[66:67], v33, off offset:1088
	v_mul_f32_e32 v33, v36, v3
	v_mul_f32_e32 v33, v33, v78
	v_bfe_u32 v36, v33, 16, 1
	v_mul_f32_e32 v3, v35, v3
	v_add3_u32 v33, v33, v36, s86
	v_mul_f32_e32 v3, v3, v79
	global_store_short_d16_hi v[66:67], v33, off offset:1152
	v_bfe_u32 v33, v3, 16, 1
	v_add3_u32 v3, v3, v33, s86
	global_store_short_d16_hi v[66:67], v3, off offset:1216
	v_fmamk_f32 v3, v46, 0x3c000000, v244
	v_rsq_f32_e32 v3, v3
	v_or_b32_e32 v50, 3, v2
	v_ashrrev_i32_e32 v51, 31, v50
	v_lshlrev_b64 v[50:51], 11, v[50:51]
	v_mul_f32_e32 v33, v34, v3
	v_mul_f32_e32 v20, v20, v3
	v_mul_f32_e32 v19, v19, v3
	v_mul_f32_e32 v3, v18, v3
	v_lshl_add_u64 v[50:51], s[2:3], 0, v[50:51]
	v_mul_f32_e32 v33, v33, v76
	v_mul_f32_e32 v3, v3, v79
	v_lshl_add_u64 v[50:51], v[50:51], 0, s[36:37]
	v_bfe_u32 v34, v33, 16, 1
	v_bfe_u32 v18, v3, 16, 1
	v_lshl_add_u64 v[50:51], v[50:51], 0, v[0:1]
	v_add3_u32 v33, v33, v34, s86
	v_mul_f32_e32 v20, v20, v77
	v_add3_u32 v3, v3, v18, s86
	global_store_short_d16_hi v[50:51], v33, off offset:1024
	v_bfe_u32 v33, v20, 16, 1
	global_store_short_d16_hi v[50:51], v3, off offset:1216
	v_fmamk_f32 v3, v47, 0x3c000000, v244
	v_add3_u32 v20, v20, v33, s86
	v_mul_f32_e32 v19, v19, v78
	v_rsq_f32_e32 v3, v3
	global_store_short_d16_hi v[50:51], v20, off offset:1088
	v_bfe_u32 v20, v19, 16, 1
	v_add3_u32 v19, v19, v20, s86
	v_add_u32_e32 v18, 8, v2
	global_store_short_d16_hi v[50:51], v19, off offset:1152
	v_ashrrev_i32_e32 v19, 31, v18
	v_lshlrev_b64 v[18:19], 11, v[18:19]
	v_mul_f32_e32 v20, v52, v3
	v_lshl_add_u64 v[18:19], s[2:3], 0, v[18:19]
	v_mul_f32_e32 v20, v20, v76
	v_lshl_add_u64 v[18:19], v[18:19], 0, s[36:37]
	v_bfe_u32 v33, v20, 16, 1
	v_lshl_add_u64 v[18:19], v[18:19], 0, v[0:1]
	v_add3_u32 v20, v20, v33, s86
	global_store_short_d16_hi v[18:19], v20, off offset:1024
	v_mul_f32_e32 v20, v37, v3
	v_mul_f32_e32 v20, v20, v77
	v_bfe_u32 v33, v20, 16, 1
	v_add3_u32 v20, v20, v33, s86
	global_store_short_d16_hi v[18:19], v20, off offset:1088
	v_mul_f32_e32 v20, v38, v3
	v_mul_f32_e32 v20, v20, v78
	v_bfe_u32 v33, v20, 16, 1
	v_mul_f32_e32 v3, v21, v3
	v_add3_u32 v20, v20, v33, s86
	v_mul_f32_e32 v3, v3, v79
	global_store_short_d16_hi v[18:19], v20, off offset:1152
	v_bfe_u32 v20, v3, 16, 1
	v_add3_u32 v3, v3, v20, s86
	global_store_short_d16_hi v[18:19], v3, off offset:1216
	v_fmamk_f32 v3, v48, 0x3c000000, v244
	v_rsq_f32_e32 v3, v3
	v_add_u32_e32 v18, 9, v2
	v_ashrrev_i32_e32 v19, 31, v18
	v_lshlrev_b64 v[18:19], 11, v[18:19]
	v_mul_f32_e32 v20, v54, v3
	v_lshl_add_u64 v[18:19], s[2:3], 0, v[18:19]
	v_mul_f32_e32 v20, v20, v76
	v_lshl_add_u64 v[18:19], v[18:19], 0, s[36:37]
	v_bfe_u32 v21, v20, 16, 1
	v_lshl_add_u64 v[18:19], v[18:19], 0, v[0:1]
	v_add3_u32 v20, v20, v21, s86
	global_store_short_d16_hi v[18:19], v20, off offset:1024
	v_mul_f32_e32 v20, v53, v3
	v_mul_f32_e32 v20, v20, v77
	v_bfe_u32 v21, v20, 16, 1
	v_add3_u32 v20, v20, v21, s86
	global_store_short_d16_hi v[18:19], v20, off offset:1088
	v_mul_f32_e32 v20, v39, v3
	v_mul_f32_e32 v20, v20, v78
	v_bfe_u32 v21, v20, 16, 1
	v_mul_f32_e32 v3, v22, v3
	v_add3_u32 v20, v20, v21, s86
	v_mul_f32_e32 v3, v3, v79
	global_store_short_d16_hi v[18:19], v20, off offset:1152
	v_bfe_u32 v20, v3, 16, 1
	v_add3_u32 v3, v3, v20, s86
	global_store_short_d16_hi v[18:19], v3, off offset:1216
	v_fmamk_f32 v3, v60, 0x3c000000, v244
	v_rsq_f32_e32 v3, v3
	v_add_u32_e32 v18, 10, v2
	v_ashrrev_i32_e32 v19, 31, v18
	v_lshlrev_b64 v[18:19], 11, v[18:19]
	v_mul_f32_e32 v20, v69, v3
	v_lshl_add_u64 v[18:19], s[2:3], 0, v[18:19]
	v_mul_f32_e32 v20, v20, v76
	v_lshl_add_u64 v[18:19], v[18:19], 0, s[36:37]
	v_bfe_u32 v21, v20, 16, 1
	v_lshl_add_u64 v[18:19], v[18:19], 0, v[0:1]
	v_add3_u32 v20, v20, v21, s86
	global_store_short_d16_hi v[18:19], v20, off offset:1024
	v_mul_f32_e32 v20, v55, v3
	v_mul_f32_e32 v20, v20, v77
	v_bfe_u32 v21, v20, 16, 1
	v_add3_u32 v20, v20, v21, s86
	global_store_short_d16_hi v[18:19], v20, off offset:1088
	v_mul_f32_e32 v20, v68, v3
	v_mul_f32_e32 v20, v20, v78
	v_bfe_u32 v21, v20, 16, 1
	v_mul_f32_e32 v3, v40, v3
	v_add3_u32 v20, v20, v21, s86
	v_mul_f32_e32 v3, v3, v79
	global_store_short_d16_hi v[18:19], v20, off offset:1152
	v_bfe_u32 v20, v3, 16, 1
	v_add3_u32 v3, v3, v20, s86
	global_store_short_d16_hi v[18:19], v3, off offset:1216
	v_fmamk_f32 v3, v62, 0x3c000000, v244
	v_rsq_f32_e32 v3, v3
	v_add_u32_e32 v18, 11, v2
	v_ashrrev_i32_e32 v19, 31, v18
	v_lshlrev_b64 v[18:19], 11, v[18:19]
	v_mul_f32_e32 v20, v72, v3
	v_lshl_add_u64 v[18:19], s[2:3], 0, v[18:19]
	v_mul_f32_e32 v20, v20, v76
	v_lshl_add_u64 v[18:19], v[18:19], 0, s[36:37]
	v_bfe_u32 v21, v20, 16, 1
	v_lshl_add_u64 v[18:19], v[18:19], 0, v[0:1]
	v_add3_u32 v20, v20, v21, s86
	global_store_short_d16_hi v[18:19], v20, off offset:1024
	v_mul_f32_e32 v20, v70, v3
	v_mul_f32_e32 v20, v20, v77
	v_bfe_u32 v21, v20, 16, 1
	v_add3_u32 v20, v20, v21, s86
	global_store_short_d16_hi v[18:19], v20, off offset:1088
	v_mul_f32_e32 v20, v71, v3
	v_mul_f32_e32 v20, v20, v78
	v_bfe_u32 v21, v20, 16, 1
	v_mul_f32_e32 v3, v56, v3
	v_add3_u32 v20, v20, v21, s86
	v_mul_f32_e32 v3, v3, v79
	global_store_short_d16_hi v[18:19], v20, off offset:1152
	v_bfe_u32 v20, v3, 16, 1
	v_add3_u32 v3, v3, v20, s86
	global_store_short_d16_hi v[18:19], v3, off offset:1216
	v_fmamk_f32 v3, v64, 0x3c000000, v244
	v_rsq_f32_e32 v3, v3
	v_add_u32_e32 v18, 16, v2
	v_ashrrev_i32_e32 v19, 31, v18
	v_lshlrev_b64 v[18:19], 11, v[18:19]
	v_mul_f32_e32 v20, v83, v3
	v_lshl_add_u64 v[18:19], s[2:3], 0, v[18:19]
	v_mul_f32_e32 v20, v20, v76
	v_lshl_add_u64 v[18:19], v[18:19], 0, s[36:37]
	v_bfe_u32 v21, v20, 16, 1
	v_lshl_add_u64 v[18:19], v[18:19], 0, v[0:1]
	v_add3_u32 v20, v20, v21, s86
	global_store_short_d16_hi v[18:19], v20, off offset:1024
	v_mul_f32_e32 v20, v74, v3
	v_mul_f32_e32 v20, v20, v77
	v_bfe_u32 v21, v20, 16, 1
	v_add3_u32 v20, v20, v21, s86
	global_store_short_d16_hi v[18:19], v20, off offset:1088
	v_mul_f32_e32 v20, v73, v3
	v_mul_f32_e32 v20, v20, v78
	v_bfe_u32 v21, v20, 16, 1
	v_mul_f32_e32 v3, v58, v3
	v_add3_u32 v20, v20, v21, s86
	v_mul_f32_e32 v3, v3, v79
	global_store_short_d16_hi v[18:19], v20, off offset:1152
	v_bfe_u32 v20, v3, 16, 1
	v_add3_u32 v3, v3, v20, s86
	global_store_short_d16_hi v[18:19], v3, off offset:1216
	v_fmamk_f32 v3, v75, 0x3c000000, v244
	v_rsq_f32_e32 v3, v3
	v_add_u32_e32 v18, 17, v2
	v_ashrrev_i32_e32 v19, 31, v18
	v_lshlrev_b64 v[18:19], 11, v[18:19]
	v_mul_f32_e32 v20, v57, v3
	v_lshl_add_u64 v[18:19], s[2:3], 0, v[18:19]
	v_mul_f32_e32 v20, v20, v76
	v_lshl_add_u64 v[18:19], v[18:19], 0, s[36:37]
	v_bfe_u32 v21, v20, 16, 1
	v_lshl_add_u64 v[18:19], v[18:19], 0, v[0:1]
	v_add3_u32 v20, v20, v21, s86
	global_store_short_d16_hi v[18:19], v20, off offset:1024
	v_mul_f32_e32 v20, v42, v3
	v_mul_f32_e32 v20, v20, v77
	v_bfe_u32 v21, v20, 16, 1
	v_add3_u32 v20, v20, v21, s86
	global_store_short_d16_hi v[18:19], v20, off offset:1088
	v_mul_f32_e32 v20, v41, v3
	v_mul_f32_e32 v20, v20, v78
	v_bfe_u32 v21, v20, 16, 1
	v_mul_f32_e32 v3, v27, v3
	v_add3_u32 v20, v20, v21, s86
	v_mul_f32_e32 v3, v3, v79
	global_store_short_d16_hi v[18:19], v20, off offset:1152
	v_bfe_u32 v20, v3, 16, 1
	v_add3_u32 v3, v3, v20, s86
	global_store_short_d16_hi v[18:19], v3, off offset:1216
	v_fmamk_f32 v3, v65, 0x3c000000, v244
	v_rsq_f32_e32 v3, v3
	v_add_u32_e32 v18, 18, v2
	v_ashrrev_i32_e32 v19, 31, v18
	v_lshlrev_b64 v[18:19], 11, v[18:19]
	v_mul_f32_e32 v20, v26, v3
	v_lshl_add_u64 v[18:19], s[2:3], 0, v[18:19]
	v_mul_f32_e32 v20, v20, v76
	v_lshl_add_u64 v[18:19], v[18:19], 0, s[36:37]
	v_bfe_u32 v21, v20, 16, 1
	v_lshl_add_u64 v[18:19], v[18:19], 0, v[0:1]
	v_add3_u32 v20, v20, v21, s86
	global_store_short_d16_hi v[18:19], v20, off offset:1024
	v_mul_f32_e32 v20, v25, v3
	v_mul_f32_e32 v20, v20, v77
	v_bfe_u32 v21, v20, 16, 1
	v_add3_u32 v20, v20, v21, s86
	global_store_short_d16_hi v[18:19], v20, off offset:1088
	v_mul_f32_e32 v20, v24, v3
	v_mul_f32_e32 v20, v20, v78
	v_bfe_u32 v21, v20, 16, 1
	v_mul_f32_e32 v3, v23, v3
	v_add3_u32 v20, v20, v21, s86
	v_mul_f32_e32 v3, v3, v79
	global_store_short_d16_hi v[18:19], v20, off offset:1152
	v_bfe_u32 v20, v3, 16, 1
	v_add3_u32 v3, v3, v20, s86
	global_store_short_d16_hi v[18:19], v3, off offset:1216
	v_fmamk_f32 v3, v63, 0x3c000000, v244
	v_rsq_f32_e32 v3, v3
	v_add_u32_e32 v18, 19, v2
	v_ashrrev_i32_e32 v19, 31, v18
	v_lshlrev_b64 v[18:19], 11, v[18:19]
	v_mul_f32_e32 v13, v13, v3
	v_mul_f32_e32 v12, v12, v3
	v_mul_f32_e32 v11, v11, v3
	v_mul_f32_e32 v3, v10, v3
	v_lshl_add_u64 v[18:19], s[2:3], 0, v[18:19]
	v_mul_f32_e32 v13, v13, v76
	v_mul_f32_e32 v3, v3, v79
	v_lshl_add_u64 v[18:19], v[18:19], 0, s[36:37]
	v_bfe_u32 v20, v13, 16, 1
	v_bfe_u32 v10, v3, 16, 1
	v_lshl_add_u64 v[18:19], v[18:19], 0, v[0:1]
	v_add3_u32 v13, v13, v20, s86
	v_mul_f32_e32 v12, v12, v77
	v_add3_u32 v3, v3, v10, s86
	global_store_short_d16_hi v[18:19], v13, off offset:1024
	v_bfe_u32 v13, v12, 16, 1
	global_store_short_d16_hi v[18:19], v3, off offset:1216
	v_fmamk_f32 v3, v61, 0x3c000000, v244
	v_add3_u32 v12, v12, v13, s86
	v_mul_f32_e32 v11, v11, v78
	v_rsq_f32_e32 v3, v3
	global_store_short_d16_hi v[18:19], v12, off offset:1088
	v_bfe_u32 v12, v11, 16, 1
	v_add3_u32 v11, v11, v12, s86
	v_add_u32_e32 v10, 24, v2
	global_store_short_d16_hi v[18:19], v11, off offset:1152
	v_ashrrev_i32_e32 v11, 31, v10
	v_lshlrev_b64 v[10:11], 11, v[10:11]
	v_mul_f32_e32 v12, v29, v3
	v_lshl_add_u64 v[10:11], s[2:3], 0, v[10:11]
	v_mul_f32_e32 v12, v12, v76
	v_lshl_add_u64 v[10:11], v[10:11], 0, s[36:37]
	v_bfe_u32 v13, v12, 16, 1
	v_lshl_add_u64 v[10:11], v[10:11], 0, v[0:1]
	v_add3_u32 v12, v12, v13, s86
	global_store_short_d16_hi v[10:11], v12, off offset:1024
	v_mul_f32_e32 v12, v14, v3
	v_mul_f32_e32 v12, v12, v77
	v_bfe_u32 v13, v12, 16, 1
	v_add3_u32 v12, v12, v13, s86
	global_store_short_d16_hi v[10:11], v12, off offset:1088
	v_mul_f32_e32 v12, v28, v3
	v_mul_f32_e32 v3, v6, v3
	v_mul_f32_e32 v3, v3, v79
	v_bfe_u32 v6, v3, 16, 1
	v_add3_u32 v3, v3, v6, s86
	v_mul_f32_e32 v12, v12, v78
	global_store_short_d16_hi v[10:11], v3, off offset:1216
	v_fmamk_f32 v3, v59, 0x3c000000, v244
	v_bfe_u32 v13, v12, 16, 1
	v_rsq_f32_e32 v3, v3
	v_add3_u32 v12, v12, v13, s86
	global_store_short_d16_hi v[10:11], v12, off offset:1152
	v_add_u32_e32 v10, 25, v2
	v_ashrrev_i32_e32 v11, 31, v10
	v_lshlrev_b64 v[10:11], 11, v[10:11]
	v_mul_f32_e32 v6, v43, v3
	v_lshl_add_u64 v[10:11], s[2:3], 0, v[10:11]
	v_mul_f32_e32 v6, v6, v76
	v_lshl_add_u64 v[10:11], v[10:11], 0, s[36:37]
	v_bfe_u32 v12, v6, 16, 1
	v_lshl_add_u64 v[10:11], v[10:11], 0, v[0:1]
	v_add3_u32 v6, v6, v12, s86
	global_store_short_d16_hi v[10:11], v6, off offset:1024
	v_mul_f32_e32 v6, v15, v3
	v_mul_f32_e32 v6, v6, v77
	v_bfe_u32 v12, v6, 16, 1
	v_add3_u32 v6, v6, v12, s86
	global_store_short_d16_hi v[10:11], v6, off offset:1088
	v_mul_f32_e32 v6, v30, v3
	v_mul_f32_e32 v6, v6, v78
	v_bfe_u32 v12, v6, 16, 1
	v_mul_f32_e32 v3, v7, v3
	v_add3_u32 v6, v6, v12, s86
	v_mul_f32_e32 v3, v3, v79
	global_store_short_d16_hi v[10:11], v6, off offset:1152
	v_bfe_u32 v6, v3, 16, 1
	v_add3_u32 v3, v3, v6, s86
	global_store_short_d16_hi v[10:11], v3, off offset:1216
	v_fmamk_f32 v3, v49, 0x3c000000, v244
	v_rsq_f32_e32 v3, v3
	v_add_u32_e32 v6, 26, v2
	v_ashrrev_i32_e32 v7, 31, v6
	v_lshlrev_b64 v[6:7], 11, v[6:7]
	v_mul_f32_e32 v10, v31, v3
	v_lshl_add_u64 v[6:7], s[2:3], 0, v[6:7]
	v_mul_f32_e32 v10, v10, v76
	v_lshl_add_u64 v[6:7], v[6:7], 0, s[36:37]
	v_bfe_u32 v11, v10, 16, 1
	v_mul_f32_e32 v8, v8, v3
	v_lshl_add_u64 v[6:7], v[6:7], 0, v[0:1]
	v_add3_u32 v10, v10, v11, s86
	v_mul_f32_e32 v8, v8, v77
	global_store_short_d16_hi v[6:7], v10, off offset:1024
	v_bfe_u32 v10, v8, 16, 1
	v_add3_u32 v8, v8, v10, s86
	global_store_short_d16_hi v[6:7], v8, off offset:1088
	v_mul_f32_e32 v8, v16, v3
	v_mul_f32_e32 v3, v4, v3
	v_mul_f32_e32 v3, v3, v79
	v_bfe_u32 v4, v3, 16, 1
	v_add3_u32 v3, v3, v4, s86
	global_store_short_d16_hi v[6:7], v3, off offset:1216
	v_fmamk_f32 v3, v44, 0x3c000000, v244
	v_add_u32_e32 v2, 27, v2
	v_rsq_f32_e32 v4, v3
	v_ashrrev_i32_e32 v3, 31, v2
	v_lshlrev_b64 v[2:3], 11, v[2:3]
	v_lshl_add_u64 v[2:3], s[2:3], 0, v[2:3]
	v_mul_f32_e32 v8, v8, v78
	v_lshl_add_u64 v[2:3], v[2:3], 0, s[36:37]
	v_bfe_u32 v10, v8, 16, 1
	v_lshl_add_u64 v[2:3], v[2:3], 0, v[0:1]
	v_mul_f32_e32 v0, v32, v4
	v_add3_u32 v8, v8, v10, s86
	v_mul_f32_e32 v0, v76, v0
	global_store_short_d16_hi v[6:7], v8, off offset:1152
	v_bfe_u32 v6, v0, 16, 1
	v_add3_u32 v0, v0, v6, s86
	global_store_short_d16_hi v[2:3], v0, off offset:1024
	v_mul_f32_e32 v0, v17, v4
	v_mul_f32_e32 v0, v77, v0
	v_bfe_u32 v6, v0, 16, 1
	v_add3_u32 v0, v0, v6, s86
	global_store_short_d16_hi v[2:3], v0, off offset:1088
	v_mul_f32_e32 v0, v9, v4
	v_mul_f32_e32 v0, v78, v0
	v_bfe_u32 v6, v0, 16, 1
	v_add3_u32 v0, v0, v6, s86
	global_store_short_d16_hi v[2:3], v0, off offset:1152
	v_mul_f32_e32 v0, v5, v4
	v_mul_f32_e32 v0, v79, v0
	v_bfe_u32 v4, v0, 16, 1
	v_add3_u32 v0, v0, v4, s86
	global_store_short_d16_hi v[2:3], v0, off offset:1216
	s_waitcnt lgkmcnt(0)
	s_barrier

.LBB0_779:
	v_mbcnt_lo_u32_b32 v0, -1, 0
	v_mbcnt_hi_u32_b32 v0, -1, v0
	s_nop 0
	v_cmp_gt_u32_e32 vcc, 32, v0
	s_and_saveexec_b64 s[4:5], vcc
	v_lshl_add_u32 v130, v0, 2, s14
	ds_write2_b32 v130, v204, v205 offset0:64 offset1:96
	s_or_b64 exec, exec, s[4:5]
	v_ashrrev_i32_e32 v134, 5, v0
	s_waitcnt lgkmcnt(0)
	v_lshl_add_u32 v139, v134, 4, s14
	ds_read_b128 v[140:143], v139 offset:256
	ds_read_b128 v[130:133], v139 offset:288
	ds_read_b128 v[144:147], v139 offset:384
	v_readlane_b32 s2, v255, 35
	v_and_b32_e32 v0, 31, v0
	s_waitcnt lgkmcnt(2)
	v_rcp_f32_e32 v140, v140
	s_waitcnt lgkmcnt(0)
	v_rcp_f32_e32 v135, v144
	s_nop 0
	v_mul_f32_e32 v144, s2, v135
	v_mul_f32_e32 v2, v2, v144
	v_fma_f32 v137, v114, v140, -v2
	v_mul_f32_e32 v2, v66, v144
	v_fma_f32 v136, v98, v140, -v2
	v_mul_f32_e32 v2, v34, v144
	v_fma_f32 v135, v82, v140, -v2
	v_mul_f32_e32 v2, v18, v144
	v_rcp_f32_e32 v18, v145
	v_fma_f32 v114, v50, v140, -v2
	v_rcp_f32_e32 v2, v141
	v_mul_f32_e32 v138, v136, v136
	v_mul_f32_e32 v18, s2, v18
	v_mul_f32_e32 v3, v3, v18
	v_fma_f32 v98, v115, v2, -v3
	v_mul_f32_e32 v3, v67, v18
	v_fma_f32 v82, v99, v2, -v3
	v_mul_f32_e32 v3, v35, v18
	v_fma_f32 v67, v83, v2, -v3
	v_mul_f32_e32 v3, v19, v18
	v_fma_f32 v66, v51, v2, -v3
	v_rcp_f32_e32 v3, v146
	v_rcp_f32_e32 v2, v142
	v_fmac_f32_e32 v138, v137, v137
	v_fmac_f32_e32 v138, v135, v135
	v_mul_f32_e32 v3, s2, v3
	v_mul_f32_e32 v4, v4, v3
	v_fma_f32 v51, v116, v2, -v4
	v_mul_f32_e32 v4, v68, v3
	v_fma_f32 v50, v100, v2, -v4
	v_mul_f32_e32 v4, v36, v3
	v_mul_f32_e32 v3, v20, v3
	v_fma_f32 v35, v52, v2, -v3
	v_rcp_f32_e32 v3, v147
	v_fma_f32 v36, v84, v2, -v4
	v_rcp_f32_e32 v2, v143
	v_fmac_f32_e32 v138, v114, v114
	v_mul_f32_e32 v3, s2, v3
	v_mul_f32_e32 v4, v5, v3
	v_fma_f32 v34, v117, v2, -v4
	v_mul_f32_e32 v4, v69, v3
	v_fma_f32 v20, v101, v2, -v4
	v_mul_f32_e32 v4, v37, v3
	v_mul_f32_e32 v3, v21, v3
	v_fma_f32 v19, v85, v2, -v4
	v_fma_f32 v18, v53, v2, -v3
	ds_read_b128 v[2:5], v139 offset:416
	v_rcp_f32_e32 v21, v130
	v_mul_f32_e32 v115, v82, v82
	v_fmac_f32_e32 v115, v98, v98
	v_fmac_f32_e32 v115, v67, v67
	s_waitcnt lgkmcnt(0)
	v_rcp_f32_e32 v2, v2
	v_rcp_f32_e32 v3, v3
	v_fmac_f32_e32 v115, v66, v66
	v_mul_f32_e32 v100, v50, v50
	v_mul_f32_e32 v2, s2, v2
	v_mul_f32_e32 v6, v6, v2
	v_fma_f32 v68, v118, v21, -v6
	v_mul_f32_e32 v6, v70, v2
	v_fma_f32 v52, v102, v21, -v6
	v_mul_f32_e32 v6, v38, v2
	v_mul_f32_e32 v2, v22, v2
	v_fma_f32 v37, v54, v21, -v2
	v_rcp_f32_e32 v2, v131
	v_mul_f32_e32 v3, s2, v3
	v_fma_f32 v53, v86, v21, -v6
	v_mul_f32_e32 v6, v7, v3
	v_fma_f32 v83, v119, v2, -v6
	v_mul_f32_e32 v6, v71, v3
	v_fma_f32 v69, v103, v2, -v6
	v_mul_f32_e32 v6, v39, v3
	v_mul_f32_e32 v3, v23, v3
	v_fma_f32 v54, v55, v2, -v3
	v_rcp_f32_e32 v3, v4
	v_fma_f32 v70, v87, v2, -v6
	v_rcp_f32_e32 v2, v132
	v_fmac_f32_e32 v100, v51, v51
	v_mul_f32_e32 v3, s2, v3
	v_mul_f32_e32 v4, v8, v3
	v_fma_f32 v84, v120, v2, -v4
	v_mul_f32_e32 v4, v72, v3
	v_fma_f32 v55, v104, v2, -v4
	v_mul_f32_e32 v4, v40, v3
	v_mul_f32_e32 v3, v24, v3
	v_fma_f32 v40, v56, v2, -v3
	v_rcp_f32_e32 v3, v5
	v_fma_f32 v71, v88, v2, -v4
	v_rcp_f32_e32 v2, v133
	v_fmac_f32_e32 v100, v36, v36
	v_mul_f32_e32 v3, s2, v3
	v_mul_f32_e32 v4, v9, v3
	v_fma_f32 v85, v121, v2, -v4
	v_mul_f32_e32 v4, v73, v3
	v_fma_f32 v56, v105, v2, -v4
	v_mul_f32_e32 v4, v41, v3
	v_mul_f32_e32 v3, v25, v3
	v_fma_f32 v72, v89, v2, -v4
	v_fma_f32 v41, v57, v2, -v3
	ds_read_b128 v[2:5], v139 offset:320
	ds_read_b128 v[6:9], v139 offset:448
	v_fmac_f32_e32 v100, v35, v35
	v_mul_f32_e32 v99, v20, v20
	v_fmac_f32_e32 v99, v34, v34
	s_waitcnt lgkmcnt(1)
	v_rcp_f32_e32 v2, v2
	s_waitcnt lgkmcnt(0)
	v_rcp_f32_e32 v6, v6
	v_fmac_f32_e32 v99, v19, v19
	v_fmac_f32_e32 v99, v18, v18
	v_mul_f32_e32 v116, v52, v52
	v_mul_f32_e32 v6, s2, v6
	v_mul_f32_e32 v10, v10, v6
	v_fma_f32 v86, v122, v2, -v10
	v_mul_f32_e32 v10, v74, v6
	v_fma_f32 v73, v106, v2, -v10
	v_mul_f32_e32 v10, v42, v6
	v_mul_f32_e32 v6, v26, v6
	v_fma_f32 v57, v90, v2, -v10
	v_fma_f32 v42, v58, v2, -v6
	v_rcp_f32_e32 v2, v3
	v_rcp_f32_e32 v3, v7
	v_fmac_f32_e32 v116, v68, v68
	v_fmac_f32_e32 v116, v53, v53
	v_fmac_f32_e32 v116, v37, v37
	v_mul_f32_e32 v3, s2, v3
	v_mul_f32_e32 v6, v11, v3
	v_fma_f32 v39, v123, v2, -v6
	v_mul_f32_e32 v6, v75, v3
	v_fma_f32 v38, v107, v2, -v6
	v_mul_f32_e32 v6, v43, v3
	v_mul_f32_e32 v3, v27, v3
	v_fma_f32 v25, v59, v2, -v3
	v_rcp_f32_e32 v3, v8
	v_fma_f32 v26, v91, v2, -v6
	v_rcp_f32_e32 v2, v4
	v_mul_f32_e32 v102, v69, v69
	v_mul_f32_e32 v3, s2, v3
	v_mul_f32_e32 v4, v12, v3
	v_fma_f32 v24, v124, v2, -v4
	v_mul_f32_e32 v4, v76, v3
	v_fma_f32 v23, v108, v2, -v4
	v_mul_f32_e32 v4, v44, v3
	v_mul_f32_e32 v3, v28, v3
	v_fma_f32 v21, v60, v2, -v3
	v_rcp_f32_e32 v3, v9
	v_fma_f32 v22, v92, v2, -v4
	v_rcp_f32_e32 v2, v5
	ds_read_b128 v[6:9], v139 offset:480
	v_mul_f32_e32 v3, s2, v3
	v_mul_f32_e32 v4, v13, v3
	v_fma_f32 v13, v125, v2, -v4
	v_mul_f32_e32 v4, v77, v3
	v_fma_f32 v12, v109, v2, -v4
	v_mul_f32_e32 v4, v45, v3
	v_mul_f32_e32 v3, v29, v3
	v_fma_f32 v11, v93, v2, -v4
	v_fma_f32 v10, v61, v2, -v3
	ds_read_b128 v[2:5], v139 offset:352
	s_waitcnt lgkmcnt(1)
	v_rcp_f32_e32 v6, v6
	v_fmac_f32_e32 v102, v83, v83
	v_fmac_f32_e32 v102, v70, v70
	v_fmac_f32_e32 v102, v54, v54
	s_waitcnt lgkmcnt(0)
	v_rcp_f32_e32 v2, v2
	v_mul_f32_e32 v6, s2, v6
	v_mul_f32_e32 v14, v14, v6
	v_mul_f32_e32 v27, v46, v6
	v_fma_f32 v28, v126, v2, -v14
	v_mul_f32_e32 v14, v78, v6
	v_mul_f32_e32 v6, v30, v6
	v_fma_f32 v14, v110, v2, -v14
	v_fma_f32 v27, v94, v2, -v27
	v_fma_f32 v6, v62, v2, -v6
	v_rcp_f32_e32 v2, v3
	v_rcp_f32_e32 v3, v7
	v_mul_f32_e32 v101, v55, v55
	v_fmac_f32_e32 v101, v84, v84
	v_fmac_f32_e32 v101, v71, v71
	v_mul_f32_e32 v7, s2, v3
	v_mul_f32_e32 v3, v15, v7
	v_fma_f32 v30, v127, v2, -v3
	v_mul_f32_e32 v3, v79, v7
	v_mul_f32_e32 v29, v47, v7
	v_mul_f32_e32 v7, v31, v7
	v_fma_f32 v15, v111, v2, -v3
	v_fma_f32 v29, v95, v2, -v29
	v_fma_f32 v7, v63, v2, -v7
	v_rcp_f32_e32 v2, v4
	v_rcp_f32_e32 v4, v8
	v_fmac_f32_e32 v101, v40, v40
	v_mul_f32_e32 v87, v56, v56
	v_fmac_f32_e32 v87, v85, v85
	v_mul_f32_e32 v4, s2, v4
	v_mul_f32_e32 v8, v16, v4
	v_fma_f32 v31, v128, v2, -v8
	v_mul_f32_e32 v8, v80, v4
	v_mul_f32_e32 v16, v48, v4
	v_mul_f32_e32 v4, v32, v4
	v_fma_f32 v8, v112, v2, -v8
	v_fma_f32 v16, v96, v2, -v16
	v_fma_f32 v4, v64, v2, -v4
	v_rcp_f32_e32 v2, v5
	v_rcp_f32_e32 v5, v9
	v_fmac_f32_e32 v87, v72, v72
	v_fmac_f32_e32 v87, v41, v41
	v_mul_f32_e32 v74, v73, v73
	v_mul_f32_e32 v5, s2, v5
	v_mul_f32_e32 v9, v17, v5
	v_fma_f32 v32, v129, v2, -v9
	v_mul_f32_e32 v9, v81, v5
	v_fma_f32 v17, v113, v2, -v9
	v_mul_f32_e32 v9, v49, v5
	v_mul_f32_e32 v5, v33, v5
	v_fma_f32 v9, v97, v2, -v9
	v_fma_f32 v5, v65, v2, -v5
	v_fmac_f32_e32 v74, v86, v86
	v_fmac_f32_e32 v74, v57, v57
	v_fmac_f32_e32 v74, v42, v42
	v_mul_f32_e32 v58, v38, v38
	s_nop 1
	v_add_f32_dpp v2, v138, v138 quad_perm:[1,0,3,2] row_mask:0xf bank_mask:0xf
	v_fmac_f32_e32 v58, v39, v39
	v_fmac_f32_e32 v58, v26, v26
	v_fmac_f32_e32 v58, v25, v25
	v_mul_f32_e32 v43, v23, v23
	s_nop 1
	v_add_f32_dpp v2, v2, v2 quad_perm:[2,3,0,1] row_mask:0xf bank_mask:0xf
	v_fmac_f32_e32 v43, v24, v24
	v_fmac_f32_e32 v43, v22, v22
	v_fmac_f32_e32 v43, v21, v21
	v_mul_f32_e32 v44, v12, v12
	s_nop 1
	v_add_f32_dpp v2, v2, v2 row_half_mirror row_mask:0xf bank_mask:0xf
	v_fmac_f32_e32 v44, v13, v13
	v_fmac_f32_e32 v44, v11, v11
	v_fmac_f32_e32 v44, v10, v10
	v_mul_f32_e32 v75, v14, v14
	s_nop 1
	v_add_f32_dpp v2, v2, v2 row_mirror row_mask:0xf bank_mask:0xf
	v_mov_b32_e32 v33, v2
	v_fmac_f32_e32 v75, v28, v28
	v_fmac_f32_e32 v75, v27, v27
	v_fmac_f32_e32 v75, v6, v6
	v_mul_f32_e32 v3, v15, v15
	s_nop 1
	v_permlane16_swap_b32_e32 v2, v33
	v_add_f32_e32 v2, v2, v33
	v_fmac_f32_e32 v3, v30, v30
	v_fmac_f32_e32 v3, v29, v29
	v_fmac_f32_e32 v3, v7, v7
	v_mul_f32_e32 v76, v8, v8
	s_nop 1
	v_add_f32_dpp v33, v115, v115 quad_perm:[1,0,3,2] row_mask:0xf bank_mask:0xf
	v_fmac_f32_e32 v76, v31, v31
	v_fmac_f32_e32 v76, v16, v16
	v_fmac_f32_e32 v76, v4, v4
	s_mov_b32 s2, s37
	s_nop 1
	v_add_f32_dpp v33, v33, v33 quad_perm:[2,3,0,1] row_mask:0xf bank_mask:0xf
	s_cmp_eq_u32 s2, 0
	v_readlane_b32 s2, v255, 26
	v_readlane_b32 s3, v255, 27
	s_nop 1
	v_add_f32_dpp v33, v33, v33 row_half_mirror row_mask:0xf bank_mask:0xf
	v_mul_f32_e32 v77, v17, v17
	v_fmac_f32_e32 v77, v32, v32
	v_fmac_f32_e32 v77, v9, v9
	v_fmac_f32_e32 v77, v5, v5
	s_nop 1
	v_add_f32_dpp v33, v33, v33 row_mirror row_mask:0xf bank_mask:0xf
	v_mov_b32_e32 v45, v33
	v_fmamk_f32 v2, v2, 0x3c000000, v244
	s_cselect_b64 vcc, -1, 0
	v_lshl_add_u32 v78, v134, 2, s0
	v_ashrrev_i32_e32 v79, 31, v78
	s_nop 1
	v_permlane16_swap_b32_e32 v33, v45
	v_add_f32_e32 v33, v33, v45
	s_lshl_b32 s36, s1, 1
	v_fmamk_f32 v33, v33, 0x3c000000, v244
	v_rsq_f32_e32 v33, v33
	s_mov_b64 s[0:1], 0x4000
	s_nop 1
	v_add_f32_dpp v45, v100, v100 quad_perm:[1,0,3,2] row_mask:0xf bank_mask:0xf
	v_mul_f32_e32 v67, v67, v33
	s_nop 1
	v_add_f32_dpp v45, v45, v45 quad_perm:[2,3,0,1] row_mask:0xf bank_mask:0xf
	s_nop 1
	v_add_f32_dpp v45, v45, v45 row_half_mirror row_mask:0xf bank_mask:0xf
	s_nop 1
	v_add_f32_dpp v45, v45, v45 row_mirror row_mask:0xf bank_mask:0xf
	v_mov_b32_e32 v46, v45
	s_nop 1
	v_permlane16_swap_b32_e32 v45, v46
	v_add_f32_e32 v45, v45, v46
	s_nop 1
	v_add_f32_dpp v46, v99, v99 quad_perm:[1,0,3,2] row_mask:0xf bank_mask:0xf
	s_nop 1
	v_add_f32_dpp v46, v46, v46 quad_perm:[2,3,0,1] row_mask:0xf bank_mask:0xf
	s_nop 1
	v_add_f32_dpp v46, v46, v46 row_half_mirror row_mask:0xf bank_mask:0xf
	s_nop 1
	v_add_f32_dpp v46, v46, v46 row_mirror row_mask:0xf bank_mask:0xf
	v_mov_b32_e32 v47, v46
	s_nop 1
	v_permlane16_swap_b32_e32 v46, v47
	v_add_f32_e32 v46, v46, v47
	s_nop 1
	v_add_f32_dpp v47, v116, v116 quad_perm:[1,0,3,2] row_mask:0xf bank_mask:0xf
	s_nop 1
	v_add_f32_dpp v47, v47, v47 quad_perm:[2,3,0,1] row_mask:0xf bank_mask:0xf
	s_nop 1
	v_add_f32_dpp v47, v47, v47 row_half_mirror row_mask:0xf bank_mask:0xf
	s_nop 1
	v_add_f32_dpp v47, v47, v47 row_mirror row_mask:0xf bank_mask:0xf
	v_mov_b32_e32 v48, v47
	s_nop 1
	v_permlane16_swap_b32_e32 v47, v48
	v_add_f32_e32 v47, v47, v48
	s_nop 1
	v_add_f32_dpp v48, v102, v102 quad_perm:[1,0,3,2] row_mask:0xf bank_mask:0xf
	s_nop 1
	v_add_f32_dpp v48, v48, v48 quad_perm:[2,3,0,1] row_mask:0xf bank_mask:0xf
	s_nop 1
	v_add_f32_dpp v48, v48, v48 row_half_mirror row_mask:0xf bank_mask:0xf
	s_nop 1
	v_add_f32_dpp v48, v48, v48 row_mirror row_mask:0xf bank_mask:0xf
	ds_swizzle_b32 v49, v48 offset:swizzle(SWAP,16)
	s_waitcnt lgkmcnt(0)
	v_add_f32_e32 v49, v48, v49
	s_nop 1
	v_add_f32_dpp v48, v101, v101 quad_perm:[1,0,3,2] row_mask:0xf bank_mask:0xf
	s_nop 1
	v_add_f32_dpp v48, v48, v48 quad_perm:[2,3,0,1] row_mask:0xf bank_mask:0xf
	s_nop 1
	v_add_f32_dpp v48, v48, v48 row_half_mirror row_mask:0xf bank_mask:0xf
	s_nop 1
	v_add_f32_dpp v48, v48, v48 row_mirror row_mask:0xf bank_mask:0xf
	ds_swizzle_b32 v59, v48 offset:swizzle(SWAP,16)
	s_waitcnt lgkmcnt(0)
	v_add_f32_e32 v59, v48, v59
	s_nop 1
	v_add_f32_dpp v48, v87, v87 quad_perm:[1,0,3,2] row_mask:0xf bank_mask:0xf
	s_nop 1
	v_add_f32_dpp v48, v48, v48 quad_perm:[2,3,0,1] row_mask:0xf bank_mask:0xf
	s_nop 1
	v_add_f32_dpp v48, v48, v48 row_half_mirror row_mask:0xf bank_mask:0xf
	s_nop 1
	v_add_f32_dpp v48, v48, v48 row_mirror row_mask:0xf bank_mask:0xf
	ds_swizzle_b32 v60, v48 offset:swizzle(SWAP,16)
	s_waitcnt lgkmcnt(0)
	v_add_f32_e32 v61, v48, v60
	s_nop 1
	v_add_f32_dpp v48, v74, v74 quad_perm:[1,0,3,2] row_mask:0xf bank_mask:0xf
	s_nop 1
	v_add_f32_dpp v48, v48, v48 quad_perm:[2,3,0,1] row_mask:0xf bank_mask:0xf
	s_nop 1
	v_add_f32_dpp v48, v48, v48 row_half_mirror row_mask:0xf bank_mask:0xf
	s_nop 1
	v_add_f32_dpp v48, v48, v48 row_mirror row_mask:0xf bank_mask:0xf
	ds_swizzle_b32 v60, v48 offset:swizzle(SWAP,16)
	s_waitcnt lgkmcnt(0)
	v_add_f32_e32 v63, v48, v60
	s_nop 1
	v_add_f32_dpp v48, v58, v58 quad_perm:[1,0,3,2] row_mask:0xf bank_mask:0xf
	s_nop 1
	v_add_f32_dpp v48, v48, v48 quad_perm:[2,3,0,1] row_mask:0xf bank_mask:0xf
	s_nop 1
	v_add_f32_dpp v48, v48, v48 row_half_mirror row_mask:0xf bank_mask:0xf
	s_nop 1
	v_add_f32_dpp v48, v48, v48 row_mirror row_mask:0xf bank_mask:0xf
	ds_swizzle_b32 v58, v48 offset:swizzle(SWAP,16)
	s_waitcnt lgkmcnt(0)
	v_add_f32_e32 v64, v48, v58
	s_nop 1
	v_add_f32_dpp v43, v43, v43 quad_perm:[1,0,3,2] row_mask:0xf bank_mask:0xf
	s_nop 1
	v_add_f32_dpp v43, v43, v43 quad_perm:[2,3,0,1] row_mask:0xf bank_mask:0xf
	s_nop 1
	v_add_f32_dpp v43, v43, v43 row_half_mirror row_mask:0xf bank_mask:0xf
	s_nop 1
	v_add_f32_dpp v43, v43, v43 row_mirror row_mask:0xf bank_mask:0xf
	ds_swizzle_b32 v48, v43 offset:swizzle(SWAP,16)
	s_waitcnt lgkmcnt(0)
	v_add_f32_e32 v62, v43, v48
	s_nop 1
	v_add_f32_dpp v43, v44, v44 quad_perm:[1,0,3,2] row_mask:0xf bank_mask:0xf
	s_nop 1
	v_add_f32_dpp v43, v43, v43 quad_perm:[2,3,0,1] row_mask:0xf bank_mask:0xf
	s_nop 1
	v_add_f32_dpp v43, v43, v43 row_half_mirror row_mask:0xf bank_mask:0xf
	s_nop 1
	v_add_f32_dpp v43, v43, v43 row_mirror row_mask:0xf bank_mask:0xf
	ds_swizzle_b32 v44, v43 offset:swizzle(SWAP,16)
	s_waitcnt lgkmcnt(0)
	v_add_f32_e32 v60, v43, v44
	s_nop 1
	v_add_f32_dpp v43, v75, v75 quad_perm:[1,0,3,2] row_mask:0xf bank_mask:0xf
	s_nop 1
	v_add_f32_dpp v43, v43, v43 quad_perm:[2,3,0,1] row_mask:0xf bank_mask:0xf
	s_nop 1
	v_add_f32_dpp v43, v43, v43 row_half_mirror row_mask:0xf bank_mask:0xf
	s_nop 1
	v_add_f32_dpp v43, v43, v43 row_mirror row_mask:0xf bank_mask:0xf
	ds_swizzle_b32 v44, v43 offset:swizzle(SWAP,16)
	s_waitcnt lgkmcnt(0)
	v_add_f32_e32 v58, v43, v44
	s_nop 1
	v_add_f32_dpp v3, v3, v3 quad_perm:[1,0,3,2] row_mask:0xf bank_mask:0xf
	s_nop 1
	v_add_f32_dpp v3, v3, v3 quad_perm:[2,3,0,1] row_mask:0xf bank_mask:0xf
	s_nop 1
	v_add_f32_dpp v3, v3, v3 row_half_mirror row_mask:0xf bank_mask:0xf
	s_nop 1
	v_add_f32_dpp v3, v3, v3 row_mirror row_mask:0xf bank_mask:0xf
	ds_swizzle_b32 v43, v3 offset:swizzle(SWAP,16)
	s_waitcnt lgkmcnt(0)
	v_add_f32_e32 v48, v3, v43
	s_nop 1
	v_add_f32_dpp v3, v76, v76 quad_perm:[1,0,3,2] row_mask:0xf bank_mask:0xf
	v_lshlrev_b32_e32 v76, 2, v0
	global_load_dword v65, v76, s[2:3]
	global_load_dword v74, v76, s[2:3] offset:128
	global_load_dword v75, v76, s[2:3] offset:256
	global_load_dword v76, v76, s[2:3] offset:384
	v_readlane_b32 s2, v254, 63
	v_readlane_b32 s3, v255, 0
	v_lshlrev_b32_e32 v0, 1, v0
	s_nop 1
	v_add_f32_dpp v3, v3, v3 quad_perm:[2,3,0,1] row_mask:0xf bank_mask:0xf
	s_nop 1
	v_add_f32_dpp v3, v3, v3 row_half_mirror row_mask:0xf bank_mask:0xf
	s_nop 1
	v_add_f32_dpp v3, v3, v3 row_mirror row_mask:0xf bank_mask:0xf
	ds_swizzle_b32 v43, v3 offset:swizzle(SWAP,16)
	s_waitcnt lgkmcnt(0)
	v_add_f32_e32 v44, v3, v43
	s_nop 1
	v_add_f32_dpp v3, v77, v77 quad_perm:[1,0,3,2] row_mask:0xf bank_mask:0xf
	v_rsq_f32_e32 v77, v2
	s_nop 1
	v_add_f32_dpp v3, v3, v3 quad_perm:[2,3,0,1] row_mask:0xf bank_mask:0xf
	s_nop 1
	v_add_f32_dpp v3, v3, v3 row_half_mirror row_mask:0xf bank_mask:0xf
	s_nop 1
	v_add_f32_dpp v3, v3, v3 row_mirror row_mask:0xf bank_mask:0xf
	ds_swizzle_b32 v43, v3 offset:swizzle(SWAP,16)
	s_waitcnt lgkmcnt(0)
	v_add_f32_e32 v43, v3, v43
	v_cndmask_b32_e32 v3, v252, v246, vcc
	s_waitcnt vmcnt(3)
	v_mul_f32_e32 v65, v65, v3
	s_waitcnt vmcnt(2)
	v_mul_f32_e32 v74, v3, v74
	s_waitcnt vmcnt(1)
	v_mul_f32_e32 v75, v3, v75
	v_mul_f32_e32 v67, v67, v75
	s_waitcnt vmcnt(0)
	v_mul_f32_e32 v76, v3, v76
	v_lshlrev_b64 v[2:3], 11, v[78:79]
	v_mul_f32_e32 v79, v137, v77
	v_lshl_add_u64 v[2:3], s[2:3], 0, v[2:3]
	v_mul_f32_e32 v79, v79, v65
	v_lshl_add_u64 v[2:3], v[2:3], 0, s[36:37]
	v_bfe_u32 v80, v79, 16, 1
	v_lshl_add_u64 v[2:3], v[2:3], 0, v[0:1]
	v_add3_u32 v79, v79, v80, s86
	global_store_short_d16_hi v[2:3], v79, off offset:1024
	v_mul_f32_e32 v79, v136, v77
	v_mul_f32_e32 v79, v79, v74
	v_bfe_u32 v80, v79, 16, 1
	v_add3_u32 v79, v79, v80, s86
	global_store_short_d16_hi v[2:3], v79, off offset:1088
	v_mul_f32_e32 v79, v135, v77
	v_mul_f32_e32 v79, v79, v75
	v_bfe_u32 v80, v79, 16, 1
	v_mul_f32_e32 v77, v114, v77
	v_add3_u32 v79, v79, v80, s86
	v_mul_f32_e32 v77, v77, v76
	global_store_short_d16_hi v[2:3], v79, off offset:1152
	v_bfe_u32 v79, v77, 16, 1
	v_or_b32_e32 v80, 1, v78
	v_add3_u32 v77, v77, v79, s86
	v_ashrrev_i32_e32 v81, 31, v80
	global_store_short_d16_hi v[2:3], v77, off offset:1216
	v_lshlrev_b64 v[80:81], 11, v[80:81]
	v_mul_f32_e32 v77, v98, v33
	v_lshl_add_u64 v[80:81], s[2:3], 0, v[80:81]
	v_mul_f32_e32 v77, v77, v65
	v_lshl_add_u64 v[80:81], v[80:81], 0, s[36:37]
	v_bfe_u32 v79, v77, 16, 1
	v_lshl_add_u64 v[80:81], v[80:81], 0, v[0:1]
	v_add3_u32 v77, v77, v79, s86
	global_store_short_d16_hi v[80:81], v77, off offset:1024
	v_mul_f32_e32 v77, v82, v33
	v_mul_f32_e32 v33, v66, v33
	v_mul_f32_e32 v33, v33, v76
	v_bfe_u32 v66, v33, 16, 1
	v_mul_f32_e32 v77, v77, v74
	v_add3_u32 v33, v33, v66, s86
	v_bfe_u32 v79, v77, 16, 1
	global_store_short_d16_hi v[80:81], v33, off offset:1216
	v_fmamk_f32 v33, v45, 0x3c000000, v244
	v_add3_u32 v77, v77, v79, s86
	v_rsq_f32_e32 v33, v33
	global_store_short_d16_hi v[80:81], v77, off offset:1088
	v_bfe_u32 v77, v67, 16, 1
	v_add3_u32 v67, v67, v77, s86
	v_or_b32_e32 v66, 2, v78
	global_store_short_d16_hi v[80:81], v67, off offset:1152
	v_ashrrev_i32_e32 v67, 31, v66
	v_lshlrev_b64 v[66:67], 11, v[66:67]
	v_mul_f32_e32 v45, v51, v33
	v_lshl_add_u64 v[66:67], s[2:3], 0, v[66:67]
	v_mul_f32_e32 v45, v45, v65
	v_lshl_add_u64 v[66:67], v[66:67], 0, s[36:37]
	v_bfe_u32 v51, v45, 16, 1
	v_lshl_add_u64 v[66:67], v[66:67], 0, v[0:1]
	v_add3_u32 v45, v45, v51, s86
	global_store_short_d16_hi v[66:67], v45, off offset:1024
	v_mul_f32_e32 v45, v50, v33
	v_mul_f32_e32 v36, v36, v33
	v_mul_f32_e32 v33, v35, v33
	v_mul_f32_e32 v33, v33, v76
	v_mul_f32_e32 v45, v45, v74
	v_bfe_u32 v35, v33, 16, 1
	v_bfe_u32 v50, v45, 16, 1
	v_add3_u32 v33, v33, v35, s86
	v_add3_u32 v45, v45, v50, s86
	global_store_short_d16_hi v[66:67], v33, off offset:1216
	v_fmamk_f32 v33, v46, 0x3c000000, v244
	v_or_b32_e32 v50, 3, v78
	v_rsq_f32_e32 v33, v33
	v_ashrrev_i32_e32 v51, 31, v50
	v_lshlrev_b64 v[50:51], 11, v[50:51]
	v_lshl_add_u64 v[50:51], s[2:3], 0, v[50:51]
	v_lshl_add_u64 v[50:51], v[50:51], 0, s[36:37]
	v_lshl_add_u64 v[50:51], v[50:51], 0, v[0:1]
	v_mul_f32_e32 v0, v34, v33
	v_mul_f32_e32 v0, v0, v65
	v_bfe_u32 v34, v0, 16, 1
	v_add3_u32 v0, v0, v34, s86
	global_store_short_d16_hi v[50:51], v0, off offset:1024
	v_mul_f32_e32 v0, v20, v33
	v_mul_f32_e32 v0, v0, v74
	v_bfe_u32 v20, v0, 16, 1
	v_add3_u32 v0, v0, v20, s86
	global_store_short_d16_hi v[50:51], v0, off offset:1088
	v_mul_f32_e32 v0, v19, v33
	v_mul_f32_e32 v0, v0, v75
	v_bfe_u32 v19, v0, 16, 1
	v_add3_u32 v0, v0, v19, s86
	global_store_short_d16_hi v[50:51], v0, off offset:1152
	v_mul_f32_e32 v0, v18, v33
	v_mul_f32_e32 v0, v0, v76
	v_bfe_u32 v18, v0, 16, 1
	v_add3_u32 v0, v0, v18, s86
	global_store_short_d16_hi v[50:51], v0, off offset:1216
	v_fmamk_f32 v0, v47, 0x3c000000, v244
	v_rsq_f32_e32 v0, v0
	v_lshl_add_u64 v[18:19], v[2:3], 0, s[0:1]
	s_mov_b64 s[0:1], 0x4800
	v_mul_f32_e32 v36, v36, v75
	v_mul_f32_e32 v20, v68, v0
	v_mul_f32_e32 v20, v20, v65
	v_bfe_u32 v33, v20, 16, 1
	v_add3_u32 v20, v20, v33, s86
	global_store_short_d16_hi v[18:19], v20, off offset:1024
	v_mul_f32_e32 v20, v52, v0
	v_mul_f32_e32 v20, v20, v74
	v_bfe_u32 v33, v20, 16, 1
	v_add3_u32 v20, v20, v33, s86
	global_store_short_d16_hi v[18:19], v20, off offset:1088
	v_mul_f32_e32 v20, v53, v0
	v_mul_f32_e32 v20, v20, v75
	v_bfe_u32 v33, v20, 16, 1
	v_mul_f32_e32 v0, v37, v0
	v_add3_u32 v20, v20, v33, s86
	v_mul_f32_e32 v0, v0, v76
	global_store_short_d16_hi v[18:19], v20, off offset:1152
	v_bfe_u32 v20, v0, 16, 1
	v_add3_u32 v0, v0, v20, s86
	global_store_short_d16_hi v[18:19], v0, off offset:1216
	v_fmamk_f32 v0, v49, 0x3c000000, v244
	v_rsq_f32_e32 v0, v0
	v_lshl_add_u64 v[18:19], v[2:3], 0, s[0:1]
	s_mov_b64 s[0:1], 0x5000
	global_store_short_d16_hi v[66:67], v45, off offset:1088
	v_mul_f32_e32 v20, v83, v0
	v_mul_f32_e32 v20, v20, v65
	v_bfe_u32 v33, v20, 16, 1
	v_add3_u32 v20, v20, v33, s86
	global_store_short_d16_hi v[18:19], v20, off offset:1024
	v_mul_f32_e32 v20, v69, v0
	v_mul_f32_e32 v20, v20, v74
	v_bfe_u32 v33, v20, 16, 1
	v_add3_u32 v20, v20, v33, s86
	global_store_short_d16_hi v[18:19], v20, off offset:1088
	v_mul_f32_e32 v20, v70, v0
	v_mul_f32_e32 v20, v20, v75
	v_bfe_u32 v33, v20, 16, 1
	v_mul_f32_e32 v0, v54, v0
	v_add3_u32 v20, v20, v33, s86
	v_mul_f32_e32 v0, v0, v76
	global_store_short_d16_hi v[18:19], v20, off offset:1152
	v_bfe_u32 v20, v0, 16, 1
	v_add3_u32 v0, v0, v20, s86
	global_store_short_d16_hi v[18:19], v0, off offset:1216
	v_fmamk_f32 v0, v59, 0x3c000000, v244
	v_rsq_f32_e32 v0, v0
	v_lshl_add_u64 v[18:19], v[2:3], 0, s[0:1]
	s_mov_b64 s[0:1], 0x5800
	v_bfe_u32 v45, v36, 16, 1
	v_mul_f32_e32 v20, v84, v0
	v_mul_f32_e32 v20, v20, v65
	v_bfe_u32 v33, v20, 16, 1
	v_add3_u32 v20, v20, v33, s86
	global_store_short_d16_hi v[18:19], v20, off offset:1024
	v_mul_f32_e32 v20, v55, v0
	v_mul_f32_e32 v20, v20, v74
	v_bfe_u32 v33, v20, 16, 1
	v_add3_u32 v20, v20, v33, s86
	global_store_short_d16_hi v[18:19], v20, off offset:1088
	v_mul_f32_e32 v20, v71, v0
	v_mul_f32_e32 v20, v20, v75
	v_bfe_u32 v33, v20, 16, 1
	v_mul_f32_e32 v0, v40, v0
	v_add3_u32 v20, v20, v33, s86
	v_mul_f32_e32 v0, v0, v76
	global_store_short_d16_hi v[18:19], v20, off offset:1152
	v_bfe_u32 v20, v0, 16, 1
	v_add3_u32 v0, v0, v20, s86
	global_store_short_d16_hi v[18:19], v0, off offset:1216
	v_fmamk_f32 v0, v61, 0x3c000000, v244
	v_rsq_f32_e32 v0, v0
	v_lshl_add_u64 v[18:19], v[2:3], 0, s[0:1]
	s_mov_b64 s[0:1], 0x8000
	v_add3_u32 v36, v36, v45, s86
	v_mul_f32_e32 v20, v85, v0
	v_mul_f32_e32 v20, v20, v65
	v_bfe_u32 v33, v20, 16, 1
	v_add3_u32 v20, v20, v33, s86
	global_store_short_d16_hi v[18:19], v20, off offset:1024
	v_mul_f32_e32 v20, v56, v0
	v_mul_f32_e32 v20, v20, v74
	v_bfe_u32 v33, v20, 16, 1
	v_add3_u32 v20, v20, v33, s86
	global_store_short_d16_hi v[18:19], v20, off offset:1088
	v_mul_f32_e32 v20, v72, v0
	v_mul_f32_e32 v20, v20, v75
	v_bfe_u32 v33, v20, 16, 1
	v_mul_f32_e32 v0, v41, v0
	v_add3_u32 v20, v20, v33, s86
	v_mul_f32_e32 v0, v0, v76
	global_store_short_d16_hi v[18:19], v20, off offset:1152
	v_bfe_u32 v20, v0, 16, 1
	v_add3_u32 v0, v0, v20, s86
	global_store_short_d16_hi v[18:19], v0, off offset:1216
	v_fmamk_f32 v0, v63, 0x3c000000, v244
	v_rsq_f32_e32 v0, v0
	v_lshl_add_u64 v[18:19], v[2:3], 0, s[0:1]
	s_mov_b64 s[0:1], 0x8800
	global_store_short_d16_hi v[66:67], v36, off offset:1152
	v_mul_f32_e32 v20, v86, v0
	v_mul_f32_e32 v20, v20, v65
	v_bfe_u32 v33, v20, 16, 1
	v_add3_u32 v20, v20, v33, s86
	global_store_short_d16_hi v[18:19], v20, off offset:1024
	v_mul_f32_e32 v20, v73, v0
	v_mul_f32_e32 v20, v20, v74
	v_bfe_u32 v33, v20, 16, 1
	v_add3_u32 v20, v20, v33, s86
	global_store_short_d16_hi v[18:19], v20, off offset:1088
	v_mul_f32_e32 v20, v57, v0
	v_mul_f32_e32 v20, v20, v75
	v_bfe_u32 v33, v20, 16, 1
	v_mul_f32_e32 v0, v42, v0
	v_add3_u32 v20, v20, v33, s86
	v_mul_f32_e32 v0, v0, v76
	global_store_short_d16_hi v[18:19], v20, off offset:1152
	v_bfe_u32 v20, v0, 16, 1
	v_add3_u32 v0, v0, v20, s86
	global_store_short_d16_hi v[18:19], v0, off offset:1216
	v_fmamk_f32 v0, v64, 0x3c000000, v244
	v_rsq_f32_e32 v0, v0
	v_lshl_add_u64 v[18:19], v[2:3], 0, s[0:1]
	s_mov_b64 s[0:1], 0x9000
	v_mul_f32_e32 v20, v39, v0
	v_mul_f32_e32 v20, v20, v65
	v_bfe_u32 v33, v20, 16, 1
	v_add3_u32 v20, v20, v33, s86
	global_store_short_d16_hi v[18:19], v20, off offset:1024
	v_mul_f32_e32 v20, v38, v0
	v_mul_f32_e32 v20, v20, v74
	v_bfe_u32 v33, v20, 16, 1
	v_add3_u32 v20, v20, v33, s86
	global_store_short_d16_hi v[18:19], v20, off offset:1088
	v_mul_f32_e32 v20, v26, v0
	v_mul_f32_e32 v20, v20, v75
	v_bfe_u32 v26, v20, 16, 1
	v_mul_f32_e32 v0, v25, v0
	v_add3_u32 v20, v20, v26, s86
	v_mul_f32_e32 v0, v0, v76
	global_store_short_d16_hi v[18:19], v20, off offset:1152
	v_bfe_u32 v20, v0, 16, 1
	v_add3_u32 v0, v0, v20, s86
	global_store_short_d16_hi v[18:19], v0, off offset:1216
	v_fmamk_f32 v0, v62, 0x3c000000, v244
	v_rsq_f32_e32 v0, v0
	v_lshl_add_u64 v[18:19], v[2:3], 0, s[0:1]
	s_mov_b64 s[0:1], 0x9800
	v_mul_f32_e32 v20, v24, v0
	v_mul_f32_e32 v20, v20, v65
	v_bfe_u32 v24, v20, 16, 1
	v_add3_u32 v20, v20, v24, s86
	global_store_short_d16_hi v[18:19], v20, off offset:1024
	v_mul_f32_e32 v20, v23, v0
	v_mul_f32_e32 v20, v20, v74
	v_bfe_u32 v23, v20, 16, 1
	v_add3_u32 v20, v20, v23, s86
	global_store_short_d16_hi v[18:19], v20, off offset:1088
	v_mul_f32_e32 v20, v22, v0
	v_mul_f32_e32 v20, v20, v75
	v_bfe_u32 v22, v20, 16, 1
	v_mul_f32_e32 v0, v21, v0
	v_add3_u32 v20, v20, v22, s86
	v_mul_f32_e32 v0, v0, v76
	global_store_short_d16_hi v[18:19], v20, off offset:1152
	v_bfe_u32 v20, v0, 16, 1
	v_add3_u32 v0, v0, v20, s86
	global_store_short_d16_hi v[18:19], v0, off offset:1216
	v_fmamk_f32 v0, v60, 0x3c000000, v244
	v_rsq_f32_e32 v0, v0
	v_lshl_add_u64 v[18:19], v[2:3], 0, s[0:1]
	s_mov_b64 s[0:1], 0xc000
	v_mul_f32_e32 v13, v13, v0
	v_mul_f32_e32 v12, v12, v0
	v_mul_f32_e32 v11, v11, v0
	v_mul_f32_e32 v0, v10, v0
	v_mul_f32_e32 v0, v0, v76
	v_bfe_u32 v10, v0, 16, 1
	v_mul_f32_e32 v13, v13, v65
	v_add3_u32 v0, v0, v10, s86
	v_bfe_u32 v20, v13, 16, 1
	global_store_short_d16_hi v[18:19], v0, off offset:1216
	v_fmamk_f32 v0, v58, 0x3c000000, v244
	v_add3_u32 v13, v13, v20, s86
	v_mul_f32_e32 v12, v12, v74
	v_rsq_f32_e32 v0, v0
	global_store_short_d16_hi v[18:19], v13, off offset:1024
	v_bfe_u32 v13, v12, 16, 1
	v_add3_u32 v12, v12, v13, s86
	v_mul_f32_e32 v11, v11, v75
	global_store_short_d16_hi v[18:19], v12, off offset:1088
	v_bfe_u32 v12, v11, 16, 1
	v_add3_u32 v11, v11, v12, s86
	v_mul_f32_e32 v12, v28, v0
	v_mul_f32_e32 v12, v12, v65
	v_bfe_u32 v13, v12, 16, 1
	global_store_short_d16_hi v[18:19], v11, off offset:1152
	v_lshl_add_u64 v[10:11], v[2:3], 0, s[0:1]
	v_add3_u32 v12, v12, v13, s86
	global_store_short_d16_hi v[10:11], v12, off offset:1024
	v_mul_f32_e32 v12, v14, v0
	v_mul_f32_e32 v12, v12, v74
	v_bfe_u32 v13, v12, 16, 1
	v_add3_u32 v12, v12, v13, s86
	global_store_short_d16_hi v[10:11], v12, off offset:1088
	v_mul_f32_e32 v12, v27, v0
	v_mul_f32_e32 v0, v6, v0
	v_mul_f32_e32 v0, v0, v76
	v_bfe_u32 v6, v0, 16, 1
	v_add3_u32 v0, v0, v6, s86
	global_store_short_d16_hi v[10:11], v0, off offset:1216
	v_fmamk_f32 v0, v48, 0x3c000000, v244
	v_rsq_f32_e32 v0, v0
	v_mul_f32_e32 v12, v12, v75
	v_bfe_u32 v13, v12, 16, 1
	v_add3_u32 v12, v12, v13, s86
	v_mul_f32_e32 v6, v30, v0
	v_mul_f32_e32 v6, v6, v65
	global_store_short_d16_hi v[10:11], v12, off offset:1152
	s_mov_b64 s[0:1], 0xc800
	v_bfe_u32 v12, v6, 16, 1
	v_lshl_add_u64 v[10:11], v[2:3], 0, s[0:1]
	v_add3_u32 v6, v6, v12, s86
	global_store_short_d16_hi v[10:11], v6, off offset:1024
	v_mul_f32_e32 v6, v15, v0
	v_mul_f32_e32 v6, v6, v74
	v_bfe_u32 v12, v6, 16, 1
	v_add3_u32 v6, v6, v12, s86
	global_store_short_d16_hi v[10:11], v6, off offset:1088
	v_mul_f32_e32 v6, v29, v0
	v_mul_f32_e32 v6, v6, v75
	v_bfe_u32 v12, v6, 16, 1
	v_mul_f32_e32 v0, v7, v0
	v_add3_u32 v6, v6, v12, s86
	v_mul_f32_e32 v0, v0, v76
	global_store_short_d16_hi v[10:11], v6, off offset:1152
	v_bfe_u32 v6, v0, 16, 1
	v_add3_u32 v0, v0, v6, s86
	global_store_short_d16_hi v[10:11], v0, off offset:1216
	v_fmamk_f32 v0, v44, 0x3c000000, v244
	v_rsq_f32_e32 v0, v0
	s_mov_b64 s[0:1], 0xd000
	v_lshl_add_u64 v[6:7], v[2:3], 0, s[0:1]
	s_mov_b64 s[0:1], 0xd800
	v_mul_f32_e32 v10, v31, v0
	v_mul_f32_e32 v10, v10, v65
	v_bfe_u32 v11, v10, 16, 1
	v_mul_f32_e32 v8, v8, v0
	v_add3_u32 v10, v10, v11, s86
	v_mul_f32_e32 v8, v8, v74
	global_store_short_d16_hi v[6:7], v10, off offset:1024
	v_bfe_u32 v10, v8, 16, 1
	v_add3_u32 v8, v8, v10, s86
	global_store_short_d16_hi v[6:7], v8, off offset:1088
	v_mul_f32_e32 v8, v16, v0
	v_mul_f32_e32 v0, v4, v0
	v_mul_f32_e32 v0, v0, v76
	v_bfe_u32 v4, v0, 16, 1
	v_add3_u32 v0, v0, v4, s86
	global_store_short_d16_hi v[6:7], v0, off offset:1216
	v_fmamk_f32 v0, v43, 0x3c000000, v244
	v_rsq_f32_e32 v0, v0
	v_mul_f32_e32 v8, v8, v75
	v_bfe_u32 v10, v8, 16, 1
	v_add3_u32 v8, v8, v10, s86
	v_mul_f32_e32 v4, v32, v0
	v_mul_f32_e32 v4, v65, v4
	global_store_short_d16_hi v[6:7], v8, off offset:1152
	v_bfe_u32 v6, v4, 16, 1
	v_lshl_add_u64 v[2:3], v[2:3], 0, s[0:1]
	v_add3_u32 v4, v4, v6, s86
	global_store_short_d16_hi v[2:3], v4, off offset:1024
	v_mul_f32_e32 v4, v17, v0
	v_mul_f32_e32 v4, v74, v4
	v_bfe_u32 v6, v4, 16, 1
	v_add3_u32 v4, v4, v6, s86
	global_store_short_d16_hi v[2:3], v4, off offset:1088
	v_mul_f32_e32 v4, v9, v0
	v_mul_f32_e32 v4, v75, v4
	v_bfe_u32 v6, v4, 16, 1
	v_mul_f32_e32 v0, v5, v0
	v_add3_u32 v4, v4, v6, s86
	v_mul_f32_e32 v0, v76, v0
	global_store_short_d16_hi v[2:3], v4, off offset:1152
	v_bfe_u32 v4, v0, 16, 1
	v_add3_u32 v0, v0, v4, s86
	global_store_short_d16_hi v[2:3], v0, off offset:1216
	s_waitcnt lgkmcnt(0)
	s_barrier

.LBB0_920:
	s_waitcnt vmcnt(3)
	v_lshlrev_b32_e32 v9, 16, v18
	s_waitcnt vmcnt(1)
	v_lshlrev_b32_e32 v77, 16, v22
	v_lshlrev_b32_e32 v73, 16, v20
	s_waitcnt vmcnt(0)
	v_lshlrev_b32_e32 v81, 16, v24
	v_fmac_f32_e32 v77, v0, v9
	v_add_f32_e32 v9, v77, v81
	v_mul_f32_e32 v77, 0xbfb8aa3b, v73
	v_exp_f32_e32 v77, v77
	v_and_b32_e32 v74, 0xffff0000, v20
	v_lshlrev_b32_e32 v75, 16, v21
	v_lshlrev_b32_e32 v71, 16, v19
	v_add_f32_e32 v77, 1.0, v77
	v_rcp_f32_e32 v77, v77
	v_lshlrev_b32_e32 v79, 16, v23
	v_lshlrev_b32_e32 v83, 16, v25
	v_fmac_f32_e32 v79, v0, v71
	v_mul_f32_e32 v73, v77, v73
	v_mul_f32_e32 v9, v73, v9
	v_mul_f32_e32 v73, 0xbfb8aa3b, v74
	v_exp_f32_e32 v73, v73
	v_and_b32_e32 v76, 0xffff0000, v21
	v_add_f32_e32 v71, v79, v83
	v_and_b32_e32 v70, 0xffff0000, v18
	v_add_f32_e32 v73, 1.0, v73
	v_rcp_f32_e32 v73, v73
	v_and_b32_e32 v78, 0xffff0000, v22
	v_and_b32_e32 v82, 0xffff0000, v24
	v_fmac_f32_e32 v78, v0, v70
	v_mul_f32_e32 v73, v73, v74
	v_mul_f32_e32 v74, 0xbfb8aa3b, v75
	v_exp_f32_e32 v74, v74
	v_add_f32_e32 v70, v78, v82
	v_and_b32_e32 v72, 0xffff0000, v19
	v_and_b32_e32 v80, 0xffff0000, v23
	v_add_f32_e32 v74, 1.0, v74
	v_rcp_f32_e32 v74, v74
	v_mul_f32_e32 v70, v73, v70
	v_and_b32_e32 v84, 0xffff0000, v25
	v_mul_f32_e32 v73, v70, v70
	v_mul_f32_e32 v74, v74, v75
	v_mul_f32_e32 v71, v74, v71
	v_mul_f32_e32 v74, 0xbfb8aa3b, v76
	v_exp_f32_e32 v74, v74
	v_fmac_f32_e32 v80, v0, v72
	v_fmac_f32_e32 v73, v9, v9
	v_add_f32_e32 v72, v80, v84
	v_add_f32_e32 v74, 1.0, v74
	v_rcp_f32_e32 v74, v74
	v_fmac_f32_e32 v73, v71, v71
	s_sub_i32 s56, s44, 24
	s_cmp_ge_i32 s56, s36
	v_mul_f32_e32 v74, v74, v76
	v_mul_f32_e32 v72, v74, v72
	v_fmac_f32_e32 v73, v72, v72
	s_nop 1
	v_add_f32_dpp v73, v73, v73 quad_perm:[1,0,3,2] row_mask:0xf bank_mask:0xf
	s_nop 1
	v_add_f32_dpp v73, v73, v73 quad_perm:[2,3,0,1] row_mask:0xf bank_mask:0xf
	s_nop 1
	v_add_f32_dpp v73, v73, v73 row_half_mirror row_mask:0xf bank_mask:0xf
	s_nop 1
	v_add_f32_dpp v73, v73, v73 row_mirror row_mask:0xf bank_mask:0xf
	v_mov_b32_e32 v74, v73
	s_nop 1
	v_permlane16_swap_b32_e32 v73, v74
	v_add_f32_e32 v73, v73, v74
	v_fmamk_f32 v73, v73, 0x3c000000, v244
	v_rsq_f32_e32 v73, v73
	s_nop 0
	v_mul_f32_e32 v9, v9, v73
	v_mul_f32_e32 v70, v70, v73
	v_mul_f32_e32 v9, v2, v9
	v_mul_f32_e32 v70, v3, v70
	v_cvt_pk_bf16_f32 v70, v9, v70
	v_mul_f32_e32 v9, v71, v73
	v_mul_f32_e32 v71, v72, v73
	v_mul_f32_e32 v71, v5, v71
	v_lshl_add_u64 v[72:73], s[42:43], 0, v[10:11]
	v_mul_f32_e32 v9, v4, v9
	v_cvt_pk_bf16_f32 v71, v9, v71
	global_store_dwordx2 v[72:73], v[70:71], off
	s_cbranch_scc1 .LBB0_923
	v_lshlrev_b32_e32 v9, 16, v26
	v_lshlrev_b32_e32 v77, 16, v30
	v_lshlrev_b32_e32 v73, 16, v28
	v_lshlrev_b32_e32 v81, 16, v32
	v_fmac_f32_e32 v77, v0, v9
	v_add_f32_e32 v9, v77, v81
	v_mul_f32_e32 v77, 0xbfb8aa3b, v73
	v_exp_f32_e32 v77, v77
	v_and_b32_e32 v74, 0xffff0000, v28
	v_lshlrev_b32_e32 v75, 16, v29
	v_lshlrev_b32_e32 v71, 16, v27
	v_add_f32_e32 v77, 1.0, v77
	v_rcp_f32_e32 v77, v77
	v_lshlrev_b32_e32 v79, 16, v31
	v_lshlrev_b32_e32 v83, 16, v33
	v_fmac_f32_e32 v79, v0, v71
	v_mul_f32_e32 v73, v77, v73
	v_mul_f32_e32 v9, v73, v9
	v_mul_f32_e32 v73, 0xbfb8aa3b, v74
	v_exp_f32_e32 v73, v73
	v_and_b32_e32 v76, 0xffff0000, v29
	v_add_f32_e32 v71, v79, v83
	v_and_b32_e32 v70, 0xffff0000, v26
	v_add_f32_e32 v73, 1.0, v73
	v_rcp_f32_e32 v73, v73
	v_and_b32_e32 v78, 0xffff0000, v30
	v_and_b32_e32 v82, 0xffff0000, v32
	v_fmac_f32_e32 v78, v0, v70
	v_mul_f32_e32 v73, v73, v74
	v_mul_f32_e32 v74, 0xbfb8aa3b, v75
	v_exp_f32_e32 v74, v74
	v_add_f32_e32 v70, v78, v82
	v_and_b32_e32 v72, 0xffff0000, v27
	v_and_b32_e32 v80, 0xffff0000, v31
	v_add_f32_e32 v74, 1.0, v74
	v_rcp_f32_e32 v74, v74
	v_mul_f32_e32 v70, v73, v70
	v_and_b32_e32 v84, 0xffff0000, v33
	v_mul_f32_e32 v73, v70, v70
	v_mul_f32_e32 v74, v74, v75
	v_mul_f32_e32 v71, v74, v71
	v_mul_f32_e32 v74, 0xbfb8aa3b, v76
	v_exp_f32_e32 v74, v74
	v_fmac_f32_e32 v80, v0, v72
	v_fmac_f32_e32 v73, v9, v9
	v_add_f32_e32 v72, v80, v84
	v_add_f32_e32 v74, 1.0, v74
	v_rcp_f32_e32 v74, v74
	v_fmac_f32_e32 v73, v71, v71
	s_ashr_i32 s57, s56, 31
	s_lshl_b64 s[56:57], s[56:57], 11
	v_mul_f32_e32 v74, v74, v76
	v_mul_f32_e32 v72, v74, v72
	v_fmac_f32_e32 v73, v72, v72
	s_nop 1
	v_add_f32_dpp v73, v73, v73 quad_perm:[1,0,3,2] row_mask:0xf bank_mask:0xf
	s_nop 1
	v_add_f32_dpp v73, v73, v73 quad_perm:[2,3,0,1] row_mask:0xf bank_mask:0xf
	s_nop 1
	v_add_f32_dpp v73, v73, v73 row_half_mirror row_mask:0xf bank_mask:0xf
	s_nop 1
	v_add_f32_dpp v73, v73, v73 row_mirror row_mask:0xf bank_mask:0xf
	v_mov_b32_e32 v74, v73
	s_nop 1
	v_permlane16_swap_b32_e32 v73, v74
	v_add_f32_e32 v73, v73, v74
	v_fmamk_f32 v73, v73, 0x3c000000, v244
	v_rsq_f32_e32 v73, v73
	s_nop 0
	v_mul_f32_e32 v9, v9, v73
	v_mul_f32_e32 v70, v70, v73
	v_mul_f32_e32 v9, v2, v9
	v_mul_f32_e32 v70, v3, v70
	v_cvt_pk_bf16_f32 v70, v9, v70
	v_mul_f32_e32 v9, v71, v73
	v_mul_f32_e32 v71, v72, v73
	v_mul_f32_e32 v71, v5, v71
	v_lshl_add_u64 v[72:73], v[44:45], 0, s[56:57]
	v_mul_f32_e32 v9, v4, v9
	v_cvt_pk_bf16_f32 v71, v9, v71
	global_store_dwordx2 v[72:73], v[70:71], off offset:512
	s_add_i32 s56, s44, -16
	s_cmp_ge_i32 s56, s36
	s_cbranch_scc0 .LBB0_924

.LBB0_924:
	v_lshlrev_b32_e32 v9, 16, v34
	v_lshlrev_b32_e32 v77, 16, v38
	v_lshlrev_b32_e32 v73, 16, v36
	v_lshlrev_b32_e32 v81, 16, v40
	v_fmac_f32_e32 v77, v0, v9
	v_add_f32_e32 v9, v77, v81
	v_mul_f32_e32 v77, 0xbfb8aa3b, v73
	v_exp_f32_e32 v77, v77
	v_and_b32_e32 v74, 0xffff0000, v36
	v_lshlrev_b32_e32 v75, 16, v37
	v_lshlrev_b32_e32 v71, 16, v35
	v_add_f32_e32 v77, 1.0, v77
	v_rcp_f32_e32 v77, v77
	v_lshlrev_b32_e32 v79, 16, v39
	v_lshlrev_b32_e32 v83, 16, v41
	v_fmac_f32_e32 v79, v0, v71
	v_mul_f32_e32 v73, v77, v73
	v_mul_f32_e32 v9, v73, v9
	v_mul_f32_e32 v73, 0xbfb8aa3b, v74
	v_exp_f32_e32 v73, v73
	v_and_b32_e32 v76, 0xffff0000, v37
	v_add_f32_e32 v71, v79, v83
	v_and_b32_e32 v70, 0xffff0000, v34
	v_add_f32_e32 v73, 1.0, v73
	v_rcp_f32_e32 v73, v73
	v_and_b32_e32 v78, 0xffff0000, v38
	v_and_b32_e32 v82, 0xffff0000, v40
	v_fmac_f32_e32 v78, v0, v70
	v_mul_f32_e32 v73, v73, v74
	v_mul_f32_e32 v74, 0xbfb8aa3b, v75
	v_exp_f32_e32 v74, v74
	v_add_f32_e32 v70, v78, v82
	v_and_b32_e32 v72, 0xffff0000, v35
	v_and_b32_e32 v80, 0xffff0000, v39
	v_add_f32_e32 v74, 1.0, v74
	v_rcp_f32_e32 v74, v74
	v_mul_f32_e32 v70, v73, v70
	v_and_b32_e32 v84, 0xffff0000, v41
	v_mul_f32_e32 v73, v70, v70
	v_mul_f32_e32 v74, v74, v75
	v_mul_f32_e32 v71, v74, v71
	v_mul_f32_e32 v74, 0xbfb8aa3b, v76
	v_exp_f32_e32 v74, v74
	v_fmac_f32_e32 v80, v0, v72
	v_fmac_f32_e32 v73, v9, v9
	v_add_f32_e32 v72, v80, v84
	v_add_f32_e32 v74, 1.0, v74
	v_rcp_f32_e32 v74, v74
	v_fmac_f32_e32 v73, v71, v71
	s_ashr_i32 s57, s56, 31
	s_lshl_b64 s[56:57], s[56:57], 11
	v_mul_f32_e32 v74, v74, v76
	v_mul_f32_e32 v72, v74, v72
	v_fmac_f32_e32 v73, v72, v72
	s_nop 1
	v_add_f32_dpp v73, v73, v73 quad_perm:[1,0,3,2] row_mask:0xf bank_mask:0xf
	s_nop 1
	v_add_f32_dpp v73, v73, v73 quad_perm:[2,3,0,1] row_mask:0xf bank_mask:0xf
	s_nop 1
	v_add_f32_dpp v73, v73, v73 row_half_mirror row_mask:0xf bank_mask:0xf
	s_nop 1
	v_add_f32_dpp v73, v73, v73 row_mirror row_mask:0xf bank_mask:0xf
	v_mov_b32_e32 v74, v73
	s_nop 1
	v_permlane16_swap_b32_e32 v73, v74
	v_add_f32_e32 v73, v73, v74
	v_fmamk_f32 v73, v73, 0x3c000000, v244
	v_rsq_f32_e32 v73, v73
	s_nop 0
	v_mul_f32_e32 v9, v9, v73
	v_mul_f32_e32 v70, v70, v73
	v_mul_f32_e32 v9, v2, v9
	v_mul_f32_e32 v70, v3, v70
	v_cvt_pk_bf16_f32 v70, v9, v70
	v_mul_f32_e32 v9, v71, v73
	v_mul_f32_e32 v71, v72, v73
	v_mul_f32_e32 v71, v5, v71
	v_lshl_add_u64 v[72:73], v[44:45], 0, s[56:57]
	v_mul_f32_e32 v9, v4, v9
	v_cvt_pk_bf16_f32 v71, v9, v71
	global_store_dwordx2 v[72:73], v[70:71], off offset:512
	s_andn2_b64 vcc, exec, s[54:55]
	s_cbranch_vccnz .LBB0_914

.LBB0_930:
	v_lshlrev_b32_e32 v9, 16, v46
	v_lshlrev_b32_e32 v77, 16, v62
	v_lshlrev_b32_e32 v73, 16, v48
	v_lshlrev_b32_e32 v81, 16, v68
	v_fmac_f32_e32 v77, v0, v9
	v_add_f32_e32 v9, v77, v81
	v_mul_f32_e32 v77, 0xbfb8aa3b, v73
	v_exp_f32_e32 v77, v77
	v_and_b32_e32 v74, 0xffff0000, v48
	v_lshlrev_b32_e32 v75, 16, v49
	v_lshlrev_b32_e32 v71, 16, v47
	v_add_f32_e32 v77, 1.0, v77
	v_rcp_f32_e32 v77, v77
	v_lshlrev_b32_e32 v79, 16, v63
	v_lshlrev_b32_e32 v83, 16, v69
	v_fmac_f32_e32 v79, v0, v71
	v_mul_f32_e32 v73, v77, v73
	v_mul_f32_e32 v9, v73, v9
	v_mul_f32_e32 v73, 0xbfb8aa3b, v74
	v_exp_f32_e32 v73, v73
	v_and_b32_e32 v76, 0xffff0000, v49
	v_add_f32_e32 v71, v79, v83
	v_and_b32_e32 v70, 0xffff0000, v46
	v_add_f32_e32 v73, 1.0, v73
	v_rcp_f32_e32 v73, v73
	v_and_b32_e32 v78, 0xffff0000, v62
	v_and_b32_e32 v82, 0xffff0000, v68
	v_fmac_f32_e32 v78, v0, v70
	v_mul_f32_e32 v73, v73, v74
	v_mul_f32_e32 v74, 0xbfb8aa3b, v75
	v_exp_f32_e32 v74, v74
	v_add_f32_e32 v70, v78, v82
	v_and_b32_e32 v72, 0xffff0000, v47
	v_and_b32_e32 v80, 0xffff0000, v63
	v_add_f32_e32 v74, 1.0, v74
	v_rcp_f32_e32 v74, v74
	v_mul_f32_e32 v70, v73, v70
	v_and_b32_e32 v84, 0xffff0000, v69
	v_mul_f32_e32 v73, v70, v70
	v_mul_f32_e32 v74, v74, v75
	v_mul_f32_e32 v71, v74, v71
	v_mul_f32_e32 v74, 0xbfb8aa3b, v76
	v_exp_f32_e32 v74, v74
	v_fmac_f32_e32 v80, v0, v72
	v_fmac_f32_e32 v73, v9, v9
	v_add_f32_e32 v72, v80, v84
	v_add_f32_e32 v74, 1.0, v74
	v_rcp_f32_e32 v74, v74
	v_fmac_f32_e32 v73, v71, v71
	s_cmp_ge_i32 s44, s36
	v_mul_f32_e32 v74, v74, v76
	v_mul_f32_e32 v72, v74, v72
	v_fmac_f32_e32 v73, v72, v72
	s_nop 1
	v_add_f32_dpp v73, v73, v73 quad_perm:[1,0,3,2] row_mask:0xf bank_mask:0xf
	s_nop 1
	v_add_f32_dpp v73, v73, v73 quad_perm:[2,3,0,1] row_mask:0xf bank_mask:0xf
	s_nop 1
	v_add_f32_dpp v73, v73, v73 row_half_mirror row_mask:0xf bank_mask:0xf
	s_nop 1
	v_add_f32_dpp v73, v73, v73 row_mirror row_mask:0xf bank_mask:0xf
	v_mov_b32_e32 v74, v73
	s_nop 1
	v_permlane16_swap_b32_e32 v73, v74
	v_add_f32_e32 v73, v73, v74
	v_fmamk_f32 v73, v73, 0x3c000000, v244
	v_rsq_f32_e32 v73, v73
	s_nop 0
	v_mul_f32_e32 v9, v9, v73
	v_mul_f32_e32 v70, v70, v73
	v_mul_f32_e32 v9, v2, v9
	v_mul_f32_e32 v70, v3, v70
	v_cvt_pk_bf16_f32 v70, v9, v70
	v_mul_f32_e32 v9, v71, v73
	v_mul_f32_e32 v71, v72, v73
	v_mul_f32_e32 v71, v5, v71
	v_lshl_add_u64 v[72:73], s[46:47], 0, v[10:11]
	v_mul_f32_e32 v9, v4, v9
	v_cvt_pk_bf16_f32 v71, v9, v71
	global_store_dwordx2 v[72:73], v[70:71], off
	s_cbranch_scc1 .LBB0_932
	v_lshlrev_b32_e32 v9, 16, v50
	v_lshlrev_b32_e32 v77, 16, v58
	v_lshlrev_b32_e32 v73, 16, v54
	v_lshlrev_b32_e32 v81, 16, v64
	v_fmac_f32_e32 v77, v0, v9
	v_add_f32_e32 v9, v77, v81
	v_mul_f32_e32 v77, 0xbfb8aa3b, v73
	v_exp_f32_e32 v77, v77
	v_and_b32_e32 v74, 0xffff0000, v54
	v_lshlrev_b32_e32 v75, 16, v55
	v_lshlrev_b32_e32 v71, 16, v51
	v_add_f32_e32 v77, 1.0, v77
	v_rcp_f32_e32 v77, v77
	v_lshlrev_b32_e32 v79, 16, v59
	v_lshlrev_b32_e32 v83, 16, v65
	v_fmac_f32_e32 v79, v0, v71
	v_mul_f32_e32 v73, v77, v73
	v_mul_f32_e32 v9, v73, v9
	v_mul_f32_e32 v73, 0xbfb8aa3b, v74
	v_exp_f32_e32 v73, v73
	v_and_b32_e32 v76, 0xffff0000, v55
	v_add_f32_e32 v71, v79, v83
	v_and_b32_e32 v70, 0xffff0000, v50
	v_add_f32_e32 v73, 1.0, v73
	v_rcp_f32_e32 v73, v73
	v_and_b32_e32 v78, 0xffff0000, v58
	v_and_b32_e32 v82, 0xffff0000, v64
	v_fmac_f32_e32 v78, v0, v70
	v_mul_f32_e32 v73, v73, v74
	v_mul_f32_e32 v74, 0xbfb8aa3b, v75
	v_exp_f32_e32 v74, v74
	v_add_f32_e32 v70, v78, v82
	v_and_b32_e32 v72, 0xffff0000, v51
	v_and_b32_e32 v80, 0xffff0000, v59
	v_add_f32_e32 v74, 1.0, v74
	v_rcp_f32_e32 v74, v74
	v_mul_f32_e32 v70, v73, v70
	v_and_b32_e32 v84, 0xffff0000, v65
	v_mul_f32_e32 v73, v70, v70
	v_mul_f32_e32 v74, v74, v75
	v_mul_f32_e32 v71, v74, v71
	v_mul_f32_e32 v74, 0xbfb8aa3b, v76
	v_exp_f32_e32 v74, v74
	v_fmac_f32_e32 v80, v0, v72
	v_fmac_f32_e32 v73, v9, v9
	v_add_f32_e32 v72, v80, v84
	v_add_f32_e32 v74, 1.0, v74
	v_rcp_f32_e32 v74, v74
	v_fmac_f32_e32 v73, v71, v71
	s_ashr_i32 s45, s44, 31
	s_lshl_b64 s[54:55], s[44:45], 11
	v_mul_f32_e32 v74, v74, v76
	v_mul_f32_e32 v72, v74, v72
	v_fmac_f32_e32 v73, v72, v72
	s_nop 1
	v_add_f32_dpp v73, v73, v73 quad_perm:[1,0,3,2] row_mask:0xf bank_mask:0xf
	s_nop 1
	v_add_f32_dpp v73, v73, v73 quad_perm:[2,3,0,1] row_mask:0xf bank_mask:0xf
	s_nop 1
	v_add_f32_dpp v73, v73, v73 row_half_mirror row_mask:0xf bank_mask:0xf
	s_nop 1
	v_add_f32_dpp v73, v73, v73 row_mirror row_mask:0xf bank_mask:0xf
	v_mov_b32_e32 v74, v73
	s_nop 1
	v_permlane16_swap_b32_e32 v73, v74
	v_add_f32_e32 v73, v73, v74
	v_fmamk_f32 v73, v73, 0x3c000000, v244
	v_rsq_f32_e32 v73, v73
	s_nop 0
	v_mul_f32_e32 v9, v9, v73
	v_mul_f32_e32 v70, v70, v73
	v_mul_f32_e32 v9, v2, v9
	v_mul_f32_e32 v70, v3, v70
	v_cvt_pk_bf16_f32 v70, v9, v70
	v_mul_f32_e32 v9, v71, v73
	v_mul_f32_e32 v71, v72, v73
	v_mul_f32_e32 v71, v5, v71
	v_lshl_add_u64 v[72:73], v[44:45], 0, s[54:55]
	v_mul_f32_e32 v9, v4, v9
	v_cvt_pk_bf16_f32 v71, v9, v71
	global_store_dwordx2 v[72:73], v[70:71], off offset:512
.LBB0_932:
	s_add_i32 s54, s44, 8
	s_cmp_ge_i32 s54, s36
	s_cbranch_scc1 .LBB0_914
	v_lshlrev_b32_e32 v9, 16, v52
	v_lshlrev_b32_e32 v77, 16, v60
	v_lshlrev_b32_e32 v73, 16, v56
	v_lshlrev_b32_e32 v81, 16, v66
	v_fmac_f32_e32 v77, v0, v9
	v_add_f32_e32 v9, v77, v81
	v_mul_f32_e32 v77, 0xbfb8aa3b, v73
	v_exp_f32_e32 v77, v77
	v_and_b32_e32 v74, 0xffff0000, v56
	v_lshlrev_b32_e32 v75, 16, v57
	v_lshlrev_b32_e32 v71, 16, v53
	v_add_f32_e32 v77, 1.0, v77
	v_rcp_f32_e32 v77, v77
	v_lshlrev_b32_e32 v79, 16, v61
	v_lshlrev_b32_e32 v83, 16, v67
	v_fmac_f32_e32 v79, v0, v71
	v_mul_f32_e32 v73, v77, v73
	v_mul_f32_e32 v9, v73, v9
	v_mul_f32_e32 v73, 0xbfb8aa3b, v74
	v_exp_f32_e32 v73, v73
	v_and_b32_e32 v76, 0xffff0000, v57
	v_add_f32_e32 v71, v79, v83
	v_and_b32_e32 v70, 0xffff0000, v52
	v_add_f32_e32 v73, 1.0, v73
	v_rcp_f32_e32 v73, v73
	v_and_b32_e32 v78, 0xffff0000, v60
	v_and_b32_e32 v82, 0xffff0000, v66
	v_fmac_f32_e32 v78, v0, v70
	v_mul_f32_e32 v73, v73, v74
	v_mul_f32_e32 v74, 0xbfb8aa3b, v75
	v_exp_f32_e32 v74, v74
	v_add_f32_e32 v70, v78, v82
	v_and_b32_e32 v72, 0xffff0000, v53
	v_and_b32_e32 v80, 0xffff0000, v61
	v_add_f32_e32 v74, 1.0, v74
	v_rcp_f32_e32 v74, v74
	v_mul_f32_e32 v70, v73, v70
	v_and_b32_e32 v84, 0xffff0000, v67
	v_mul_f32_e32 v73, v70, v70
	v_mul_f32_e32 v74, v74, v75
	v_mul_f32_e32 v71, v74, v71
	v_mul_f32_e32 v74, 0xbfb8aa3b, v76
	v_exp_f32_e32 v74, v74
	v_fmac_f32_e32 v80, v0, v72
	v_fmac_f32_e32 v73, v9, v9
	v_add_f32_e32 v72, v80, v84
	v_add_f32_e32 v74, 1.0, v74
	v_rcp_f32_e32 v74, v74
	v_fmac_f32_e32 v73, v71, v71
	s_ashr_i32 s55, s54, 31
	s_lshl_b64 s[54:55], s[54:55], 11
	v_mul_f32_e32 v74, v74, v76
	v_mul_f32_e32 v72, v74, v72
	v_fmac_f32_e32 v73, v72, v72
	s_nop 1
	v_add_f32_dpp v73, v73, v73 quad_perm:[1,0,3,2] row_mask:0xf bank_mask:0xf
	s_nop 1
	v_add_f32_dpp v73, v73, v73 quad_perm:[2,3,0,1] row_mask:0xf bank_mask:0xf
	s_nop 1
	v_add_f32_dpp v73, v73, v73 row_half_mirror row_mask:0xf bank_mask:0xf
	s_nop 1
	v_add_f32_dpp v73, v73, v73 row_mirror row_mask:0xf bank_mask:0xf
	v_mov_b32_e32 v74, v73
	s_nop 1
	v_permlane16_swap_b32_e32 v73, v74
	v_add_f32_e32 v73, v73, v74
	v_fmamk_f32 v73, v73, 0x3c000000, v244
	v_rsq_f32_e32 v73, v73
	s_nop 0
	v_mul_f32_e32 v9, v9, v73
	v_mul_f32_e32 v70, v70, v73
	v_mul_f32_e32 v9, v2, v9
	v_mul_f32_e32 v70, v3, v70
	v_cvt_pk_bf16_f32 v70, v9, v70
	v_mul_f32_e32 v9, v71, v73
	v_mul_f32_e32 v71, v72, v73
	v_mul_f32_e32 v71, v5, v71
	v_lshl_add_u64 v[72:73], v[44:45], 0, s[54:55]
	v_mul_f32_e32 v9, v4, v9
	v_cvt_pk_bf16_f32 v71, v9, v71
	global_store_dwordx2 v[72:73], v[70:71], off offset:512
	s_branch .LBB0_914

.LBB0_942:
	v_ashrrev_i32_e32 v9, 31, v8
	s_waitcnt lgkmcnt(0)
	v_lshl_add_u64 v[2:3], v[8:9], 2, s[8:9]
	global_load_dword v0, v[2:3], off
	v_lshl_add_u64 v[2:3], v[6:7], 2, s[10:11]
	global_load_dwordx4 v[2:5], v[2:3], off
	s_and_b64 vcc, exec, s[6:7]
	s_cbranch_vccnz .LBB0_944
	s_waitcnt vmcnt(5)
	v_and_b32_e32 v9, 0xffff0000, v32
	s_waitcnt vmcnt(3)
	v_lshlrev_b32_e32 v36, 16, v30
	v_and_b32_e32 v30, 0xffff0000, v30
	v_lshlrev_b32_e32 v34, 16, v26
	v_and_b32_e32 v26, 0xffff0000, v26
	v_lshlrev_b32_e32 v35, 16, v27
	s_waitcnt vmcnt(2)
	v_lshlrev_b32_e32 v38, 16, v28
	v_and_b32_e32 v28, 0xffff0000, v28
	s_waitcnt vmcnt(1)
	v_fmac_f32_e32 v30, v0, v9
	v_add_f32_e32 v9, v30, v28
	v_mul_f32_e32 v28, 0xbfb8aa3b, v26
	v_mul_f32_e32 v30, 0xbfb8aa3b, v35
	v_exp_f32_e32 v28, v28
	v_exp_f32_e32 v30, v30
	v_lshlrev_b32_e32 v8, 16, v32
	v_lshlrev_b32_e32 v32, 16, v33
	v_add_f32_e32 v28, 1.0, v28
	v_add_f32_e32 v30, 1.0, v30
	v_rcp_f32_e32 v28, v28
	v_rcp_f32_e32 v30, v30
	v_lshlrev_b32_e32 v37, 16, v31
	v_fmac_f32_e32 v36, v0, v8
	v_lshlrev_b32_e32 v39, 16, v29
	v_add_f32_e32 v8, v36, v38
	v_mul_f32_e32 v36, 0xbfb8aa3b, v34
	v_fmac_f32_e32 v37, v0, v32
	v_and_b32_e32 v27, 0xffff0000, v27
	v_exp_f32_e32 v36, v36
	v_mul_f32_e32 v26, v28, v26
	v_add_f32_e32 v28, v37, v39
	v_mul_f32_e32 v30, v30, v35
	v_mul_f32_e32 v28, v28, v30
	v_mul_f32_e32 v30, 0xbfb8aa3b, v27
	v_exp_f32_e32 v30, v30
	v_add_f32_e32 v36, 1.0, v36
	v_rcp_f32_e32 v36, v36
	v_and_b32_e32 v33, 0xffff0000, v33
	v_add_f32_e32 v30, 1.0, v30
	v_rcp_f32_e32 v30, v30
	v_and_b32_e32 v31, 0xffff0000, v31
	v_mul_f32_e32 v34, v36, v34
	v_mul_f32_e32 v9, v9, v26
	v_and_b32_e32 v29, 0xffff0000, v29
	v_mul_f32_e32 v8, v8, v34
	v_mul_f32_e32 v26, v9, v9
	v_fmac_f32_e32 v31, v0, v33
	v_fmac_f32_e32 v26, v8, v8
	v_add_f32_e32 v29, v31, v29
	v_mul_f32_e32 v27, v30, v27
	v_fmac_f32_e32 v26, v28, v28
	v_mul_f32_e32 v27, v29, v27
	v_fmac_f32_e32 v26, v27, v27
	s_ashr_i32 s47, s46, 31
	s_lshl_b64 s[6:7], s[46:47], 11
	s_add_u32 s6, s20, s6
	s_addc_u32 s7, s21, s7
	s_nop 1
	v_add_f32_dpp v26, v26, v26 quad_perm:[1,0,3,2] row_mask:0xf bank_mask:0xf
	s_nop 1
	v_add_f32_dpp v26, v26, v26 quad_perm:[2,3,0,1] row_mask:0xf bank_mask:0xf
	s_nop 1
	v_add_f32_dpp v26, v26, v26 row_half_mirror row_mask:0xf bank_mask:0xf
	s_nop 1
	v_add_f32_dpp v26, v26, v26 row_mirror row_mask:0xf bank_mask:0xf
	v_mov_b32_e32 v29, v26
	s_nop 1
	v_permlane16_swap_b32_e32 v26, v29
	v_add_f32_e32 v26, v26, v29
	v_fmamk_f32 v26, v26, 0x3c000000, v244
	v_rsq_f32_e32 v26, v26
	s_nop 0
	v_mul_f32_e32 v8, v8, v26
	v_mul_f32_e32 v9, v9, v26
	s_waitcnt vmcnt(0)
	v_mul_f32_e32 v8, v2, v8
	v_mul_f32_e32 v9, v3, v9
	v_cvt_pk_bf16_f32 v8, v8, v9
	v_mul_f32_e32 v9, v28, v26
	v_mul_f32_e32 v26, v27, v26
	v_mul_f32_e32 v9, v4, v9
	v_mul_f32_e32 v26, v5, v26
	v_cvt_pk_bf16_f32 v9, v9, v26
	v_lshl_add_u64 v[26:27], v[6:7], 1, s[6:7]
	v_add_co_u32_e32 v26, vcc, 0x16200000, v26
	s_nop 1
	v_addc_co_u32_e32 v27, vcc, 0, v27, vcc
	global_store_dwordx2 v[26:27], v[8:9], off offset:512
	s_and_b64 vcc, exec, s[4:5]
	s_cbranch_vccnz .LBB0_896
	s_branch .LBB0_945

.LBB0_945:
	s_waitcnt vmcnt(5)
	v_and_b32_e32 v9, 0xffff0000, v24
	s_waitcnt vmcnt(2)
	v_lshlrev_b32_e32 v28, 16, v20
	v_and_b32_e32 v20, 0xffff0000, v20
	v_lshlrev_b32_e32 v26, 16, v22
	v_and_b32_e32 v22, 0xffff0000, v22
	v_lshlrev_b32_e32 v30, 16, v18
	v_and_b32_e32 v18, 0xffff0000, v18
	s_waitcnt vmcnt(1)
	v_fmac_f32_e32 v20, v0, v9
	v_add_f32_e32 v9, v20, v18
	v_mul_f32_e32 v18, 0xbfb8aa3b, v22
	v_exp_f32_e32 v18, v18
	v_lshlrev_b32_e32 v8, 16, v24
	v_fmac_f32_e32 v28, v0, v8
	v_lshlrev_b32_e32 v24, 16, v25
	v_add_f32_e32 v18, 1.0, v18
	v_rcp_f32_e32 v18, v18
	v_and_b32_e32 v25, 0xffff0000, v25
	v_lshlrev_b32_e32 v27, 16, v23
	v_lshlrev_b32_e32 v29, 16, v21
	v_and_b32_e32 v21, 0xffff0000, v21
	v_add_f32_e32 v8, v28, v30
	v_mul_f32_e32 v28, 0xbfb8aa3b, v26
	v_and_b32_e32 v23, 0xffff0000, v23
	v_lshlrev_b32_e32 v31, 16, v19
	v_and_b32_e32 v19, 0xffff0000, v19
	v_exp_f32_e32 v28, v28
	v_mul_f32_e32 v18, v18, v22
	v_mul_f32_e32 v22, 0xbfb8aa3b, v27
	v_fmac_f32_e32 v21, v0, v25
	v_exp_f32_e32 v22, v22
	v_add_f32_e32 v19, v21, v19
	v_mul_f32_e32 v21, 0xbfb8aa3b, v23
	v_exp_f32_e32 v21, v21
	v_add_f32_e32 v28, 1.0, v28
	v_rcp_f32_e32 v28, v28
	v_add_f32_e32 v22, 1.0, v22
	v_rcp_f32_e32 v22, v22
	v_add_f32_e32 v21, 1.0, v21
	v_rcp_f32_e32 v21, v21
	v_mul_f32_e32 v26, v28, v26
	v_mul_f32_e32 v9, v9, v18
	v_fmac_f32_e32 v29, v0, v24
	v_mul_f32_e32 v8, v8, v26
	v_mul_f32_e32 v18, v9, v9
	v_add_f32_e32 v20, v29, v31
	v_mul_f32_e32 v22, v22, v27
	v_fmac_f32_e32 v18, v8, v8
	v_mul_f32_e32 v20, v20, v22
	v_mul_f32_e32 v21, v21, v23
	v_fmac_f32_e32 v18, v20, v20
	v_mul_f32_e32 v19, v19, v21
	v_fmac_f32_e32 v18, v19, v19
	s_ashr_i32 s45, s44, 31
	s_lshl_b64 s[4:5], s[44:45], 11
	s_add_u32 s4, s20, s4
	s_addc_u32 s5, s21, s5
	s_nop 1
	v_add_f32_dpp v18, v18, v18 quad_perm:[1,0,3,2] row_mask:0xf bank_mask:0xf
	s_nop 1
	v_add_f32_dpp v18, v18, v18 quad_perm:[2,3,0,1] row_mask:0xf bank_mask:0xf
	s_nop 1
	v_add_f32_dpp v18, v18, v18 row_half_mirror row_mask:0xf bank_mask:0xf
	s_nop 1
	v_add_f32_dpp v18, v18, v18 row_mirror row_mask:0xf bank_mask:0xf
	v_mov_b32_e32 v21, v18
	s_nop 1
	v_permlane16_swap_b32_e32 v18, v21
	v_add_f32_e32 v18, v18, v21
	v_fmamk_f32 v18, v18, 0x3c000000, v244
	v_rsq_f32_e32 v18, v18
	s_nop 0
	v_mul_f32_e32 v8, v8, v18
	v_mul_f32_e32 v9, v9, v18
	s_waitcnt vmcnt(0)
	v_mul_f32_e32 v8, v2, v8
	v_mul_f32_e32 v9, v3, v9
	v_cvt_pk_bf16_f32 v8, v8, v9
	v_mul_f32_e32 v9, v20, v18
	v_mul_f32_e32 v18, v19, v18
	v_mul_f32_e32 v9, v4, v9
	v_mul_f32_e32 v18, v5, v18
	v_cvt_pk_bf16_f32 v9, v9, v18
	v_lshl_add_u64 v[18:19], v[6:7], 1, s[4:5]
	v_add_co_u32_e32 v18, vcc, 0x16200000, v18
	s_nop 1
	v_addc_co_u32_e32 v19, vcc, 0, v19, vcc
	global_store_dwordx2 v[18:19], v[8:9], off offset:512
	s_branch .LBB0_896
.LBB0_946:
	s_waitcnt vmcnt(5)
	v_and_b32_e32 v9, 0xffff0000, v16
	s_waitcnt vmcnt(3)
	v_lshlrev_b32_e32 v20, 16, v14
	v_and_b32_e32 v14, 0xffff0000, v14
	v_lshlrev_b32_e32 v8, 16, v16
	s_waitcnt vmcnt(2)
	v_lshlrev_b32_e32 v18, 16, v10
	v_and_b32_e32 v10, 0xffff0000, v10
	v_lshlrev_b32_e32 v22, 16, v12
	v_and_b32_e32 v12, 0xffff0000, v12
	s_waitcnt vmcnt(1)
	v_fmac_f32_e32 v14, v0, v9
	v_fmac_f32_e32 v20, v0, v8
	v_add_f32_e32 v9, v14, v12
	v_mul_f32_e32 v12, 0xbfb8aa3b, v10
	v_lshlrev_b32_e32 v16, 16, v17
	v_and_b32_e32 v17, 0xffff0000, v17
	v_lshlrev_b32_e32 v19, 16, v11
	v_lshlrev_b32_e32 v21, 16, v15
	v_and_b32_e32 v15, 0xffff0000, v15
	v_add_f32_e32 v8, v20, v22
	v_mul_f32_e32 v20, 0xbfb8aa3b, v18
	v_exp_f32_e32 v12, v12
	v_and_b32_e32 v11, 0xffff0000, v11
	v_lshlrev_b32_e32 v23, 16, v13
	v_and_b32_e32 v13, 0xffff0000, v13
	v_exp_f32_e32 v20, v20
	v_mul_f32_e32 v14, 0xbfb8aa3b, v19
	v_fmac_f32_e32 v15, v0, v17
	v_fmac_f32_e32 v21, v0, v16
	v_exp_f32_e32 v14, v14
	v_add_f32_e32 v0, v15, v13
	v_mul_f32_e32 v13, 0xbfb8aa3b, v11
	v_exp_f32_e32 v13, v13
	v_add_f32_e32 v12, 1.0, v12
	v_add_f32_e32 v20, 1.0, v20
	v_rcp_f32_e32 v12, v12
	v_rcp_f32_e32 v20, v20
	v_add_f32_e32 v14, 1.0, v14
	v_rcp_f32_e32 v14, v14
	v_add_f32_e32 v13, 1.0, v13
	v_rcp_f32_e32 v13, v13
	v_mul_f32_e32 v10, v12, v10
	v_mul_f32_e32 v18, v20, v18
	v_mul_f32_e32 v9, v9, v10
	v_mul_f32_e32 v8, v8, v18
	v_mul_f32_e32 v10, v9, v9
	v_add_f32_e32 v12, v21, v23
	v_mul_f32_e32 v14, v14, v19
	v_fmac_f32_e32 v10, v8, v8
	v_mul_f32_e32 v12, v12, v14
	v_mul_f32_e32 v11, v13, v11
	v_fmac_f32_e32 v10, v12, v12
	v_mul_f32_e32 v0, v0, v11
	v_fmac_f32_e32 v10, v0, v0
	s_ashr_i32 s43, s42, 31
	s_lshl_b64 s[2:3], s[42:43], 11
	s_add_u32 s2, s20, s2
	s_addc_u32 s3, s21, s3
	s_nop 1
	v_add_f32_dpp v10, v10, v10 quad_perm:[1,0,3,2] row_mask:0xf bank_mask:0xf
	s_nop 1
	v_add_f32_dpp v10, v10, v10 quad_perm:[2,3,0,1] row_mask:0xf bank_mask:0xf
	s_nop 1
	v_add_f32_dpp v10, v10, v10 row_half_mirror row_mask:0xf bank_mask:0xf
	s_nop 1
	v_add_f32_dpp v10, v10, v10 row_mirror row_mask:0xf bank_mask:0xf
	v_mov_b32_e32 v11, v10
	s_nop 1
	v_permlane16_swap_b32_e32 v10, v11
	v_add_f32_e32 v10, v10, v11
	v_fmamk_f32 v10, v10, 0x3c000000, v244
	v_rsq_f32_e32 v10, v10
	s_nop 0
	v_mul_f32_e32 v8, v8, v10
	s_waitcnt vmcnt(0)
	v_mul_f32_e32 v2, v2, v8
	v_mul_f32_e32 v8, v9, v10
	v_mul_f32_e32 v3, v3, v8
	v_cvt_pk_bf16_f32 v2, v2, v3
	v_mul_f32_e32 v3, v12, v10
	v_mul_f32_e32 v0, v0, v10
	v_mul_f32_e32 v3, v4, v3
	v_mul_f32_e32 v0, v5, v0
	v_lshl_add_u64 v[4:5], v[6:7], 1, s[2:3]
	v_add_co_u32_e32 v4, vcc, 0x16200000, v4
	v_cvt_pk_bf16_f32 v3, v3, v0
	s_nop 1
	v_addc_co_u32_e32 v5, vcc, 0, v5, vcc
	global_store_dwordx2 v[4:5], v[2:3], off offset:512
	s_branch .LBB0_897

.LBB0_1571:
	s_waitcnt vmcnt(4)
	s_ashr_i32 s3, s2, 31
	s_waitcnt vmcnt(3)
	v_and_b32_e32 v79, 0xffff0000, v18
	v_lshlrev_b32_e32 v80, 16, v19
	s_waitcnt vmcnt(2)
	v_lshlrev_b32_e32 v82, 16, v20
	s_nop 1
	v_add_f32_dpp v77, v70, v70 quad_perm:[1,0,3,2] row_mask:0xf bank_mask:0xf
	v_and_b32_e32 v83, 0xffff0000, v20
	v_lshlrev_b32_e32 v84, 16, v21
	s_lshl_b64 s[6:7], s[2:3], 12
	s_waitcnt vmcnt(1)
	v_lshlrev_b32_e32 v86, 16, v22
	s_nop 1
	v_add_f32_dpp v77, v77, v77 quad_perm:[2,3,0,1] row_mask:0xf bank_mask:0xf
	v_lshlrev_b32_e32 v78, 16, v18
	v_and_b32_e32 v87, 0xffff0000, v22
	v_lshlrev_b32_e32 v88, 16, v23
	v_lshl_add_u64 v[92:93], v[44:45], 0, s[6:7]
	s_nop 1
	v_add_f32_dpp v77, v77, v77 row_half_mirror row_mask:0xf bank_mask:0xf
	v_and_b32_e32 v81, 0xffff0000, v19
	s_add_i32 s6, s16, s2
	s_cmpk_gt_i32 s6, 0x7fff
	s_nop 1
	v_add_f32_dpp v77, v77, v77 row_mirror row_mask:0xf bank_mask:0xf
	v_mov_b32_e32 v89, v77
	v_and_b32_e32 v85, 0xffff0000, v21
	s_nop 1
	v_permlane16_swap_b32_e32 v77, v89
	v_add_f32_e32 v77, v77, v89
	v_mov_b32_e32 v89, v77
	s_nop 1
	v_permlane32_swap_b32_e32 v77, v89
	v_add_f32_e32 v77, v77, v89
	v_fmamk_f32 v77, v77, 0x39800000, v73
	v_rsq_f32_e32 v90, v77
	v_and_b32_e32 v89, 0xffff0000, v23
	v_pk_mul_f32 v[78:79], v[90:91], v[78:79] op_sel_hi:[0,1]
	v_pk_mul_f32 v[80:81], v[90:91], v[80:81] op_sel_hi:[0,1]
	v_pk_mul_f32 v[82:83], v[90:91], v[82:83] op_sel_hi:[0,1]
	v_pk_mul_f32 v[84:85], v[90:91], v[84:85] op_sel_hi:[0,1]
	v_pk_mul_f32 v[80:81], v[2:3], v[80:81]
	v_pk_mul_f32 v[78:79], v[0:1], v[78:79]
	v_pk_mul_f32 v[84:85], v[6:7], v[84:85]
	v_pk_mul_f32 v[82:83], v[4:5], v[82:83]
	global_store_dwordx4 v[92:93], v[78:81], off
	global_store_dwordx4 v[92:93], v[82:85], off offset:1024
	s_nop 0
	v_pk_mul_f32 v[78:79], v[90:91], v[86:87] op_sel_hi:[0,1]
	v_pk_mul_f32 v[80:81], v[90:91], v[88:89] op_sel_hi:[0,1]
	v_pk_mul_f32 v[80:81], v[10:11], v[80:81]
	v_pk_mul_f32 v[78:79], v[8:9], v[78:79]
	global_store_dwordx4 v[92:93], v[78:81], off offset:2048
	s_waitcnt vmcnt(3)
	s_nop 0
	v_lshlrev_b32_e32 v78, 16, v24
	v_and_b32_e32 v79, 0xffff0000, v24
	v_lshlrev_b32_e32 v80, 16, v25
	v_and_b32_e32 v81, 0xffff0000, v25
	v_pk_mul_f32 v[78:79], v[90:91], v[78:79] op_sel_hi:[0,1]
	v_pk_mul_f32 v[80:81], v[90:91], v[80:81] op_sel_hi:[0,1]
	v_pk_mul_f32 v[80:81], v[14:15], v[80:81]
	v_pk_mul_f32 v[78:79], v[12:13], v[78:79]
	global_store_dwordx4 v[92:93], v[78:81], off offset:3072
	s_cbranch_scc1 .LBB0_1574
	s_ashr_i32 s7, s6, 31
	v_and_b32_e32 v79, 0xffff0000, v26
	v_lshlrev_b32_e32 v80, 16, v27
	v_lshlrev_b32_e32 v82, 16, v28
	s_nop 1
	v_add_f32_dpp v77, v71, v71 quad_perm:[1,0,3,2] row_mask:0xf bank_mask:0xf
	v_and_b32_e32 v83, 0xffff0000, v28
	v_lshlrev_b32_e32 v84, 16, v29
	s_lshl_b64 s[6:7], s[6:7], 12
	v_lshlrev_b32_e32 v86, 16, v30
	s_nop 1
	v_add_f32_dpp v77, v77, v77 quad_perm:[2,3,0,1] row_mask:0xf bank_mask:0xf
	v_lshlrev_b32_e32 v78, 16, v26
	v_and_b32_e32 v87, 0xffff0000, v30
	v_lshlrev_b32_e32 v88, 16, v31
	v_lshl_add_u64 v[92:93], v[44:45], 0, s[6:7]
	s_nop 1
	v_add_f32_dpp v77, v77, v77 row_half_mirror row_mask:0xf bank_mask:0xf
	v_and_b32_e32 v81, 0xffff0000, v27
	s_nop 1
	v_add_f32_dpp v77, v77, v77 row_mirror row_mask:0xf bank_mask:0xf
	v_mov_b32_e32 v89, v77
	v_and_b32_e32 v85, 0xffff0000, v29
	s_nop 1
	v_permlane16_swap_b32_e32 v77, v89
	v_add_f32_e32 v77, v77, v89
	v_mov_b32_e32 v89, v77
	s_nop 1
	v_permlane32_swap_b32_e32 v77, v89
	v_add_f32_e32 v77, v77, v89
	v_fmamk_f32 v77, v77, 0x39800000, v73
	v_rsq_f32_e32 v90, v77
	v_and_b32_e32 v89, 0xffff0000, v31
	v_pk_mul_f32 v[78:79], v[90:91], v[78:79] op_sel_hi:[0,1]
	v_pk_mul_f32 v[80:81], v[90:91], v[80:81] op_sel_hi:[0,1]
	v_pk_mul_f32 v[82:83], v[90:91], v[82:83] op_sel_hi:[0,1]
	v_pk_mul_f32 v[84:85], v[90:91], v[84:85] op_sel_hi:[0,1]
	v_pk_mul_f32 v[80:81], v[2:3], v[80:81]
	v_pk_mul_f32 v[78:79], v[0:1], v[78:79]
	v_pk_mul_f32 v[84:85], v[6:7], v[84:85]
	v_pk_mul_f32 v[82:83], v[4:5], v[82:83]
	global_store_dwordx4 v[92:93], v[78:81], off
	global_store_dwordx4 v[92:93], v[82:85], off offset:1024
	s_nop 0
	v_pk_mul_f32 v[78:79], v[90:91], v[86:87] op_sel_hi:[0,1]
	v_pk_mul_f32 v[80:81], v[90:91], v[88:89] op_sel_hi:[0,1]
	v_pk_mul_f32 v[80:81], v[10:11], v[80:81]
	v_pk_mul_f32 v[78:79], v[8:9], v[78:79]
	global_store_dwordx4 v[92:93], v[78:81], off offset:2048
	s_nop 1
	v_lshlrev_b32_e32 v78, 16, v32
	v_and_b32_e32 v79, 0xffff0000, v32
	v_lshlrev_b32_e32 v80, 16, v33
	v_and_b32_e32 v81, 0xffff0000, v33
	v_pk_mul_f32 v[78:79], v[90:91], v[78:79] op_sel_hi:[0,1]
	v_pk_mul_f32 v[80:81], v[90:91], v[80:81] op_sel_hi:[0,1]
	v_pk_mul_f32 v[80:81], v[14:15], v[80:81]
	v_pk_mul_f32 v[78:79], v[12:13], v[78:79]
	global_store_dwordx4 v[92:93], v[78:81], off offset:3072
	s_add_i32 s6, s9, s2
	s_cmpk_gt_i32 s6, 0x7fff
	s_cbranch_scc0 .LBB0_1575

.LBB0_1575:
	s_ashr_i32 s7, s6, 31
	v_and_b32_e32 v79, 0xffff0000, v34
	v_lshlrev_b32_e32 v80, 16, v35
	v_lshlrev_b32_e32 v82, 16, v36
	s_nop 1
	v_add_f32_dpp v77, v72, v72 quad_perm:[1,0,3,2] row_mask:0xf bank_mask:0xf
	v_and_b32_e32 v83, 0xffff0000, v36
	v_lshlrev_b32_e32 v84, 16, v37
	s_lshl_b64 s[6:7], s[6:7], 12
	v_lshlrev_b32_e32 v86, 16, v38
	s_nop 1
	v_add_f32_dpp v77, v77, v77 quad_perm:[2,3,0,1] row_mask:0xf bank_mask:0xf
	v_lshlrev_b32_e32 v78, 16, v34
	v_and_b32_e32 v87, 0xffff0000, v38
	v_lshlrev_b32_e32 v88, 16, v39
	v_lshl_add_u64 v[92:93], v[44:45], 0, s[6:7]
	s_nop 1
	v_add_f32_dpp v77, v77, v77 row_half_mirror row_mask:0xf bank_mask:0xf
	v_and_b32_e32 v81, 0xffff0000, v35
	s_nop 1
	v_add_f32_dpp v77, v77, v77 row_mirror row_mask:0xf bank_mask:0xf
	v_mov_b32_e32 v89, v77
	v_and_b32_e32 v85, 0xffff0000, v37
	s_nop 1
	v_permlane16_swap_b32_e32 v77, v89
	v_add_f32_e32 v77, v77, v89
	v_mov_b32_e32 v89, v77
	s_nop 1
	v_permlane32_swap_b32_e32 v77, v89
	v_add_f32_e32 v77, v77, v89
	v_fmamk_f32 v77, v77, 0x39800000, v73
	v_rsq_f32_e32 v90, v77
	v_and_b32_e32 v89, 0xffff0000, v39
	v_pk_mul_f32 v[78:79], v[90:91], v[78:79] op_sel_hi:[0,1]
	v_pk_mul_f32 v[80:81], v[90:91], v[80:81] op_sel_hi:[0,1]
	v_pk_mul_f32 v[82:83], v[90:91], v[82:83] op_sel_hi:[0,1]
	v_pk_mul_f32 v[84:85], v[90:91], v[84:85] op_sel_hi:[0,1]
	v_pk_mul_f32 v[80:81], v[2:3], v[80:81]
	v_pk_mul_f32 v[78:79], v[0:1], v[78:79]
	v_pk_mul_f32 v[84:85], v[6:7], v[84:85]
	v_pk_mul_f32 v[82:83], v[4:5], v[82:83]
	global_store_dwordx4 v[92:93], v[78:81], off
	global_store_dwordx4 v[92:93], v[82:85], off offset:1024
	s_nop 0
	v_pk_mul_f32 v[78:79], v[90:91], v[86:87] op_sel_hi:[0,1]
	v_pk_mul_f32 v[80:81], v[90:91], v[88:89] op_sel_hi:[0,1]
	v_pk_mul_f32 v[80:81], v[10:11], v[80:81]
	v_pk_mul_f32 v[78:79], v[8:9], v[78:79]
	global_store_dwordx4 v[92:93], v[78:81], off offset:2048
	s_nop 1
	v_lshlrev_b32_e32 v78, 16, v40
	v_and_b32_e32 v79, 0xffff0000, v40
	v_lshlrev_b32_e32 v80, 16, v41
	v_and_b32_e32 v81, 0xffff0000, v41
	v_pk_mul_f32 v[78:79], v[90:91], v[78:79] op_sel_hi:[0,1]
	v_pk_mul_f32 v[80:81], v[90:91], v[80:81] op_sel_hi:[0,1]
	v_pk_mul_f32 v[80:81], v[14:15], v[80:81]
	v_pk_mul_f32 v[78:79], v[12:13], v[78:79]
	global_store_dwordx4 v[92:93], v[78:81], off offset:3072
	s_andn2_b64 vcc, exec, s[4:5]
	s_add_i32 s4, s8, s2
	s_cbranch_vccnz .LBB0_1565

.LBB0_1581:
	s_ashr_i32 s1, s0, 31
	v_and_b32_e32 v79, 0xffff0000, v62
	v_lshlrev_b32_e32 v80, 16, v63
	v_lshlrev_b32_e32 v82, 16, v64
	s_nop 1
	v_add_f32_dpp v77, v76, v76 quad_perm:[1,0,3,2] row_mask:0xf bank_mask:0xf
	v_and_b32_e32 v83, 0xffff0000, v64
	v_lshlrev_b32_e32 v84, 16, v65
	s_lshl_b64 s[0:1], s[0:1], 12
	v_lshlrev_b32_e32 v86, 16, v66
	s_nop 1
	v_add_f32_dpp v77, v77, v77 quad_perm:[2,3,0,1] row_mask:0xf bank_mask:0xf
	v_lshlrev_b32_e32 v78, 16, v62
	v_and_b32_e32 v87, 0xffff0000, v66
	v_lshlrev_b32_e32 v88, 16, v67
	v_lshl_add_u64 v[92:93], v[44:45], 0, s[0:1]
	s_nop 1
	v_add_f32_dpp v77, v77, v77 row_half_mirror row_mask:0xf bank_mask:0xf
	v_and_b32_e32 v81, 0xffff0000, v63
	v_readlane_b32 s0, v254, 7
	s_add_i32 s0, s0, s2
	s_cmpk_gt_i32 s0, 0x7fff
	s_nop 1
	v_add_f32_dpp v77, v77, v77 row_mirror row_mask:0xf bank_mask:0xf
	v_mov_b32_e32 v89, v77
	v_and_b32_e32 v85, 0xffff0000, v65
	s_nop 1
	v_permlane16_swap_b32_e32 v77, v89
	v_add_f32_e32 v77, v77, v89
	v_mov_b32_e32 v89, v77
	s_nop 1
	v_permlane32_swap_b32_e32 v77, v89
	v_add_f32_e32 v77, v77, v89
	v_fmamk_f32 v77, v77, 0x39800000, v73
	v_rsq_f32_e32 v90, v77
	v_and_b32_e32 v89, 0xffff0000, v67
	v_pk_mul_f32 v[78:79], v[90:91], v[78:79] op_sel_hi:[0,1]
	v_pk_mul_f32 v[80:81], v[90:91], v[80:81] op_sel_hi:[0,1]
	v_pk_mul_f32 v[82:83], v[90:91], v[82:83] op_sel_hi:[0,1]
	v_pk_mul_f32 v[84:85], v[90:91], v[84:85] op_sel_hi:[0,1]
	v_pk_mul_f32 v[80:81], v[2:3], v[80:81]
	v_pk_mul_f32 v[78:79], v[0:1], v[78:79]
	v_pk_mul_f32 v[84:85], v[6:7], v[84:85]
	v_pk_mul_f32 v[82:83], v[4:5], v[82:83]
	global_store_dwordx4 v[92:93], v[78:81], off
	global_store_dwordx4 v[92:93], v[82:85], off offset:1024
	s_nop 0
	v_pk_mul_f32 v[78:79], v[90:91], v[86:87] op_sel_hi:[0,1]
	v_pk_mul_f32 v[80:81], v[90:91], v[88:89] op_sel_hi:[0,1]
	v_pk_mul_f32 v[80:81], v[10:11], v[80:81]
	v_pk_mul_f32 v[78:79], v[8:9], v[78:79]
	global_store_dwordx4 v[92:93], v[78:81], off offset:2048
	s_nop 1
	v_lshlrev_b32_e32 v78, 16, v68
	v_and_b32_e32 v79, 0xffff0000, v68
	v_lshlrev_b32_e32 v80, 16, v69
	v_and_b32_e32 v81, 0xffff0000, v69
	v_pk_mul_f32 v[78:79], v[90:91], v[78:79] op_sel_hi:[0,1]
	v_pk_mul_f32 v[80:81], v[90:91], v[80:81] op_sel_hi:[0,1]
	v_pk_mul_f32 v[80:81], v[14:15], v[80:81]
	v_pk_mul_f32 v[78:79], v[12:13], v[78:79]
	global_store_dwordx4 v[92:93], v[78:81], off offset:3072
	s_cbranch_scc1 .LBB0_1583
	s_ashr_i32 s1, s0, 31
	v_and_b32_e32 v79, 0xffff0000, v60
	v_lshlrev_b32_e32 v80, 16, v61
	v_lshlrev_b32_e32 v82, 16, v58
	s_nop 1
	v_add_f32_dpp v77, v75, v75 quad_perm:[1,0,3,2] row_mask:0xf bank_mask:0xf
	v_and_b32_e32 v83, 0xffff0000, v58
	v_lshlrev_b32_e32 v84, 16, v59
	s_lshl_b64 s[0:1], s[0:1], 12
	v_lshlrev_b32_e32 v86, 16, v56
	s_nop 1
	v_add_f32_dpp v77, v77, v77 quad_perm:[2,3,0,1] row_mask:0xf bank_mask:0xf
	v_lshlrev_b32_e32 v78, 16, v60
	v_and_b32_e32 v87, 0xffff0000, v56
	v_lshlrev_b32_e32 v88, 16, v57
	v_lshl_add_u64 v[92:93], v[44:45], 0, s[0:1]
	s_nop 1
	v_add_f32_dpp v77, v77, v77 row_half_mirror row_mask:0xf bank_mask:0xf
	v_and_b32_e32 v81, 0xffff0000, v61
	s_nop 1
	v_add_f32_dpp v77, v77, v77 row_mirror row_mask:0xf bank_mask:0xf
	v_mov_b32_e32 v89, v77
	v_and_b32_e32 v85, 0xffff0000, v59
	s_nop 1
	v_permlane16_swap_b32_e32 v77, v89
	v_add_f32_e32 v77, v77, v89
	v_mov_b32_e32 v89, v77
	s_nop 1
	v_permlane32_swap_b32_e32 v77, v89
	v_add_f32_e32 v77, v77, v89
	v_fmamk_f32 v77, v77, 0x39800000, v73
	v_rsq_f32_e32 v90, v77
	v_and_b32_e32 v89, 0xffff0000, v57
	v_pk_mul_f32 v[78:79], v[90:91], v[78:79] op_sel_hi:[0,1]
	v_pk_mul_f32 v[80:81], v[90:91], v[80:81] op_sel_hi:[0,1]
	v_pk_mul_f32 v[82:83], v[90:91], v[82:83] op_sel_hi:[0,1]
	v_pk_mul_f32 v[84:85], v[90:91], v[84:85] op_sel_hi:[0,1]
	v_pk_mul_f32 v[80:81], v[2:3], v[80:81]
	v_pk_mul_f32 v[78:79], v[0:1], v[78:79]
	v_pk_mul_f32 v[84:85], v[6:7], v[84:85]
	v_pk_mul_f32 v[82:83], v[4:5], v[82:83]
	global_store_dwordx4 v[92:93], v[78:81], off
	global_store_dwordx4 v[92:93], v[82:85], off offset:1024
	s_nop 0
	v_pk_mul_f32 v[78:79], v[90:91], v[86:87] op_sel_hi:[0,1]
	v_pk_mul_f32 v[80:81], v[90:91], v[88:89] op_sel_hi:[0,1]
	v_pk_mul_f32 v[80:81], v[10:11], v[80:81]
	v_pk_mul_f32 v[78:79], v[8:9], v[78:79]
	global_store_dwordx4 v[92:93], v[78:81], off offset:2048
	s_nop 1
	v_lshlrev_b32_e32 v78, 16, v54
	v_and_b32_e32 v79, 0xffff0000, v54
	v_lshlrev_b32_e32 v80, 16, v55
	v_and_b32_e32 v81, 0xffff0000, v55
	v_pk_mul_f32 v[78:79], v[90:91], v[78:79] op_sel_hi:[0,1]
	v_pk_mul_f32 v[80:81], v[90:91], v[80:81] op_sel_hi:[0,1]
	v_pk_mul_f32 v[80:81], v[14:15], v[80:81]
	v_pk_mul_f32 v[78:79], v[12:13], v[78:79]
	global_store_dwordx4 v[92:93], v[78:81], off offset:3072
.LBB0_1583:
	s_add_i32 s0, s11, s2
	s_cmpk_gt_i32 s0, 0x7fff
	s_cbranch_scc1 .LBB0_1565
	s_ashr_i32 s1, s0, 31
	v_and_b32_e32 v79, 0xffff0000, v52
	v_lshlrev_b32_e32 v80, 16, v53
	v_lshlrev_b32_e32 v82, 16, v50
	s_nop 1
	v_add_f32_dpp v77, v74, v74 quad_perm:[1,0,3,2] row_mask:0xf bank_mask:0xf
	v_and_b32_e32 v83, 0xffff0000, v50
	v_lshlrev_b32_e32 v84, 16, v51
	s_lshl_b64 s[0:1], s[0:1], 12
	v_lshlrev_b32_e32 v86, 16, v48
	s_nop 1
	v_add_f32_dpp v77, v77, v77 quad_perm:[2,3,0,1] row_mask:0xf bank_mask:0xf
	v_lshlrev_b32_e32 v78, 16, v52
	v_and_b32_e32 v87, 0xffff0000, v48
	v_lshlrev_b32_e32 v88, 16, v49
	v_lshl_add_u64 v[92:93], v[44:45], 0, s[0:1]
	s_nop 1
	v_add_f32_dpp v77, v77, v77 row_half_mirror row_mask:0xf bank_mask:0xf
	v_and_b32_e32 v81, 0xffff0000, v53
	s_nop 1
	v_add_f32_dpp v77, v77, v77 row_mirror row_mask:0xf bank_mask:0xf
	v_mov_b32_e32 v89, v77
	v_and_b32_e32 v85, 0xffff0000, v51
	s_nop 1
	v_permlane16_swap_b32_e32 v77, v89
	v_add_f32_e32 v77, v77, v89
	v_mov_b32_e32 v89, v77
	s_nop 1
	v_permlane32_swap_b32_e32 v77, v89
	v_add_f32_e32 v77, v77, v89
	v_fmamk_f32 v77, v77, 0x39800000, v73
	v_rsq_f32_e32 v90, v77
	v_and_b32_e32 v89, 0xffff0000, v49
	v_pk_mul_f32 v[78:79], v[90:91], v[78:79] op_sel_hi:[0,1]
	v_pk_mul_f32 v[80:81], v[90:91], v[80:81] op_sel_hi:[0,1]
	v_pk_mul_f32 v[82:83], v[90:91], v[82:83] op_sel_hi:[0,1]
	v_pk_mul_f32 v[84:85], v[90:91], v[84:85] op_sel_hi:[0,1]
	v_pk_mul_f32 v[80:81], v[2:3], v[80:81]
	v_pk_mul_f32 v[78:79], v[0:1], v[78:79]
	v_pk_mul_f32 v[84:85], v[6:7], v[84:85]
	v_pk_mul_f32 v[82:83], v[4:5], v[82:83]
	global_store_dwordx4 v[92:93], v[78:81], off
	global_store_dwordx4 v[92:93], v[82:85], off offset:1024
	s_nop 0
	v_pk_mul_f32 v[78:79], v[90:91], v[86:87] op_sel_hi:[0,1]
	v_pk_mul_f32 v[80:81], v[90:91], v[88:89] op_sel_hi:[0,1]
	v_pk_mul_f32 v[80:81], v[10:11], v[80:81]
	v_pk_mul_f32 v[78:79], v[8:9], v[78:79]
	global_store_dwordx4 v[92:93], v[78:81], off offset:2048
	s_nop 1
	v_lshlrev_b32_e32 v78, 16, v46
	v_and_b32_e32 v79, 0xffff0000, v46
	v_lshlrev_b32_e32 v80, 16, v47
	v_and_b32_e32 v81, 0xffff0000, v47
	v_pk_mul_f32 v[78:79], v[90:91], v[78:79] op_sel_hi:[0,1]
	v_pk_mul_f32 v[80:81], v[90:91], v[80:81] op_sel_hi:[0,1]
	v_pk_mul_f32 v[80:81], v[14:15], v[80:81]
	v_pk_mul_f32 v[78:79], v[12:13], v[78:79]
	global_store_dwordx4 v[92:93], v[78:81], off offset:3072
	s_branch .LBB0_1565
